# 78 replay-rule s_nop pads between back-to-back loads removed (xnack is off)
# baseline (speedup 1.0000x reference)
.LBB0_59:
	s_lshr_b32 s48, s10, 6
	s_waitcnt lgkmcnt(0)
	v_cvt_f32_u32_e32 v0, s48
	s_sub_i32 s56, 0, s48
	s_abs_i32 s55, s49
	s_and_b64 s[46:47], s[28:29], s[46:47]
	v_rcp_iflag_f32_e32 v0, v0
	s_ashr_i32 s54, s49, 31
	s_load_dwordx2 s[4:5], s[4:5], 0x0
	v_mul_f32_e32 v0, 0x4f7ffffe, v0
	v_cvt_u32_f32_e32 v0, v0
	s_nop 0
	v_readfirstlane_b32 s57, v0
	s_mul_i32 s56, s56, s57
	s_mul_hi_u32 s56, s57, s56
	s_add_i32 s57, s57, s56
	s_mul_hi_u32 s56, s55, s57
	s_mul_i32 s57, s56, s48
	s_sub_i32 s55, s55, s57
	s_add_i32 s58, s56, 1
	s_sub_i32 s57, s55, s48
	s_cmp_ge_u32 s55, s48
	s_cselect_b32 s56, s58, s56
	s_cselect_b32 s55, s57, s55
	s_add_i32 s57, s56, 1
	s_cmp_ge_u32 s55, s48
	s_cselect_b32 s55, s57, s56
	s_xor_b32 s55, s55, s54
	s_sub_i32 s54, s55, s54
	s_mul_i32 s55, s54, s48
	s_lshl_b32 s48, s54, 6
	s_sub_i32 s54, s49, s55
	s_ashr_i32 s49, s48, 31
	s_lshl_b32 s54, s54, 6
	s_mul_i32 s55, s49, s10
	s_mul_hi_u32 s56, s48, s10
	v_or_b32_e32 v0, s54, v6
	s_add_i32 s57, s56, s55
	s_mul_i32 s56, s48, s10
	s_lshl_b64 s[56:57], s[56:57], 2
	v_cmp_gt_i32_e32 vcc, s10, v0
	s_waitcnt lgkmcnt(0)
	s_add_u32 s4, s4, s56
	s_addc_u32 s5, s5, s57
	v_cndmask_b32_e32 v0, 0, v0, vcc
	v_ashrrev_i32_e32 v1, 31, v0
	v_lshl_add_u64 v[0:1], v[0:1], 2, s[4:5]
	s_lshl_b32 s4, s10, 1
	s_mov_b32 s5, s11
	v_lshl_add_u64 v[10:11], s[4:5], 2, v[0:1]
	s_mul_i32 s4, s10, 3
	v_lshl_add_u64 v[22:23], s[4:5], 2, v[0:1]
	s_lshl_b32 s4, s10, 2
	v_lshl_add_u64 v[24:25], s[4:5], 2, v[0:1]
	s_mul_i32 s4, s10, 5
	v_lshl_add_u64 v[26:27], s[4:5], 2, v[0:1]
	s_mul_i32 s4, s10, 6
	v_lshl_add_u64 v[28:29], s[4:5], 2, v[0:1]
	s_mul_i32 s4, s10, 7
	v_lshl_add_u64 v[2:3], s[10:11], 2, v[0:1]
	v_lshl_add_u64 v[30:31], s[4:5], 2, v[0:1]
	s_lshl_b32 s4, s10, 3
	global_load_dword v34, v[0:1], off nt
	global_load_dword v35, v[2:3], off nt
	global_load_dword v36, v[10:11], off nt
	global_load_dword v37, v[22:23], off nt
	global_load_dword v38, v[24:25], off nt
	global_load_dword v39, v[26:27], off nt
	global_load_dword v40, v[28:29], off nt
	global_load_dword v41, v[30:31], off nt
	v_lshl_add_u64 v[2:3], s[4:5], 2, v[0:1]
	s_mul_i32 s4, s10, 9
	v_lshl_add_u64 v[10:11], s[4:5], 2, v[0:1]
	s_mul_i32 s4, s10, 10
	v_lshl_add_u64 v[22:23], s[4:5], 2, v[0:1]
	s_mul_i32 s4, s10, 11
	v_lshl_add_u64 v[24:25], s[4:5], 2, v[0:1]
	s_mul_i32 s4, s10, 12
	v_lshl_add_u64 v[26:27], s[4:5], 2, v[0:1]
	s_mul_i32 s4, s10, 13
	v_lshl_add_u64 v[28:29], s[4:5], 2, v[0:1]
	s_mul_i32 s4, s10, 14
	v_lshl_add_u64 v[30:31], s[4:5], 2, v[0:1]
	s_mul_i32 s4, s10, 15
	v_lshl_add_u64 v[32:33], s[4:5], 2, v[0:1]
	s_lshl_b32 s4, s10, 4
	global_load_dword v42, v[2:3], off nt
	global_load_dword v43, v[10:11], off nt
	global_load_dword v44, v[22:23], off nt
	global_load_dword v45, v[24:25], off nt
	global_load_dword v46, v[26:27], off nt
	global_load_dword v47, v[28:29], off nt
	global_load_dword v48, v[30:31], off nt
	global_load_dword v49, v[32:33], off nt
	v_lshl_add_u64 v[2:3], s[4:5], 2, v[0:1]
	s_mul_i32 s4, s10, 17
	v_lshl_add_u64 v[10:11], s[4:5], 2, v[0:1]
	s_mul_i32 s4, s10, 18
	v_lshl_add_u64 v[22:23], s[4:5], 2, v[0:1]
	s_mul_i32 s4, s10, 19
	v_lshl_add_u64 v[24:25], s[4:5], 2, v[0:1]
	s_mul_i32 s4, s10, 20
	v_lshl_add_u64 v[26:27], s[4:5], 2, v[0:1]
	s_mul_i32 s4, s10, 21
	v_lshl_add_u64 v[28:29], s[4:5], 2, v[0:1]
	s_mul_i32 s4, s10, 22
	v_lshl_add_u64 v[30:31], s[4:5], 2, v[0:1]
	s_mul_i32 s4, s10, 23
	v_lshl_add_u64 v[32:33], s[4:5], 2, v[0:1]
	s_mul_i32 s4, s10, 24
	global_load_dword v50, v[2:3], off nt
	global_load_dword v51, v[10:11], off nt
	global_load_dword v52, v[22:23], off nt
	global_load_dword v53, v[24:25], off nt
	global_load_dword v54, v[26:27], off nt
	global_load_dword v55, v[28:29], off nt
	global_load_dword v56, v[30:31], off nt
	global_load_dword v57, v[32:33], off nt
	v_lshl_add_u64 v[2:3], s[4:5], 2, v[0:1]
	s_mul_i32 s4, s10, 25
	v_lshl_add_u64 v[10:11], s[4:5], 2, v[0:1]
	s_mul_i32 s4, s10, 26
	v_lshl_add_u64 v[22:23], s[4:5], 2, v[0:1]
	s_mul_i32 s4, s10, 27
	v_lshl_add_u64 v[24:25], s[4:5], 2, v[0:1]
	s_mul_i32 s4, s10, 28
	v_lshl_add_u64 v[26:27], s[4:5], 2, v[0:1]
	s_mul_i32 s4, s10, 29
	v_lshl_add_u64 v[28:29], s[4:5], 2, v[0:1]
	s_mul_i32 s4, s10, 30
	v_lshl_add_u64 v[30:31], s[4:5], 2, v[0:1]
	s_mul_i32 s4, s10, 31
	v_lshl_add_u64 v[32:33], s[4:5], 2, v[0:1]
	s_lshl_b32 s4, s10, 5
	global_load_dword v58, v[2:3], off nt
	global_load_dword v59, v[10:11], off nt
	global_load_dword v60, v[22:23], off nt
	global_load_dword v61, v[24:25], off nt
	global_load_dword v62, v[26:27], off nt
	global_load_dword v63, v[28:29], off nt
	global_load_dword v64, v[30:31], off nt
	global_load_dword v65, v[32:33], off nt
	v_lshl_add_u64 v[2:3], s[4:5], 2, v[0:1]
	s_mul_i32 s4, s10, 33
	v_lshl_add_u64 v[10:11], s[4:5], 2, v[0:1]
	s_mul_i32 s4, s10, 34
	v_lshl_add_u64 v[22:23], s[4:5], 2, v[0:1]
	s_mul_i32 s4, s10, 35
	v_lshl_add_u64 v[24:25], s[4:5], 2, v[0:1]
	s_mul_i32 s4, s10, 36
	v_lshl_add_u64 v[26:27], s[4:5], 2, v[0:1]
	s_mul_i32 s4, s10, 37
	v_lshl_add_u64 v[28:29], s[4:5], 2, v[0:1]
	s_mul_i32 s4, s10, 38
	v_lshl_add_u64 v[30:31], s[4:5], 2, v[0:1]
	s_mul_i32 s4, s10, 39
	v_lshl_add_u64 v[32:33], s[4:5], 2, v[0:1]
	s_mul_i32 s4, s10, 40
	global_load_dword v66, v[2:3], off nt
	global_load_dword v67, v[10:11], off nt
	global_load_dword v68, v[22:23], off nt
	global_load_dword v69, v[24:25], off nt
	global_load_dword v70, v[26:27], off nt
	global_load_dword v71, v[28:29], off nt
	global_load_dword v72, v[30:31], off nt
	global_load_dword v73, v[32:33], off nt
	v_lshl_add_u64 v[2:3], s[4:5], 2, v[0:1]
	s_mul_i32 s4, s10, 41
	v_lshl_add_u64 v[10:11], s[4:5], 2, v[0:1]
	s_mul_i32 s4, s10, 42
	v_lshl_add_u64 v[22:23], s[4:5], 2, v[0:1]
	s_mul_i32 s4, s10, 43
	v_lshl_add_u64 v[24:25], s[4:5], 2, v[0:1]
	s_mul_i32 s4, s10, 44
	v_lshl_add_u64 v[26:27], s[4:5], 2, v[0:1]
	s_mul_i32 s4, s10, 45
	v_lshl_add_u64 v[28:29], s[4:5], 2, v[0:1]
	s_mul_i32 s4, s10, 46
	v_lshl_add_u64 v[30:31], s[4:5], 2, v[0:1]
	s_mul_i32 s4, s10, 47
	v_lshl_add_u64 v[32:33], s[4:5], 2, v[0:1]
	s_mul_i32 s4, s10, 48
	global_load_dword v74, v[2:3], off nt
	global_load_dword v75, v[10:11], off nt
	global_load_dword v76, v[22:23], off nt
	global_load_dword v77, v[24:25], off nt
	global_load_dword v78, v[26:27], off nt
	global_load_dword v79, v[28:29], off nt
	global_load_dword v80, v[30:31], off nt
	global_load_dword v81, v[32:33], off nt
	v_lshl_add_u64 v[2:3], s[4:5], 2, v[0:1]
	s_mul_i32 s4, s10, 49
	v_lshl_add_u64 v[10:11], s[4:5], 2, v[0:1]
	s_mul_i32 s4, s10, 50
	v_lshl_add_u64 v[22:23], s[4:5], 2, v[0:1]
	s_mul_i32 s4, s10, 51
	v_lshl_add_u64 v[24:25], s[4:5], 2, v[0:1]
	s_mul_i32 s4, s10, 52
	v_lshl_add_u64 v[26:27], s[4:5], 2, v[0:1]
	s_mul_i32 s4, s10, 53
	v_lshl_add_u64 v[28:29], s[4:5], 2, v[0:1]
	s_mul_i32 s4, s10, 54
	v_lshl_add_u64 v[30:31], s[4:5], 2, v[0:1]
	s_mul_i32 s4, s10, 55
	v_lshl_add_u64 v[32:33], s[4:5], 2, v[0:1]
	s_mul_i32 s4, s10, 56
	global_load_dword v82, v[2:3], off nt
	global_load_dword v83, v[10:11], off nt
	global_load_dword v84, v[22:23], off nt
	global_load_dword v85, v[24:25], off nt
	global_load_dword v86, v[26:27], off nt
	global_load_dword v87, v[28:29], off nt
	global_load_dword v88, v[30:31], off nt
	global_load_dword v32, v[32:33], off nt
	v_lshl_add_u64 v[2:3], s[4:5], 2, v[0:1]
	s_mul_i32 s4, s10, 57
	v_lshl_add_u64 v[10:11], s[4:5], 2, v[0:1]
	s_mul_i32 s4, s10, 58
	v_lshl_add_u64 v[22:23], s[4:5], 2, v[0:1]
	s_mul_i32 s4, s10, 59
	v_lshl_add_u64 v[24:25], s[4:5], 2, v[0:1]
	s_mul_i32 s4, s10, 60
	v_lshl_add_u64 v[26:27], s[4:5], 2, v[0:1]
	s_mul_i32 s4, s10, 61
	v_lshl_add_u64 v[28:29], s[4:5], 2, v[0:1]
	s_mul_i32 s4, s10, 62
	v_lshl_add_u64 v[30:31], s[4:5], 2, v[0:1]
	s_mul_i32 s4, s10, 63
	v_lshl_add_u64 v[0:1], s[4:5], 2, v[0:1]
	global_load_dword v33, v[2:3], off nt
	global_load_dword v10, v[10:11], off nt
	global_load_dword v11, v[22:23], off nt
	global_load_dword v22, v[24:25], off nt
	global_load_dword v23, v[26:27], off nt
	global_load_dword v24, v[28:29], off nt
	global_load_dword v25, v[30:31], off nt
	global_load_dword v26, v[0:1], off nt
	s_waitcnt vmcnt(62)
	v_cvt_pk_bf16_f32 v0, v34, v35
	s_waitcnt vmcnt(60)
	v_cvt_pk_bf16_f32 v1, v36, v37
	s_waitcnt vmcnt(58)
	v_cvt_pk_bf16_f32 v2, v38, v39
	s_waitcnt vmcnt(56)
	v_cvt_pk_bf16_f32 v3, v40, v41
	ds_write_b128 v18, v[0:3]
	s_waitcnt vmcnt(54)
	v_cvt_pk_bf16_f32 v0, v42, v43
	s_waitcnt vmcnt(52)
	v_cvt_pk_bf16_f32 v1, v44, v45
	s_waitcnt vmcnt(50)
	v_cvt_pk_bf16_f32 v2, v46, v47
	s_waitcnt vmcnt(48)
	v_cvt_pk_bf16_f32 v3, v48, v49
	ds_write_b128 v18, v[0:3] offset:16
	s_waitcnt vmcnt(46)
	v_cvt_pk_bf16_f32 v0, v50, v51
	s_waitcnt vmcnt(44)
	v_cvt_pk_bf16_f32 v1, v52, v53
	s_waitcnt vmcnt(42)
	v_cvt_pk_bf16_f32 v2, v54, v55
	s_waitcnt vmcnt(40)
	v_cvt_pk_bf16_f32 v3, v56, v57
	ds_write_b128 v18, v[0:3] offset:32
	s_waitcnt vmcnt(38)
	v_cvt_pk_bf16_f32 v0, v58, v59
	s_waitcnt vmcnt(36)
	v_cvt_pk_bf16_f32 v1, v60, v61
	s_waitcnt vmcnt(34)
	v_cvt_pk_bf16_f32 v2, v62, v63
	s_waitcnt vmcnt(32)
	v_cvt_pk_bf16_f32 v3, v64, v65
	ds_write_b128 v18, v[0:3] offset:48
	s_andn2_b64 vcc, exec, s[46:47]
	s_waitcnt vmcnt(30)
	v_cvt_pk_bf16_f32 v0, v66, v67
	s_waitcnt vmcnt(28)
	v_cvt_pk_bf16_f32 v1, v68, v69
	s_waitcnt vmcnt(26)
	v_cvt_pk_bf16_f32 v2, v70, v71
	s_waitcnt vmcnt(24)
	v_cvt_pk_bf16_f32 v3, v72, v73
	ds_write_b128 v18, v[0:3] offset:64
	s_waitcnt vmcnt(22)
	v_cvt_pk_bf16_f32 v0, v74, v75
	s_waitcnt vmcnt(20)
	v_cvt_pk_bf16_f32 v1, v76, v77
	s_waitcnt vmcnt(18)
	v_cvt_pk_bf16_f32 v2, v78, v79
	s_waitcnt vmcnt(16)
	v_cvt_pk_bf16_f32 v3, v80, v81
	ds_write_b128 v18, v[0:3] offset:80
	s_waitcnt vmcnt(14)
	v_cvt_pk_bf16_f32 v0, v82, v83
	s_waitcnt vmcnt(12)
	v_cvt_pk_bf16_f32 v1, v84, v85
	s_waitcnt vmcnt(10)
	v_cvt_pk_bf16_f32 v2, v86, v87
	s_waitcnt vmcnt(8)
	v_cvt_pk_bf16_f32 v3, v88, v32
	ds_write_b128 v18, v[0:3] offset:96
	s_waitcnt vmcnt(6)
	v_cvt_pk_bf16_f32 v0, v33, v10
	v_cndmask_b32_e64 v10, 0, 1, s[46:47]
	s_waitcnt vmcnt(4)
	v_cvt_pk_bf16_f32 v1, v11, v22
	v_or_b32_e32 v22, s54, v5
	s_waitcnt vmcnt(2)
	v_cvt_pk_bf16_f32 v2, v23, v24
	v_cmp_ne_u32_e64 s[4:5], 1, v10
	s_waitcnt vmcnt(0)
	v_cvt_pk_bf16_f32 v3, v25, v26
	ds_write_b128 v18, v[0:3] offset:112
	ds_read_b128 v[0:3], v19
	v_mov_b32_e32 v23, v22
	s_cbranch_vccnz .LBB0_61
	v_cmp_lt_i32_e32 vcc, s50, v22
	v_and_b32_e32 v23, 0x47, v22
	s_nop 0
	v_cndmask_b32_e32 v10, 0, v20, vcc
	v_add_lshl_u32 v10, v10, v22, 1
	v_and_b32_e32 v10, 0xffffff00, v10
	v_cndmask_b32_e32 v11, 0, v21, vcc
	v_or3_b32 v23, v11, v23, v10

.LBB0_149:
	s_add_i32 s46, s6, 0xffffe000
	s_cmpk_gt_i32 s6, 0x1fff
	s_cselect_b64 s[4:5], -1, 0
	s_and_b64 s[12:13], s[4:5], exec
	v_readlane_b32 s14, v254, 46
	s_cselect_b32 s12, s46, s6
	v_readlane_b32 s15, v254, 47
	s_cselect_b32 s7, s3, s1
	s_cselect_b32 s18, s2, s0
	s_ashr_i32 s13, s12, 31
	s_and_b64 vcc, exec, s[14:15]
	s_mov_b64 s[14:15], -1
	s_cbranch_vccnz .LBB0_151
	s_lshl_b64 s[14:15], s[12:13], 13
	s_add_u32 s14, s18, s14
	s_addc_u32 s15, s7, s15
	v_lshl_add_u64 v[2:3], s[14:15], 0, v[0:1]
	global_load_dwordx4 v[26:29], v0, s[14:15] offset:16
	global_load_dwordx4 v[30:33], v0, s[14:15]
	global_load_dwordx4 v[18:21], v0, s[14:15] offset:2064
	global_load_dwordx4 v[22:25], v0, s[14:15] offset:2048
	s_mov_b64 s[14:15], 0x1000
	v_lshl_add_u64 v[4:5], v[2:3], 0, s[14:15]
	s_movk_i32 s14, 0x1000
	v_add_co_u32_e32 v6, vcc, s14, v2
	s_mov_b64 s[14:15], 0x1800
	s_nop 0
	v_addc_co_u32_e32 v7, vcc, 0, v3, vcc
	v_lshl_add_u64 v[2:3], v[2:3], 0, s[14:15]
	global_load_dwordx4 v[14:17], v[6:7], off
	global_load_dwordx4 v[10:13], v[4:5], off offset:16
	global_load_dwordx4 v[6:9], v[6:7], off offset:2048
	global_load_dwordx4 v[2:5], v[2:3], off offset:16
	s_mov_b64 s[14:15], 0

.LBB0_217:
	s_mov_b64 s[20:21], -1
	s_and_b64 vcc, exec, s[0:1]
	s_cbranch_vccz .LBB0_223
	s_mov_b64 s[22:23], -1
	v_mov_b32_e32 v0, 8
	v_mov_b64_e32 v[30:31], 18
	v_mov_b64_e32 v[24:25], 9
	v_mov_b64_e32 v[28:29], 0x42c00000
	v_mov_b64_e32 v[32:33], s[14:15]
	v_mov_b64_e32 v[26:27], v[8:9]
	s_and_saveexec_b64 s[20:21], s[6:7]
	v_mov_b32_e32 v0, 6
	v_mov_b64_e32 v[30:31], 16
	v_mov_b64_e32 v[24:25], 7
	v_mov_b64_e32 v[28:29], 0x43200000
	v_mov_b64_e32 v[32:33], s[12:13]
	s_orn2_b64 s[22:23], s[8:9], exec
	v_mov_b64_e32 v[26:27], v[2:3]
	s_or_b64 exec, exec, s[20:21]
	s_and_saveexec_b64 s[20:21], s[22:23]
	s_cbranch_execz .LBB0_222
	global_load_dwordx2 v[32:33], v[32:33], off
	s_ashr_i32 s22, s16, 8
	s_lshl_b32 s18, s22, 1
	v_readlane_b32 s24, v254, 54
	s_add_i32 s18, s18, s24
	s_and_b32 s23, s16, 0xff
	s_ashr_i32 s19, s18, 31
	v_lshlrev_b32_e64 v0, v0, s23
	v_lshlrev_b64 v[30:31], v30, s[18:19]
	v_lshlrev_b32_e32 v0, 2, v0
	s_mulk_i32 s22, 0x500
	s_or_b32 s18, s22, s23
	s_addk_i32 s18, 0x2000
	s_ashr_i32 s19, s18, 31
	v_lshl_add_u64 v[28:29], s[2:3], 0, v[28:29]
	v_lshlrev_b64 v[24:25], v24, s[18:19]
	v_lshl_add_u64 v[24:25], v[28:29], 0, v[24:25]
	v_lshl_add_u64 v[24:25], v[26:27], 1, v[24:25]
	v_readlane_b32 s25, v254, 55
	s_waitcnt vmcnt(0)
	v_lshl_add_u64 v[30:31], v[32:33], 0, v[30:31]
	v_lshl_add_u64 v[30:31], v[30:31], 0, v[0:1]
	v_lshl_add_u64 v[34:35], v[26:27], 2, v[30:31]
	global_load_dwordx4 v[30:33], v[34:35], off
	global_load_dwordx4 v[34:37], v[34:35], off offset:16
	s_waitcnt vmcnt(1)
	v_cvt_pk_bf16_f32 v28, v30, v31
	v_cvt_pk_bf16_f32 v29, v32, v33
	s_waitcnt vmcnt(0)
	v_cvt_pk_bf16_f32 v30, v34, v35
	v_cvt_pk_bf16_f32 v31, v36, v37
	global_store_dwordx4 v[24:25], v[28:31], off

.LBB0_224:
	s_ashr_i32 s19, s16, 8
	s_load_dwordx8 s[20:27], s[10:11], 0x10
	s_lshl_b32 s28, s19, 1
	v_readlane_b32 s30, v254, 54
	v_readlane_b32 s31, v254, 55
	s_add_i32 s30, s28, s30
	s_ashr_i32 s31, s30, 31
	s_lshl_b64 s[36:37], s[30:31], 3
	s_and_b32 s18, s16, 0xff
	v_mov_b32_e32 v23, v1
	v_mov_b32_e32 v27, s37
	v_or_b32_e32 v26, s36, v6
	v_or_b32_e32 v7, s18, v5
	s_waitcnt lgkmcnt(0)
	v_lshl_add_u64 v[34:35], s[20:21], 0, v[22:23]
	v_lshlrev_b64 v[36:37], 17, v[26:27]
	v_lshlrev_b32_e32 v38, 8, v7
	v_mov_b32_e32 v39, v1
	v_lshl_add_u64 v[26:27], v[34:35], 0, v[36:37]
	v_lshl_add_u64 v[30:31], v[26:27], 0, v[38:39]
	global_load_dwordx4 v[26:29], v[30:31], off offset:16
	global_load_dwordx4 v[30:33], v[30:31], off
	s_mulk_i32 s19, 0x500
	s_or_b32 s20, s19, s18
	s_ashr_i32 s21, s20, 31
	s_lshl_b32 s19, s18, 9
	s_add_u32 s22, s22, s19
	s_addc_u32 s23, s23, 0
	v_lshlrev_b32_e32 v0, 2, v4
	v_lshl_add_u64 v[24:25], s[22:23], 0, v[0:1]
	s_lshl_b64 s[22:23], s[20:21], 11
	v_lshl_add_u64 v[40:41], v[18:19], 0, s[22:23]
	s_waitcnt vmcnt(0)
	v_cvt_pk_bf16_f32 v30, v30, v31
	v_cvt_pk_bf16_f32 v31, v32, v33
	v_cvt_pk_bf16_f32 v32, v26, v27
	v_cvt_pk_bf16_f32 v33, v28, v29
	global_store_dwordx4 v[40:41], v[30:33], off
	s_nop 1
	v_lshl_add_u64 v[30:31], v[24:25], 0, v[36:37]
	global_load_dwordx4 v[26:29], v[30:31], off offset:16
	global_load_dwordx4 v[30:33], v[30:31], off
	v_lshl_add_u64 v[36:37], v[20:21], 0, s[22:23]
	s_waitcnt vmcnt(0)
	v_cvt_pk_bf16_f32 v30, v30, v31
	v_cvt_pk_bf16_f32 v31, v32, v33
	v_cvt_pk_bf16_f32 v32, v26, v27
	v_mov_b32_e32 v27, s37
	v_or_b32_e32 v26, s36, v10
	v_lshlrev_b64 v[42:43], 17, v[26:27]
	v_cvt_pk_bf16_f32 v33, v28, v29
	v_lshl_add_u64 v[26:27], v[34:35], 0, v[42:43]
	global_store_dwordx4 v[36:37], v[30:33], off
	s_nop 1
	v_lshl_add_u64 v[30:31], v[26:27], 0, v[38:39]
	global_load_dwordx4 v[26:29], v[30:31], off offset:16
	global_load_dwordx4 v[30:33], v[30:31], off
	s_waitcnt vmcnt(0)
	v_cvt_pk_bf16_f32 v30, v30, v31
	v_cvt_pk_bf16_f32 v31, v32, v33
	v_cvt_pk_bf16_f32 v32, v26, v27
	v_cvt_pk_bf16_f32 v33, v28, v29
	global_store_dwordx4 v[40:41], v[30:33], off offset:1024
	v_lshl_add_u64 v[28:29], v[24:25], 0, v[42:43]
	global_load_dwordx4 v[24:27], v[28:29], off offset:16
	global_load_dwordx4 v[28:31], v[28:29], off
	s_waitcnt vmcnt(0)
	v_cvt_pk_bf16_f32 v28, v28, v29
	v_cvt_pk_bf16_f32 v29, v30, v31
	v_cvt_pk_bf16_f32 v30, v24, v25
	v_cvt_pk_bf16_f32 v31, v26, v27
	global_store_dwordx4 v[36:37], v[28:31], off offset:1024
	s_and_saveexec_b64 s[22:23], s[4:5]
	s_cbranch_execz .LBB0_215
	s_lshl_b64 s[28:29], s[30:31], 9
	v_or_b32_e32 v7, s28, v12
	v_mov_b32_e32 v25, s29
	v_or_b32_e32 v24, s18, v7
	v_lshlrev_b64 v[32:33], 9, v[24:25]
	v_lshl_add_u64 v[24:25], s[24:25], 0, v[32:33]
	v_lshl_add_u64 v[28:29], v[24:25], 0, v[0:1]
	global_load_dwordx4 v[24:27], v[28:29], off offset:16
	global_load_dwordx4 v[28:31], v[28:29], off
	s_lshl_b64 s[18:19], s[20:21], 9
	s_waitcnt vmcnt(0)
	v_cvt_pk_bf16_f32 v28, v28, v29
	v_cvt_pk_bf16_f32 v29, v30, v31
	v_cvt_pk_bf16_f32 v30, v24, v25
	v_cvt_pk_bf16_f32 v31, v26, v27
	v_lshl_add_u64 v[24:25], v[14:15], 0, s[18:19]
	global_store_dwordx4 v[24:25], v[28:31], off
	v_lshl_add_u64 v[24:25], s[26:27], 0, v[32:33]
	s_nop 0
	v_lshl_add_u64 v[28:29], v[24:25], 0, v[0:1]
	global_load_dwordx4 v[24:27], v[28:29], off offset:16
	global_load_dwordx4 v[28:31], v[28:29], off
	s_waitcnt vmcnt(0)
	v_cvt_pk_bf16_f32 v28, v28, v29
	v_cvt_pk_bf16_f32 v29, v30, v31
	v_cvt_pk_bf16_f32 v30, v24, v25
	v_cvt_pk_bf16_f32 v31, v26, v27
	v_lshl_add_u64 v[24:25], v[16:17], 0, s[18:19]
	global_store_dwordx4 v[24:25], v[28:31], off
	s_branch .LBB0_215

.LBB0_283:
	s_load_dwordx4 s[36:39], s[20:21], 0xc8
	v_readlane_b32 s14, v254, 54
	v_readlane_b32 s15, v254, 55
	s_mov_b32 s26, s14
	s_mulk_i32 s14, 0x6000
	s_waitcnt lgkmcnt(0)
	s_add_u32 s14, s36, s14
	s_mul_hi_u32 s15, s26, 0x6000
	s_addc_u32 s15, s37, s15
	s_add_u32 s26, s38, s24
	s_addc_u32 s27, s39, s25
	v_lshl_add_u64 v[18:19], s[14:15], 0, v[0:1]
	global_load_dwordx4 v[6:9], v0, s[26:27] offset:16
	global_load_dwordx4 v[58:61], v0, s[26:27]
	global_load_dwordx4 v[10:13], v0, s[14:15] offset:16
	global_load_dwordx4 v[62:65], v0, s[14:15]
	s_mov_b64 s[14:15], 0x2000
	v_lshl_add_u64 v[14:15], v[18:19], 0, s[14:15]
	s_movk_i32 s14, 0x2000
	v_add_co_u32_e32 v16, vcc, s14, v18
	s_mov_b64 s[14:15], 0x4000
	s_nop 0
	v_addc_co_u32_e32 v17, vcc, 0, v19, vcc
	v_lshl_add_u64 v[20:21], v[18:19], 0, s[14:15]
	s_movk_i32 s14, 0x4000
	v_add_co_u32_e32 v18, vcc, s14, v18
	global_load_dwordx4 v[66:69], v[16:17], off
	global_load_dwordx4 v[14:17], v[14:15], off offset:16
	v_addc_co_u32_e32 v19, vcc, 0, v19, vcc
	global_load_dwordx4 v[70:73], v[18:19], off
	global_load_dwordx4 v[18:21], v[20:21], off offset:16
	s_waitcnt vmcnt(0)
	v_lshlrev_b32_e32 v134, 16, v26
	v_and_b32_e32 v135, 0xffff0000, v26
	v_lshlrev_b32_e32 v130, 16, v22
	v_and_b32_e32 v131, 0xffff0000, v22
	v_lshlrev_b32_e32 v126, 16, v30
	v_and_b32_e32 v127, 0xffff0000, v30
	v_lshlrev_b32_e32 v124, 16, v34
	v_and_b32_e32 v125, 0xffff0000, v34
	v_lshlrev_b32_e32 v118, 16, v38
	v_and_b32_e32 v119, 0xffff0000, v38
	v_lshlrev_b32_e32 v114, 16, v42
	v_and_b32_e32 v115, 0xffff0000, v42
	v_lshlrev_b32_e32 v110, 16, v46
	v_and_b32_e32 v111, 0xffff0000, v46
	v_lshlrev_b32_e32 v104, 16, v50
	v_and_b32_e32 v105, 0xffff0000, v50
	v_lshlrev_b32_e32 v106, 16, v54
	v_and_b32_e32 v107, 0xffff0000, v54
	v_lshlrev_b32_e32 v50, 16, v51
	v_and_b32_e32 v51, 0xffff0000, v51
	v_lshlrev_b32_e32 v54, 16, v55
	v_and_b32_e32 v55, 0xffff0000, v55
	s_lshl_b32 s46, s1, 11
	s_movk_i32 s1, 0x1000
	s_mov_b64 s[14:15], 0
	v_pk_fma_f32 v[134:135], v[62:63], v[134:135], v[58:59]
	v_pk_fma_f32 v[132:133], v[62:63], v[130:131], v[58:59]
	v_pk_fma_f32 v[128:129], v[62:63], v[126:127], v[58:59]
	v_pk_fma_f32 v[120:121], v[62:63], v[124:125], v[58:59]
	v_pk_fma_f32 v[116:117], v[62:63], v[118:119], v[58:59]
	v_pk_fma_f32 v[112:113], v[62:63], v[114:115], v[58:59]
	v_pk_fma_f32 v[108:109], v[62:63], v[110:111], v[58:59]
	v_pk_fma_f32 v[58:59], v[62:63], v[104:105], v[58:59]
	v_pk_fma_f32 v[130:131], v[66:67], v[130:131], v[134:135]
	v_pk_fma_f32 v[108:109], v[66:67], v[104:105], v[108:109]
	v_pk_fma_f32 v[58:59], v[66:67], v[106:107], v[58:59]
	v_pk_fma_f32 v[130:131], v[70:71], v[126:127], v[130:131]
	v_pk_fma_f32 v[126:127], v[66:67], v[126:127], v[132:133]
	v_mul_f32_e32 v22, 0xbfb8aa3b, v130
	v_pk_fma_f32 v[126:127], v[70:71], v[124:125], v[126:127]
	v_pk_fma_f32 v[124:125], v[66:67], v[124:125], v[128:129]
	v_exp_f32_e32 v22, v22
	v_pk_fma_f32 v[124:125], v[70:71], v[118:119], v[124:125]
	v_pk_fma_f32 v[118:119], v[66:67], v[118:119], v[120:121]
	v_mul_f32_e32 v26, 0xbfb8aa3b, v126
	v_pk_fma_f32 v[118:119], v[70:71], v[114:115], v[118:119]
	v_pk_fma_f32 v[114:115], v[66:67], v[114:115], v[116:117]
	v_add_f32_e32 v22, 1.0, v22
	v_pk_fma_f32 v[114:115], v[70:71], v[110:111], v[114:115]
	v_pk_fma_f32 v[110:111], v[66:67], v[110:111], v[112:113]
	v_rcp_f32_e32 v134, v22
	v_pk_fma_f32 v[110:111], v[70:71], v[104:105], v[110:111]
	v_mul_f32_e32 v22, 0xbfb8aa3b, v131
	v_mul_f32_e32 v42, 0xbfb8aa3b, v110
	v_exp_f32_e32 v42, v42
	v_exp_f32_e32 v22, v22
	v_exp_f32_e32 v26, v26
	v_pk_fma_f32 v[108:109], v[70:71], v[106:107], v[108:109]
	v_add_f32_e32 v42, 1.0, v42
	v_rcp_f32_e32 v112, v42
	v_mul_f32_e32 v42, 0xbfb8aa3b, v111
	v_exp_f32_e32 v42, v42
	v_add_f32_e32 v22, 1.0, v22
	v_rcp_f32_e32 v135, v22
	v_mul_f32_e32 v46, 0xbfb8aa3b, v108
	v_add_f32_e32 v42, 1.0, v42
	v_rcp_f32_e32 v113, v42
	v_exp_f32_e32 v46, v46
	v_pk_mul_f32 v[130:131], v[130:131], v[134:135]
	v_add_f32_e32 v26, 1.0, v26
	v_pk_mul_f32 v[130:131], v[88:89], v[130:131]
	v_pk_mul_f32 v[110:111], v[110:111], v[112:113]
	v_cvt_pk_bf16_f32 v22, v130, v131
	v_rcp_f32_e32 v130, v26
	v_mul_f32_e32 v26, 0xbfb8aa3b, v127
	v_exp_f32_e32 v26, v26
	v_pk_mul_f32 v[110:111], v[88:89], v[110:111]
	v_add_f32_e32 v46, 1.0, v46
	v_cvt_pk_bf16_f32 v42, v110, v111
	v_rcp_f32_e32 v110, v46
	v_mul_f32_e32 v46, 0xbfb8aa3b, v109
	v_exp_f32_e32 v46, v46
	v_add_f32_e32 v26, 1.0, v26
	v_rcp_f32_e32 v131, v26
	v_mul_f32_e32 v30, 0xbfb8aa3b, v124
	v_exp_f32_e32 v30, v30
	v_mul_f32_e32 v34, 0xbfb8aa3b, v118
	v_add_f32_e32 v46, 1.0, v46
	v_exp_f32_e32 v34, v34
	v_mul_f32_e32 v38, 0xbfb8aa3b, v114
	v_rcp_f32_e32 v111, v46
	v_exp_f32_e32 v38, v38
	v_pk_mul_f32 v[126:127], v[126:127], v[130:131]
	v_add_f32_e32 v30, 1.0, v30
	v_pk_mul_f32 v[126:127], v[88:89], v[126:127]
	v_add_f32_e32 v34, 1.0, v34
	v_cvt_pk_bf16_f32 v26, v126, v127
	v_rcp_f32_e32 v126, v30
	v_mul_f32_e32 v30, 0xbfb8aa3b, v125
	v_pk_mul_f32 v[108:109], v[108:109], v[110:111]
	v_exp_f32_e32 v30, v30
	v_rcp_f32_e32 v120, v34
	v_mul_f32_e32 v34, 0xbfb8aa3b, v119
	v_add_f32_e32 v38, 1.0, v38
	v_pk_mul_f32 v[108:109], v[88:89], v[108:109]
	v_exp_f32_e32 v34, v34
	v_rcp_f32_e32 v116, v38
	v_mul_f32_e32 v38, 0xbfb8aa3b, v115
	v_cvt_pk_bf16_f32 v46, v108, v109
	v_lshlrev_b32_e32 v108, 16, v2
	v_and_b32_e32 v109, 0xffff0000, v2
	v_exp_f32_e32 v38, v38
	v_pk_fma_f32 v[58:59], v[70:71], v[108:109], v[58:59]
	v_add_f32_e32 v30, 1.0, v30
	v_mul_f32_e32 v2, 0xbfb8aa3b, v58
	v_exp_f32_e32 v2, v2
	v_rcp_f32_e32 v127, v30
	v_add_f32_e32 v34, 1.0, v34
	v_rcp_f32_e32 v121, v34
	v_add_f32_e32 v38, 1.0, v38
	v_rcp_f32_e32 v117, v38
	v_add_f32_e32 v2, 1.0, v2
	v_pk_mul_f32 v[124:125], v[124:125], v[126:127]
	v_rcp_f32_e32 v62, v2
	v_mul_f32_e32 v2, 0xbfb8aa3b, v59
	v_pk_mul_f32 v[124:125], v[88:89], v[124:125]
	v_pk_mul_f32 v[118:119], v[118:119], v[120:121]
	v_exp_f32_e32 v2, v2
	v_cvt_pk_bf16_f32 v30, v124, v125
	v_pk_mul_f32 v[118:119], v[88:89], v[118:119]
	v_pk_mul_f32 v[114:115], v[114:115], v[116:117]
	v_lshlrev_b32_e32 v124, 16, v27
	v_and_b32_e32 v125, 0xffff0000, v27
	v_cvt_pk_bf16_f32 v34, v118, v119
	v_pk_mul_f32 v[114:115], v[88:89], v[114:115]
	v_lshlrev_b32_e32 v118, 16, v23
	v_and_b32_e32 v119, 0xffff0000, v23
	v_pk_fma_f32 v[124:125], v[64:65], v[124:125], v[60:61]
	v_cvt_pk_bf16_f32 v38, v114, v115
	v_lshlrev_b32_e32 v114, 16, v31
	v_and_b32_e32 v115, 0xffff0000, v31
	v_pk_fma_f32 v[120:121], v[64:65], v[118:119], v[60:61]
	v_pk_fma_f32 v[118:119], v[68:69], v[118:119], v[124:125]
	v_add_f32_e32 v2, 1.0, v2
	v_pk_fma_f32 v[118:119], v[72:73], v[114:115], v[118:119]
	v_rcp_f32_e32 v63, v2
	v_mul_f32_e32 v2, 0xbfb8aa3b, v118
	v_exp_f32_e32 v2, v2
	v_lshlrev_b32_e32 v110, 16, v35
	v_and_b32_e32 v111, 0xffff0000, v35
	v_pk_fma_f32 v[116:117], v[64:65], v[114:115], v[60:61]
	v_add_f32_e32 v2, 1.0, v2
	v_rcp_f32_e32 v124, v2
	v_mul_f32_e32 v2, 0xbfb8aa3b, v119
	v_exp_f32_e32 v2, v2
	v_pk_fma_f32 v[114:115], v[68:69], v[114:115], v[120:121]
	v_lshlrev_b32_e32 v106, 16, v39
	v_pk_fma_f32 v[114:115], v[72:73], v[110:111], v[114:115]
	v_add_f32_e32 v2, 1.0, v2
	v_rcp_f32_e32 v125, v2
	v_mul_f32_e32 v2, 0xbfb8aa3b, v114
	v_exp_f32_e32 v2, v2
	v_and_b32_e32 v107, 0xffff0000, v39
	v_pk_mul_f32 v[118:119], v[118:119], v[124:125]
	v_pk_fma_f32 v[112:113], v[64:65], v[110:111], v[60:61]
	v_pk_mul_f32 v[118:119], v[88:89], v[118:119]
	v_add_f32_e32 v2, 1.0, v2
	v_cvt_pk_bf16_f32 v23, v118, v119
	v_rcp_f32_e32 v118, v2
	v_mul_f32_e32 v2, 0xbfb8aa3b, v115
	v_exp_f32_e32 v2, v2
	v_pk_fma_f32 v[110:111], v[68:69], v[110:111], v[116:117]
	v_lshlrev_b32_e32 v104, 16, v43
	v_pk_fma_f32 v[110:111], v[72:73], v[106:107], v[110:111]
	v_add_f32_e32 v2, 1.0, v2
	v_rcp_f32_e32 v119, v2
	v_mul_f32_e32 v2, 0xbfb8aa3b, v110
	v_exp_f32_e32 v2, v2
	v_and_b32_e32 v105, 0xffff0000, v43
	v_pk_mul_f32 v[114:115], v[114:115], v[118:119]
	v_pk_fma_f32 v[108:109], v[64:65], v[106:107], v[60:61]
	v_pk_mul_f32 v[114:115], v[88:89], v[114:115]
	v_add_f32_e32 v2, 1.0, v2
	v_cvt_pk_bf16_f32 v27, v114, v115
	v_rcp_f32_e32 v114, v2
	v_mul_f32_e32 v2, 0xbfb8aa3b, v111
	v_exp_f32_e32 v2, v2
	v_pk_fma_f32 v[106:107], v[68:69], v[106:107], v[112:113]
	v_lshlrev_b32_e32 v66, 16, v47
	v_pk_fma_f32 v[106:107], v[72:73], v[104:105], v[106:107]
	v_add_f32_e32 v2, 1.0, v2
	v_rcp_f32_e32 v115, v2
	v_mul_f32_e32 v2, 0xbfb8aa3b, v106
	v_exp_f32_e32 v2, v2
	v_and_b32_e32 v67, 0xffff0000, v47
	v_pk_mul_f32 v[110:111], v[110:111], v[114:115]
	v_pk_fma_f32 v[70:71], v[64:65], v[104:105], v[60:61]
	v_pk_mul_f32 v[110:111], v[88:89], v[110:111]
	v_add_f32_e32 v2, 1.0, v2
	v_cvt_pk_bf16_f32 v31, v110, v111
	v_rcp_f32_e32 v110, v2
	v_mul_f32_e32 v2, 0xbfb8aa3b, v107
	v_exp_f32_e32 v2, v2
	v_pk_fma_f32 v[104:105], v[68:69], v[104:105], v[108:109]
	v_pk_mul_f32 v[58:59], v[58:59], v[62:63]
	v_pk_fma_f32 v[104:105], v[72:73], v[66:67], v[104:105]
	v_add_f32_e32 v2, 1.0, v2
	v_rcp_f32_e32 v111, v2
	v_mul_f32_e32 v2, 0xbfb8aa3b, v104
	v_exp_f32_e32 v2, v2
	v_pk_fma_f32 v[62:63], v[64:65], v[66:67], v[60:61]
	v_pk_mul_f32 v[106:107], v[106:107], v[110:111]
	v_pk_fma_f32 v[66:67], v[68:69], v[66:67], v[70:71]
	v_pk_mul_f32 v[106:107], v[88:89], v[106:107]
	v_add_f32_e32 v2, 1.0, v2
	v_cvt_pk_bf16_f32 v35, v106, v107
	v_rcp_f32_e32 v106, v2
	v_mul_f32_e32 v2, 0xbfb8aa3b, v105
	v_exp_f32_e32 v2, v2
	v_pk_fma_f32 v[66:67], v[72:73], v[50:51], v[66:67]
	v_pk_fma_f32 v[62:63], v[68:69], v[50:51], v[62:63]
	v_lshlrev_b32_e32 v114, 16, v28
	v_add_f32_e32 v2, 1.0, v2
	v_rcp_f32_e32 v107, v2
	v_mul_f32_e32 v2, 0xbfb8aa3b, v66
	v_exp_f32_e32 v2, v2
	v_pk_fma_f32 v[62:63], v[72:73], v[54:55], v[62:63]
	v_and_b32_e32 v115, 0xffff0000, v28
	v_lshlrev_b32_e32 v110, 16, v24
	v_add_f32_e32 v2, 1.0, v2
	v_rcp_f32_e32 v70, v2
	v_mul_f32_e32 v2, 0xbfb8aa3b, v67
	v_exp_f32_e32 v2, v2
	v_and_b32_e32 v111, 0xffff0000, v24
	v_pk_fma_f32 v[114:115], v[10:11], v[114:115], v[6:7]
	v_pk_mul_f32 v[104:105], v[104:105], v[106:107]
	v_add_f32_e32 v2, 1.0, v2
	v_rcp_f32_e32 v71, v2
	v_mul_f32_e32 v2, 0xbfb8aa3b, v62
	v_exp_f32_e32 v2, v2
	v_lshlrev_b32_e32 v106, 16, v32
	v_and_b32_e32 v107, 0xffff0000, v32
	v_pk_fma_f32 v[112:113], v[10:11], v[110:111], v[6:7]
	v_pk_fma_f32 v[110:111], v[14:15], v[110:111], v[114:115]
	v_pk_mul_f32 v[66:67], v[66:67], v[70:71]
	v_pk_fma_f32 v[110:111], v[18:19], v[106:107], v[110:111]
	v_pk_mul_f32 v[66:67], v[88:89], v[66:67]
	v_mul_f32_e32 v24, 0xbfb8aa3b, v110
	v_exp_f32_e32 v24, v24
	v_add_f32_e32 v2, 1.0, v2
	v_cvt_pk_bf16_f32 v43, v66, v67
	v_rcp_f32_e32 v66, v2
	v_mul_f32_e32 v2, 0xbfb8aa3b, v63
	v_exp_f32_e32 v2, v2
	v_add_f32_e32 v24, 1.0, v24
	v_rcp_f32_e32 v114, v24
	v_mul_f32_e32 v24, 0xbfb8aa3b, v111
	v_exp_f32_e32 v24, v24
	v_add_f32_e32 v2, 1.0, v2
	v_pk_fma_f32 v[50:51], v[64:65], v[50:51], v[60:61]
	v_rcp_f32_e32 v67, v2
	v_lshlrev_b32_e32 v2, 16, v3
	v_and_b32_e32 v3, 0xffff0000, v3
	v_pk_fma_f32 v[50:51], v[68:69], v[54:55], v[50:51]
	v_pk_fma_f32 v[108:109], v[10:11], v[106:107], v[6:7]
	v_pk_fma_f32 v[2:3], v[72:73], v[2:3], v[50:51]
	v_lshlrev_b32_e32 v72, 16, v36
	v_and_b32_e32 v73, 0xffff0000, v36
	v_pk_fma_f32 v[106:107], v[14:15], v[106:107], v[112:113]
	v_add_f32_e32 v24, 1.0, v24
	v_pk_fma_f32 v[106:107], v[18:19], v[72:73], v[106:107]
	v_mul_f32_e32 v50, 0xbfb8aa3b, v2
	v_mul_f32_e32 v51, 0xbfb8aa3b, v3
	v_rcp_f32_e32 v115, v24
	v_mul_f32_e32 v28, 0xbfb8aa3b, v106
	v_exp_f32_e32 v50, v50
	v_exp_f32_e32 v51, v51
	v_exp_f32_e32 v28, v28
	v_pk_mul_f32 v[110:111], v[110:111], v[114:115]
	v_add_f32_e32 v50, 1.0, v50
	v_add_f32_e32 v51, 1.0, v51
	v_pk_mul_f32 v[110:111], v[88:89], v[110:111]
	v_add_f32_e32 v28, 1.0, v28
	v_pk_mul_f32 v[104:105], v[88:89], v[104:105]
	v_rcp_f32_e32 v50, v50
	v_rcp_f32_e32 v51, v51
	v_cvt_pk_bf16_f32 v24, v110, v111
	v_rcp_f32_e32 v110, v28
	v_mul_f32_e32 v28, 0xbfb8aa3b, v107
	v_cvt_pk_bf16_f32 v39, v104, v105
	v_pk_mul_f32 v[62:63], v[62:63], v[66:67]
	v_lshlrev_b32_e32 v68, 16, v40
	v_and_b32_e32 v69, 0xffff0000, v40
	v_pk_fma_f32 v[104:105], v[10:11], v[72:73], v[6:7]
	v_exp_f32_e32 v28, v28
	v_pk_fma_f32 v[72:73], v[14:15], v[72:73], v[108:109]
	v_pk_mul_f32 v[62:63], v[88:89], v[62:63]
	v_lshlrev_b32_e32 v66, 16, v44
	v_and_b32_e32 v67, 0xffff0000, v44
	v_pk_fma_f32 v[70:71], v[10:11], v[68:69], v[6:7]
	v_pk_fma_f32 v[72:73], v[18:19], v[68:69], v[72:73]
	v_pk_fma_f32 v[68:69], v[14:15], v[68:69], v[104:105]
	v_cvt_pk_bf16_f32 v47, v62, v63
	v_lshlrev_b32_e32 v62, 16, v48
	v_and_b32_e32 v63, 0xffff0000, v48
	v_pk_fma_f32 v[64:65], v[10:11], v[66:67], v[6:7]
	v_pk_fma_f32 v[68:69], v[18:19], v[66:67], v[68:69]
	v_pk_fma_f32 v[66:67], v[14:15], v[66:67], v[70:71]
	v_pk_mul_f32 v[2:3], v[2:3], v[50:51]
	v_lshlrev_b32_e32 v50, 16, v52
	v_and_b32_e32 v51, 0xffff0000, v52
	v_pk_fma_f32 v[60:61], v[10:11], v[62:63], v[6:7]
	v_pk_fma_f32 v[66:67], v[18:19], v[62:63], v[66:67]
	v_pk_fma_f32 v[62:63], v[14:15], v[62:63], v[64:65]
	v_add_f32_e32 v28, 1.0, v28
	v_pk_fma_f32 v[62:63], v[18:19], v[50:51], v[62:63]
	v_rcp_f32_e32 v111, v28
	v_mul_f32_e32 v32, 0xbfb8aa3b, v72
	v_mul_f32_e32 v44, 0xbfb8aa3b, v62
	v_exp_f32_e32 v32, v32
	v_exp_f32_e32 v44, v44
	v_pk_mul_f32 v[106:107], v[106:107], v[110:111]
	v_lshlrev_b32_e32 v54, 16, v56
	v_pk_mul_f32 v[106:107], v[88:89], v[106:107]
	v_add_f32_e32 v32, 1.0, v32
	v_add_f32_e32 v44, 1.0, v44
	v_cvt_pk_bf16_f32 v28, v106, v107
	v_rcp_f32_e32 v106, v32
	v_mul_f32_e32 v32, 0xbfb8aa3b, v73
	v_rcp_f32_e32 v64, v44
	v_mul_f32_e32 v44, 0xbfb8aa3b, v63
	v_exp_f32_e32 v32, v32
	v_exp_f32_e32 v44, v44
	v_and_b32_e32 v55, 0xffff0000, v56
	v_pk_fma_f32 v[60:61], v[14:15], v[50:51], v[60:61]
	v_add_f32_e32 v32, 1.0, v32
	v_add_f32_e32 v44, 1.0, v44
	v_pk_fma_f32 v[60:61], v[18:19], v[54:55], v[60:61]
	v_rcp_f32_e32 v107, v32
	v_mul_f32_e32 v36, 0xbfb8aa3b, v68
	v_rcp_f32_e32 v65, v44
	v_mul_f32_e32 v48, 0xbfb8aa3b, v60
	v_exp_f32_e32 v36, v36
	v_exp_f32_e32 v48, v48
	v_pk_mul_f32 v[72:73], v[72:73], v[106:107]
	v_pk_mul_f32 v[62:63], v[62:63], v[64:65]
	v_pk_mul_f32 v[72:73], v[88:89], v[72:73]
	v_add_f32_e32 v36, 1.0, v36
	v_pk_mul_f32 v[62:63], v[88:89], v[62:63]
	v_add_f32_e32 v48, 1.0, v48
	v_cvt_pk_bf16_f32 v32, v72, v73
	v_rcp_f32_e32 v72, v36
	v_mul_f32_e32 v36, 0xbfb8aa3b, v69
	v_cvt_pk_bf16_f32 v44, v62, v63
	v_rcp_f32_e32 v62, v48
	v_mul_f32_e32 v48, 0xbfb8aa3b, v61
	v_exp_f32_e32 v36, v36
	v_exp_f32_e32 v48, v48
	v_mul_f32_e32 v40, 0xbfb8aa3b, v66
	v_exp_f32_e32 v40, v40
	v_add_f32_e32 v36, 1.0, v36
	v_add_f32_e32 v48, 1.0, v48
	v_rcp_f32_e32 v73, v36
	v_rcp_f32_e32 v63, v48
	v_add_f32_e32 v40, 1.0, v40
	v_pk_fma_f32 v[6:7], v[10:11], v[50:51], v[6:7]
	v_pk_mul_f32 v[68:69], v[68:69], v[72:73]
	v_pk_mul_f32 v[60:61], v[60:61], v[62:63]
	v_pk_mul_f32 v[68:69], v[88:89], v[68:69]
	v_pk_mul_f32 v[60:61], v[88:89], v[60:61]
	v_cvt_pk_bf16_f32 v36, v68, v69
	v_rcp_f32_e32 v68, v40
	v_mul_f32_e32 v40, 0xbfb8aa3b, v67
	v_cvt_pk_bf16_f32 v48, v60, v61
	v_lshlrev_b32_e32 v60, 16, v4
	v_and_b32_e32 v61, 0xffff0000, v4
	v_pk_fma_f32 v[6:7], v[14:15], v[54:55], v[6:7]
	v_exp_f32_e32 v40, v40
	v_pk_fma_f32 v[6:7], v[18:19], v[60:61], v[6:7]
	v_lshlrev_b32_e32 v104, 16, v29
	v_mul_f32_e32 v4, 0xbfb8aa3b, v6
	v_exp_f32_e32 v4, v4
	v_add_f32_e32 v40, 1.0, v40
	v_rcp_f32_e32 v69, v40
	v_and_b32_e32 v105, 0xffff0000, v29
	v_add_f32_e32 v4, 1.0, v4
	v_rcp_f32_e32 v10, v4
	v_mul_f32_e32 v4, 0xbfb8aa3b, v7
	v_exp_f32_e32 v4, v4
	v_pk_mul_f32 v[66:67], v[66:67], v[68:69]
	v_lshlrev_b32_e32 v70, 16, v25
	v_pk_mul_f32 v[66:67], v[88:89], v[66:67]
	v_and_b32_e32 v71, 0xffff0000, v25
	v_pk_fma_f32 v[104:105], v[12:13], v[104:105], v[8:9]
	v_cvt_pk_bf16_f32 v40, v66, v67
	v_lshlrev_b32_e32 v66, 16, v33
	v_and_b32_e32 v67, 0xffff0000, v33
	v_pk_fma_f32 v[72:73], v[12:13], v[70:71], v[8:9]
	v_pk_fma_f32 v[70:71], v[16:17], v[70:71], v[104:105]
	v_add_f32_e32 v4, 1.0, v4
	v_pk_fma_f32 v[70:71], v[20:21], v[66:67], v[70:71]
	v_rcp_f32_e32 v11, v4
	v_mul_f32_e32 v4, 0xbfb8aa3b, v70
	v_exp_f32_e32 v4, v4
	v_lshlrev_b32_e32 v62, 16, v37
	v_and_b32_e32 v63, 0xffff0000, v37
	v_pk_fma_f32 v[68:69], v[12:13], v[66:67], v[8:9]
	v_add_f32_e32 v4, 1.0, v4
	v_rcp_f32_e32 v104, v4
	v_mul_f32_e32 v4, 0xbfb8aa3b, v71
	v_exp_f32_e32 v4, v4
	v_pk_fma_f32 v[66:67], v[16:17], v[66:67], v[72:73]
	v_lshlrev_b32_e32 v14, 16, v57
	v_pk_fma_f32 v[66:67], v[20:21], v[62:63], v[66:67]
	v_add_f32_e32 v4, 1.0, v4
	v_rcp_f32_e32 v105, v4
	v_mul_f32_e32 v4, 0xbfb8aa3b, v66
	v_exp_f32_e32 v4, v4
	v_and_b32_e32 v15, 0xffff0000, v57
	v_pk_mul_f32 v[70:71], v[70:71], v[104:105]
	v_lshlrev_b32_e32 v56, 16, v41
	v_pk_mul_f32 v[70:71], v[88:89], v[70:71]
	v_add_f32_e32 v4, 1.0, v4
	v_cvt_pk_bf16_f32 v25, v70, v71
	v_rcp_f32_e32 v70, v4
	v_mul_f32_e32 v4, 0xbfb8aa3b, v67
	v_exp_f32_e32 v4, v4
	v_and_b32_e32 v57, 0xffff0000, v41
	v_pk_fma_f32 v[64:65], v[12:13], v[62:63], v[8:9]
	v_pk_fma_f32 v[62:63], v[16:17], v[62:63], v[68:69]
	v_add_f32_e32 v4, 1.0, v4
	v_pk_fma_f32 v[62:63], v[20:21], v[56:57], v[62:63]
	v_rcp_f32_e32 v71, v4
	v_mul_f32_e32 v4, 0xbfb8aa3b, v62
	v_exp_f32_e32 v4, v4
	v_lshlrev_b32_e32 v54, 16, v45
	v_pk_mul_f32 v[66:67], v[66:67], v[70:71]
	v_and_b32_e32 v55, 0xffff0000, v45
	v_pk_mul_f32 v[66:67], v[88:89], v[66:67]
	v_add_f32_e32 v4, 1.0, v4
	v_cvt_pk_bf16_f32 v29, v66, v67
	v_rcp_f32_e32 v66, v4
	v_mul_f32_e32 v4, 0xbfb8aa3b, v63
	v_exp_f32_e32 v4, v4
	v_pk_fma_f32 v[60:61], v[12:13], v[56:57], v[8:9]
	v_pk_fma_f32 v[56:57], v[16:17], v[56:57], v[64:65]
	v_pk_mul_f32 v[6:7], v[6:7], v[10:11]
	v_add_f32_e32 v4, 1.0, v4
	v_pk_fma_f32 v[56:57], v[20:21], v[54:55], v[56:57]
	v_rcp_f32_e32 v67, v4
	v_mul_f32_e32 v4, 0xbfb8aa3b, v56
	v_exp_f32_e32 v4, v4
	v_lshlrev_b32_e32 v10, 16, v53
	v_pk_mul_f32 v[62:63], v[62:63], v[66:67]
	v_and_b32_e32 v11, 0xffff0000, v53
	v_pk_mul_f32 v[62:63], v[88:89], v[62:63]
	v_add_f32_e32 v4, 1.0, v4
	v_cvt_pk_bf16_f32 v33, v62, v63
	v_rcp_f32_e32 v62, v4
	v_mul_f32_e32 v4, 0xbfb8aa3b, v57
	v_exp_f32_e32 v4, v4
	v_lshlrev_b32_e32 v50, 16, v49
	v_and_b32_e32 v51, 0xffff0000, v49
	v_pk_fma_f32 v[52:53], v[12:13], v[54:55], v[8:9]
	v_pk_fma_f32 v[54:55], v[16:17], v[54:55], v[60:61]
	v_add_f32_e32 v4, 1.0, v4
	v_pk_fma_f32 v[54:55], v[20:21], v[50:51], v[54:55]
	v_rcp_f32_e32 v63, v4
	v_mul_f32_e32 v4, 0xbfb8aa3b, v54
	v_exp_f32_e32 v4, v4
	v_pk_fma_f32 v[18:19], v[12:13], v[50:51], v[8:9]
	v_pk_mul_f32 v[56:57], v[56:57], v[62:63]
	v_pk_fma_f32 v[50:51], v[16:17], v[50:51], v[52:53]
	v_pk_mul_f32 v[56:57], v[88:89], v[56:57]
	v_add_f32_e32 v4, 1.0, v4
	v_cvt_pk_bf16_f32 v37, v56, v57
	v_rcp_f32_e32 v56, v4
	v_mul_f32_e32 v4, 0xbfb8aa3b, v55
	v_exp_f32_e32 v4, v4
	v_pk_fma_f32 v[50:51], v[20:21], v[10:11], v[50:51]
	v_pk_fma_f32 v[18:19], v[16:17], v[10:11], v[18:19]
	v_pk_fma_f32 v[8:9], v[12:13], v[10:11], v[8:9]
	v_add_f32_e32 v4, 1.0, v4
	v_rcp_f32_e32 v57, v4
	v_mul_f32_e32 v4, 0xbfb8aa3b, v50
	v_exp_f32_e32 v4, v4
	v_pk_fma_f32 v[18:19], v[20:21], v[14:15], v[18:19]
	v_pk_fma_f32 v[8:9], v[16:17], v[14:15], v[8:9]
	v_pk_mul_f32 v[2:3], v[88:89], v[2:3]
	v_add_f32_e32 v4, 1.0, v4
	v_rcp_f32_e32 v52, v4
	v_mul_f32_e32 v4, 0xbfb8aa3b, v51
	v_exp_f32_e32 v4, v4
	v_pk_mul_f32 v[6:7], v[88:89], v[6:7]
	v_pk_mul_f32 v[54:55], v[54:55], v[56:57]
	v_cvt_pk_bf16_f32 v6, v6, v7
	v_add_f32_e32 v4, 1.0, v4
	v_rcp_f32_e32 v53, v4
	v_mul_f32_e32 v4, 0xbfb8aa3b, v18
	v_exp_f32_e32 v4, v4
	v_pk_mul_f32 v[54:55], v[88:89], v[54:55]
	v_pk_mul_f32 v[50:51], v[50:51], v[52:53]
	v_pk_mul_f32 v[58:59], v[88:89], v[58:59]
	v_pk_mul_f32 v[50:51], v[88:89], v[50:51]
	v_add_f32_e32 v4, 1.0, v4
	v_cvt_pk_bf16_f32 v45, v50, v51
	v_rcp_f32_e32 v50, v4
	v_mul_f32_e32 v4, 0xbfb8aa3b, v19
	v_exp_f32_e32 v4, v4
	v_cvt_pk_bf16_f32 v41, v54, v55
	v_add_f32_e32 v4, 1.0, v4
	v_rcp_f32_e32 v51, v4
	v_lshlrev_b32_e32 v4, 16, v5
	v_and_b32_e32 v5, 0xffff0000, v5
	v_pk_fma_f32 v[4:5], v[20:21], v[4:5], v[8:9]
	v_pk_mul_f32 v[18:19], v[18:19], v[50:51]
	v_mul_f32_e32 v8, 0xbfb8aa3b, v4
	v_mul_f32_e32 v9, 0xbfb8aa3b, v5
	v_exp_f32_e32 v8, v8
	v_exp_f32_e32 v9, v9
	v_pk_mul_f32 v[18:19], v[88:89], v[18:19]
	v_add_f32_e32 v8, 1.0, v8
	v_add_f32_e32 v9, 1.0, v9
	v_rcp_f32_e32 v8, v8
	v_rcp_f32_e32 v9, v9
	v_cvt_pk_bf16_f32 v49, v18, v19
	v_pk_mul_f32 v[4:5], v[4:5], v[8:9]
	s_nop 0
	v_pk_mul_f32 v[8:9], v[88:89], v[4:5]
	v_cvt_pk_bf16_f32 v5, v2, v3
	v_lshl_add_u64 v[2:3], v[90:91], 0, s[46:47]
	v_cvt_pk_bf16_f32 v7, v8, v9
	v_add_co_u32_e32 v8, vcc, s1, v2
	global_store_dwordx4 v[2:3], v[22:25], off
	global_store_dwordx4 v[2:3], v[26:29], off offset:2048
	v_addc_co_u32_e32 v9, vcc, 0, v3, vcc
	global_store_dwordx4 v[8:9], v[30:33], off
	global_store_dwordx4 v[8:9], v[34:37], off offset:2048
	v_add_co_u32_e32 v8, vcc, 0x2000, v2
	v_cvt_pk_bf16_f32 v4, v58, v59
	s_nop 0
	v_addc_co_u32_e32 v9, vcc, 0, v3, vcc
	v_add_co_u32_e32 v2, vcc, 0x3000, v2
	global_store_dwordx4 v[8:9], v[38:41], off
	global_store_dwordx4 v[8:9], v[42:45], off offset:2048
	v_addc_co_u32_e32 v3, vcc, 0, v3, vcc
	global_store_dwordx4 v[2:3], v[46:49], off
	global_store_dwordx4 v[2:3], v[4:7], off offset:2048
.LBB0_284:
	s_and_b64 vcc, exec, s[14:15]
	s_cbranch_vccz .LBB0_261
	v_lshl_add_u64 v[2:3], s[2:3], 0, v[96:97]
	v_add_co_u32_e32 v4, vcc, 0x28a00000, v2
	v_lshl_add_u64 v[18:19], s[2:3], 0, v[100:101]
	s_nop 0
	v_addc_co_u32_e32 v5, vcc, 0, v3, vcc
	v_add_co_u32_e32 v6, vcc, 0x28c80000, v2
	v_lshl_add_u64 v[20:21], s[2:3], 0, v[102:103]
	s_nop 0
	v_addc_co_u32_e32 v7, vcc, 0, v3, vcc
	global_load_dwordx4 v[14:17], v[4:5], off
	global_load_dwordx4 v[10:13], v[6:7], off
	v_add_co_u32_e32 v4, vcc, 0x28f00000, v2
	s_nop 1
	v_addc_co_u32_e32 v5, vcc, 0, v3, vcc
	v_add_co_u32_e32 v2, vcc, 0x29180000, v2
	s_nop 1
	v_addc_co_u32_e32 v3, vcc, 0, v3, vcc
	global_load_dwordx4 v[6:9], v[4:5], off
	global_load_dwordx4 v[2:5], v[2:3], off
	global_load_dwordx4 v[22:25], v[18:19], off
	global_load_dwordx4 v[18:21], v[20:21], off
	s_and_saveexec_b64 s[14:15], s[4:5]
	s_cbranch_execz .LBB0_289
	v_lshl_add_u64 v[26:27], s[2:3], 0, v[98:99]
	v_add_co_u32_e32 v28, vcc, 0x29180000, v26
	s_mov_b32 s1, 0x28a00000
	s_nop 0
	v_addc_co_u32_e32 v29, vcc, 0, v27, vcc
	global_load_ushort v30, v[28:29], off offset:128
	v_add_co_u32_e32 v28, vcc, 0x28c80000, v26
	s_load_dwordx2 s[26:27], s[20:21], 0xd8
	s_nop 0
	v_addc_co_u32_e32 v29, vcc, 0, v27, vcc
	global_load_ushort v28, v[28:29], off offset:128
	s_waitcnt vmcnt(0)
	v_lshlrev_b32_e32 v29, 16, v28
	v_lshlrev_b32_e32 v28, 16, v30
	v_add_co_u32_e32 v30, vcc, 0x28f00000, v26
	s_nop 1
	v_addc_co_u32_e32 v31, vcc, 0, v27, vcc
	v_add_co_u32_e32 v26, vcc, s1, v26
	global_load_ushort v30, v[30:31], off offset:128
	s_nop 0
	v_addc_co_u32_e32 v27, vcc, 0, v27, vcc
	global_load_ushort v26, v[26:27], off offset:128
	s_waitcnt vmcnt(0)
	v_lshlrev_b32_e32 v27, 16, v26
	v_lshlrev_b32_e32 v26, 16, v30
	v_pk_add_f32 v[26:27], v[28:29], v[26:27]
	s_nop 0
	v_add_f32_e32 v28, v26, v27
	s_waitcnt lgkmcnt(0)
	v_lshl_add_u64 v[26:27], v[76:77], 2, s[26:27]
	global_load_dword v26, v[26:27], off
	s_waitcnt vmcnt(0)
	v_add_f32_e32 v26, v26, v28
	s_and_saveexec_b64 s[26:27], s[6:7]
	s_cbranch_execz .LBB0_288
	s_mov_b32 s1, 0xbfb8aa3b
	v_mul_f32_e64 v27, |v26|, s1
	v_exp_f32_e32 v27, v27
	s_mov_b32 s1, 0x3a83126f
	v_max_f32_e32 v26, v26, v26
	v_min_f32_e32 v26, 0, v26
	v_add_f32_e32 v28, 1.0, v27
	v_log_f32_e32 v28, v28
	v_fma_f32 v29, v27, -0.5, 1.0
	v_mul_f32_e32 v29, v27, v29
	v_cmp_gt_f32_e32 vcc, s1, v27
	v_mul_f32_e32 v28, 0x3f317218, v28
	s_nop 0
	v_cndmask_b32_e32 v27, v28, v29, vcc
	v_sub_f32_e32 v26, v26, v27

.LBB0_289:
	s_or_b64 exec, exec, s[14:15]
	s_load_dwordx2 s[14:15], s[20:21], 0xe8
	s_waitcnt vmcnt(0)
	v_lshlrev_b32_e32 v32, 16, v25
	v_and_b32_e32 v33, 0xffff0000, v25
	v_lshlrev_b32_e32 v36, 16, v24
	v_and_b32_e32 v37, 0xffff0000, v24
	s_waitcnt lgkmcnt(0)
	v_lshl_add_u64 v[28:29], v[78:79], 2, s[14:15]
	global_load_dwordx4 v[24:27], v[28:29], off offset:16
	global_load_dwordx4 v[28:31], v[28:29], off
	v_lshlrev_b32_e32 v44, 16, v22
	v_and_b32_e32 v45, 0xffff0000, v22
	v_lshlrev_b32_e32 v40, 16, v23
	v_and_b32_e32 v41, 0xffff0000, v23
	v_pk_mul_f32 v[22:23], v[44:45], v[44:45]
	v_pk_mul_f32 v[42:43], v[40:41], v[40:41]
	v_add_f32_e32 v22, v22, v23
	v_add_f32_e32 v22, v42, v22
	v_pk_mul_f32 v[38:39], v[36:37], v[36:37]
	v_add_f32_e32 v22, v43, v22
	v_add_f32_e32 v22, v38, v22
	v_pk_mul_f32 v[34:35], v[32:33], v[32:33]
	v_add_f32_e32 v22, v39, v22
	v_add_f32_e32 v22, v34, v22
	v_add_f32_e32 v22, v35, v22
	s_nop 1
	v_add_f32_dpp v22, v22, v22 quad_perm:[1,0,3,2] row_mask:0xf bank_mask:0xf bound_ctrl:1
	s_nop 1
	v_add_f32_dpp v22, v22, v22 quad_perm:[2,3,0,1] row_mask:0xf bank_mask:0xf bound_ctrl:1
	s_nop 1
	v_add_f32_dpp v22, v22, v22 row_half_mirror row_mask:0xf bank_mask:0xf bound_ctrl:1
	s_nop 1
	v_add_f32_dpp v22, v22, v22 row_mirror row_mask:0xf bank_mask:0xf bound_ctrl:1
	ds_swizzle_b32 v23, v22 offset:swizzle(SWAP,16)
	s_waitcnt lgkmcnt(0)
	v_add_f32_e32 v22, v22, v23
	v_mov_b32_e32 v23, v22
	s_nop 1
	v_permlane32_swap_b32_e32 v22, v23
	v_add_f32_e32 v22, v22, v23
	v_fmamk_f32 v22, v22, 0x3b000000, v233
	v_rsq_f32_e32 v22, v22
	s_nop 0
	v_pk_mul_f32 v[34:35], v[22:23], v[44:45] op_sel_hi:[0,1]
	s_waitcnt vmcnt(0)
	v_pk_mul_f32 v[28:29], v[28:29], v[34:35]
	v_pk_mul_f32 v[34:35], v[22:23], v[40:41] op_sel_hi:[0,1]
	v_pk_mul_f32 v[30:31], v[30:31], v[34:35]
	v_pk_mul_f32 v[34:35], v[22:23], v[36:37] op_sel_hi:[0,1]
	v_pk_mul_f32 v[22:23], v[22:23], v[32:33] op_sel_hi:[0,1]
	v_pk_mul_f32 v[24:25], v[24:25], v[34:35]
	v_pk_mul_f32 v[26:27], v[22:23], v[26:27]
	v_cvt_pk_bf16_f32 v22, v28, v29
	v_cvt_pk_bf16_f32 v23, v30, v31
	v_cvt_pk_bf16_f32 v24, v24, v25
	v_cvt_pk_bf16_f32 v25, v26, v27
	v_lshl_add_u64 v[26:27], s[2:3], 0, v[94:95]
	global_store_dwordx4 v[26:27], v[22:25], off
	v_mov_b32_e32 v30, 0
	v_mov_b32_e32 v26, 0
	v_mov_b32_e32 v22, 0
	v_mov_b32_e32 v23, 0
	v_mov_b32_e32 v24, 0
	v_mov_b32_e32 v25, 0
	v_mov_b32_e32 v27, 0
	v_mov_b32_e32 v28, 0
	v_mov_b32_e32 v29, 0
	s_and_saveexec_b64 s[14:15], s[4:5]
	s_cbranch_execz .LBB0_291
	v_lshlrev_b32_e32 v22, 16, v18
	v_and_b32_e32 v23, 0xffff0000, v18
	v_pk_mul_f32 v[30:31], v[22:23], v[22:23]
	v_and_b32_e32 v18, 0xffff0000, v19
	v_lshlrev_b32_e32 v19, 16, v19
	v_pk_mov_b32 v[24:25], v[18:19], v[18:19] op_sel:[1,0]
	v_pk_mul_f32 v[18:19], v[18:19], v[18:19]
	v_add_f32_e32 v30, v30, v31
	v_and_b32_e32 v28, 0xffff0000, v20
	v_lshlrev_b32_e32 v29, 16, v20
	v_add_f32_e32 v19, v19, v30
	v_pk_mul_f32 v[32:33], v[28:29], v[28:29]
	v_add_f32_e32 v18, v18, v19
	v_and_b32_e32 v20, 0xffff0000, v21
	v_lshlrev_b32_e32 v21, 16, v21
	v_add_f32_e32 v18, v33, v18
	v_pk_mov_b32 v[26:27], v[28:29], v[28:29] op_sel:[1,0]
	v_pk_mov_b32 v[28:29], v[20:21], v[20:21] op_sel:[1,0]
	v_pk_mul_f32 v[20:21], v[20:21], v[20:21]
	v_add_f32_e32 v18, v32, v18
	v_add_f32_e32 v18, v21, v18
	v_add_f32_e32 v30, v20, v18
.LBB0_291:
	s_or_b64 exec, exec, s[14:15]
	s_nop 0
	v_add_f32_dpp v18, v30, v30 quad_perm:[1,0,3,2] row_mask:0xf bank_mask:0xf bound_ctrl:1
	s_add_i32 s1, s0, 0xffffe000
	s_lshr_b32 s1, s1, 10
	v_add_f32_dpp v18, v18, v18 quad_perm:[2,3,0,1] row_mask:0xf bank_mask:0xf bound_ctrl:1
	s_mulk_i32 s1, 0x500
	s_and_b32 s14, s0, 0x3ff
	v_add_f32_dpp v18, v18, v18 row_half_mirror row_mask:0xf bank_mask:0xf bound_ctrl:1
	s_add_i32 s1, s14, s1
	s_ashr_i32 s29, s0, 8
	v_add_f32_dpp v18, v18, v18 row_mirror row_mask:0xf bank_mask:0xf bound_ctrl:1
	ds_swizzle_b32 v19, v18 offset:swizzle(SWAP,16)
	s_addk_i32 s1, 0x2100
	s_cmpk_lt_i32 s0, 0x2000
	s_cselect_b64 s[14:15], -1, 0
	s_and_b64 s[26:27], s[14:15], exec
	s_movk_i32 s26, 0x3ff
	s_waitcnt lgkmcnt(0)
	v_add_f32_e32 v18, v18, v19
	s_cselect_b32 s27, 0xff, s26
	v_mov_b32_e32 v19, v18
	v_cndmask_b32_e64 v20, 0, 1, s[14:15]
	s_cselect_b32 s26, s0, s1
	s_and_b32 s1, s27, s0
	v_permlane32_swap_b32_e32 v18, v19
	v_cmp_ne_u32_e64 s[14:15], 1, v20
	s_and_saveexec_b64 s[30:31], s[4:5]
	s_cbranch_execz .LBB0_294
	s_load_dwordx2 s[34:35], s[20:21], 0xf8
	v_add_f32_e32 v18, v18, v19
	v_fmamk_f32 v18, v18, 0x3b800000, v233
	v_rsq_f32_e32 v34, v18
	s_ashr_i32 s27, s26, 31
	s_waitcnt lgkmcnt(0)
	v_lshl_add_u64 v[30:31], v[80:81], 2, s[34:35]
	global_load_dwordx4 v[18:21], v[30:31], off offset:16
	global_load_dwordx4 v[30:33], v[30:31], off
	v_pk_mul_f32 v[26:27], v[26:27], v[34:35] op_sel_hi:[1,0]
	v_pk_mul_f32 v[22:23], v[22:23], v[34:35] op_sel_hi:[1,0]
	v_pk_mul_f32 v[24:25], v[24:25], v[34:35] op_sel_hi:[1,0]
	s_lshl_b64 s[34:35], s[26:27], 9
	s_and_b64 vcc, exec, s[14:15]
	s_waitcnt vmcnt(1)
	v_pk_mul_f32 v[18:19], v[26:27], v[18:19]
	v_pk_mul_f32 v[26:27], v[28:29], v[34:35] op_sel_hi:[1,0]
	s_waitcnt vmcnt(0)
	v_pk_mul_f32 v[22:23], v[22:23], v[30:31]
	v_pk_mul_f32 v[24:25], v[24:25], v[32:33]
	v_pk_mul_f32 v[20:21], v[26:27], v[20:21]
	v_cvt_pk_bf16_f32 v26, v22, v23
	v_cvt_pk_bf16_f32 v27, v24, v25
	v_cvt_pk_bf16_f32 v28, v18, v19
	v_cvt_pk_bf16_f32 v29, v20, v21
	v_lshl_add_u64 v[30:31], v[82:83], 0, s[34:35]
	global_store_dwordx4 v[30:31], v[26:29], off
	s_cbranch_vccnz .LBB0_294
	s_lshl_b32 s27, s29, 1
	v_readlane_b32 s34, v254, 54
	v_readlane_b32 s35, v254, 55
	s_add_i32 s34, s27, s34
	s_ashr_i32 s35, s34, 31
	s_lshl_b64 s[34:35], s[34:35], 18
	s_add_u32 s27, s16, s34
	s_addc_u32 s33, s17, s35
	s_lshl_b32 s34, s1, 10
	s_add_u32 s34, s27, s34
	s_addc_u32 s35, s33, 0
	v_lshlrev_b32_e32 v26, 2, v74
	global_store_dwordx4 v26, v[22:25], s[34:35]
	global_store_dwordx4 v26, v[18:21], s[34:35] offset:16

.LBB0_419:
	s_andn2_b64 vcc, exec, s[2:3]
	s_cbranch_vccnz .LBB0_422
	s_load_dwordx4 s[12:15], s[22:23], 0x40
	s_load_dwordx2 s[2:3], s[22:23], 0x50
	s_lshl_b64 s[20:21], s[52:53], 16
	v_lshlrev_b32_e32 v0, 2, v172
	s_waitcnt lgkmcnt(0)
	s_add_u32 s11, s12, s20
	s_addc_u32 s13, s13, s21
	s_lshl_b32 s12, s16, 7
	s_add_u32 s12, s11, s12
	s_addc_u32 s13, s13, 0
	v_lshl_add_u64 v[2:3], s[12:13], 0, v[0:1]
	v_lshl_add_u64 v[2:3], v[2:3], 0, v[176:177]
	v_add_co_u32_e32 v4, vcc, s33, v2
	s_movk_i32 s11, 0x2000
	s_nop 0
	v_addc_co_u32_e32 v5, vcc, 0, v3, vcc
	v_add_co_u32_e32 v6, vcc, s11, v2
	s_movk_i32 s11, 0x3000
	s_nop 0
	v_addc_co_u32_e32 v7, vcc, 0, v3, vcc
	global_load_dword v16, v[2:3], off
	global_load_dword v17, v[2:3], off offset:512
	global_load_dword v18, v[2:3], off offset:1024
	global_load_dword v19, v[2:3], off offset:1536
	global_load_dword v20, v[6:7], off offset:-4096
	global_load_dword v21, v[4:5], off offset:512
	global_load_dword v22, v[4:5], off offset:1024
	global_load_dword v23, v[4:5], off offset:1536
	global_load_dword v24, v[6:7], off
	global_load_dword v25, v[6:7], off offset:512
	global_load_dword v26, v[6:7], off offset:1024
	global_load_dword v27, v[6:7], off offset:1536
	v_add_co_u32_e32 v4, vcc, s11, v2
	s_movk_i32 s11, 0x4000
	s_nop 0
	v_addc_co_u32_e32 v5, vcc, 0, v3, vcc
	v_add_co_u32_e32 v6, vcc, s11, v2
	s_movk_i32 s11, 0x6000
	s_nop 0
	v_addc_co_u32_e32 v7, vcc, 0, v3, vcc
	global_load_dword v28, v[6:7], off offset:-4096
	global_load_dword v29, v[4:5], off offset:512
	global_load_dword v30, v[4:5], off offset:1024
	global_load_dword v31, v[4:5], off offset:1536
	global_load_dword v32, v[6:7], off
	global_load_dword v33, v[6:7], off offset:512
	global_load_dword v34, v[6:7], off offset:1024
	global_load_dword v35, v[6:7], off offset:1536
	v_add_co_u32_e32 v4, vcc, s24, v2
	s_lshl_b64 s[12:13], s[52:53], 9
	s_nop 0
	v_addc_co_u32_e32 v5, vcc, 0, v3, vcc
	v_add_co_u32_e32 v6, vcc, s11, v2
	s_movk_i32 s11, 0x7000
	s_nop 0
	v_addc_co_u32_e32 v7, vcc, 0, v3, vcc
	global_load_dword v36, v[6:7], off offset:-4096
	global_load_dword v37, v[4:5], off offset:512
	global_load_dword v38, v[4:5], off offset:1024
	global_load_dword v39, v[4:5], off offset:1536
	global_load_dword v40, v[6:7], off
	global_load_dword v41, v[6:7], off offset:512
	global_load_dword v42, v[6:7], off offset:1024
	global_load_dword v43, v[6:7], off offset:1536
	v_add_co_u32_e32 v4, vcc, s11, v2
	s_mov_b32 s11, 0x8000
	s_nop 0
	v_addc_co_u32_e32 v5, vcc, 0, v3, vcc
	v_add_co_u32_e32 v6, vcc, s11, v2
	s_mov_b32 s11, 0x9000
	s_nop 0
	v_addc_co_u32_e32 v7, vcc, 0, v3, vcc
	global_load_dword v44, v[6:7], off offset:-4096
	global_load_dword v45, v[4:5], off offset:512
	global_load_dword v46, v[4:5], off offset:1024
	global_load_dword v47, v[4:5], off offset:1536
	global_load_dword v48, v[6:7], off
	global_load_dword v49, v[6:7], off offset:512
	global_load_dword v50, v[6:7], off offset:1024
	global_load_dword v51, v[6:7], off offset:1536
	v_add_co_u32_e32 v4, vcc, s11, v2
	s_mov_b32 s11, 0xa000
	s_nop 0
	v_addc_co_u32_e32 v5, vcc, 0, v3, vcc
	v_add_co_u32_e32 v6, vcc, s11, v2
	s_mov_b32 s11, 0xc000
	s_nop 0
	v_addc_co_u32_e32 v7, vcc, 0, v3, vcc
	global_load_dword v52, v[6:7], off offset:-4096
	global_load_dword v53, v[4:5], off offset:512
	global_load_dword v54, v[4:5], off offset:1024
	global_load_dword v55, v[4:5], off offset:1536
	global_load_dword v56, v[6:7], off
	global_load_dword v57, v[6:7], off offset:512
	global_load_dword v58, v[6:7], off offset:1024
	global_load_dword v59, v[6:7], off offset:1536
	v_add_co_u32_e32 v4, vcc, s17, v2
	s_add_u32 s12, s14, s12
	s_nop 0
	v_addc_co_u32_e32 v5, vcc, 0, v3, vcc
	v_add_co_u32_e32 v6, vcc, s11, v2
	s_mov_b32 s11, 0xd000
	s_nop 0
	v_addc_co_u32_e32 v7, vcc, 0, v3, vcc
	global_load_dword v60, v[6:7], off offset:-4096
	global_load_dword v61, v[4:5], off offset:512
	global_load_dword v62, v[4:5], off offset:1024
	global_load_dword v63, v[4:5], off offset:1536
	global_load_dword v64, v[6:7], off
	global_load_dword v65, v[6:7], off offset:512
	global_load_dword v66, v[6:7], off offset:1024
	global_load_dword v67, v[6:7], off offset:1536
	v_add_co_u32_e32 v4, vcc, s11, v2
	s_mov_b32 s11, 0xe000
	s_nop 0
	v_addc_co_u32_e32 v5, vcc, 0, v3, vcc
	v_add_co_u32_e32 v6, vcc, s11, v2
	s_mov_b32 s11, 0xf000
	s_nop 0
	v_addc_co_u32_e32 v7, vcc, 0, v3, vcc
	global_load_dword v68, v[6:7], off offset:-4096
	global_load_dword v69, v[4:5], off offset:512
	global_load_dword v70, v[4:5], off offset:1024
	global_load_dword v71, v[4:5], off offset:1536
	global_load_dword v72, v[6:7], off
	global_load_dword v73, v[6:7], off offset:512
	global_load_dword v74, v[6:7], off offset:1024
	global_load_dword v75, v[6:7], off offset:1536
	v_add_co_u32_e32 v2, vcc, s11, v2
	s_addc_u32 s13, s15, s13
	s_nop 0
	v_addc_co_u32_e32 v3, vcc, 0, v3, vcc
	v_lshlrev_b32_e32 v0, 2, v170
	global_load_dword v76, v[2:3], off
	global_load_dword v77, v[2:3], off offset:512
	global_load_dword v78, v[2:3], off offset:1024
	global_load_dword v79, v[2:3], off offset:1536
	v_lshl_add_u32 v3, v170, 2, s97
	global_load_dword v2, v0, s[12:13]
	global_load_dword v0, v0, s[12:13] offset:256
	s_lshl_b64 s[12:13], s[52:53], 2
	s_add_u32 s2, s2, s12
	s_addc_u32 s3, s3, s13
	global_load_dword v217, v1, s[2:3]
	s_waitcnt vmcnt(0)
	ds_write2st64_b32 v3, v2, v0 offset0:4 offset1:5
	s_branch .LBB0_423

.LBB0_426:
	s_andn2_b64 vcc, exec, s[12:13]
	s_cbranch_vccnz .LBB0_428
	v_or_b32_e32 v0, s14, v170
	v_lshlrev_b64 v[2:3], 10, v[0:1]
	v_lshl_or_b32 v2, s9, 7, v2
	s_lshl_b32 s12, s16, 4
	v_or_b32_e32 v2, s12, v2
	v_lshlrev_b64 v[2:3], 1, v[2:3]
	v_lshl_add_u64 v[4:5], s[30:31], 0, v[2:3]
	v_lshl_add_u64 v[10:11], s[42:43], 0, v[2:3]
	v_mov_b64_e32 v[2:3], s[74:75]
	v_mad_u64_u32 v[2:3], s[0:1], v0, s85, v[2:3]
	s_lshl_b32 s46, s9, 8
	v_lshl_add_u64 v[2:3], v[2:3], 0, s[46:47]
	s_lshl_b32 s46, s16, 5
	v_lshl_add_u64 v[100:101], v[2:3], 0, s[46:47]
	global_load_dwordx4 v[84:87], v[4:5], off offset:16
	global_load_dwordx4 v[92:95], v[4:5], off
	global_load_dwordx4 v[88:91], v[10:11], off offset:16
	global_load_dwordx4 v[96:99], v[10:11], off
	global_load_dwordx4 v[6:9], v[4:5], off offset:144
	global_load_dwordx4 v[80:83], v[4:5], off offset:128
	global_load_dwordx4 v[2:5], v[10:11], off offset:144
	global_load_dwordx4 v[10:13], v[10:11], off offset:128
	v_add_u32_e32 v0, s46, v179
	s_or_b32 s0, s12, 1
	s_mul_i32 s1, s0, 0x90
	s_add_i32 s12, s1, 0x90
	s_mulk_i32 s0, 0x88
	v_lshl_add_u64 v[14:15], v[100:101], 0, s[40:41]
	s_waitcnt vmcnt(0)
	v_mov_b32_e32 v208, 0
	v_mov_b32_e32 v207, 0
	ds_write2_b64 v0, v[92:93], v[94:95] offset1:1
	v_add_co_u32_e32 v92, vcc, s33, v100
	v_add_u32_e32 v0, 0x4200, v0
	s_nop 0
	v_addc_co_u32_e32 v93, vcc, 0, v101, vcc
	global_load_dwordx4 v[92:95], v[92:93], off
	ds_write2_b64 v0, v[96:97], v[98:99] offset1:1
	v_add_u32_e32 v0, s88, v189
	ds_write_b16 v0, v96 offset:33792
	v_add_u32_e32 v0, s1, v189
	ds_write_b16_d16_hi v0, v96 offset:33792
	v_add_u32_e32 v0, s12, v189
	s_add_i32 s12, s1, 0x120
	ds_write_b16 v0, v97 offset:33792
	v_add_u32_e32 v0, s12, v189
	s_add_i32 s12, s1, 0x1b0
	ds_write_b16_d16_hi v0, v97 offset:33792
	v_add_u32_e32 v0, s12, v189
	s_add_i32 s12, s1, 0x240
	ds_write_b16 v0, v98 offset:33792
	v_add_u32_e32 v0, s12, v189
	s_add_i32 s12, s1, 0x2d0
	ds_write_b16_d16_hi v0, v98 offset:33792
	v_add_u32_e32 v0, s12, v189
	s_addk_i32 s1, 0x360
	ds_write_b16 v0, v99 offset:33792
	v_add_u32_e32 v0, s1, v189
	ds_write_b16_d16_hi v0, v99 offset:33792
	v_add_u32_e32 v0, s17, v189
	s_add_i32 s1, s0, 0x88
	s_waitcnt vmcnt(0)
	ds_write_b16 v0, v92 offset:52224
	v_add_u32_e32 v0, s0, v189
	ds_write_b16_d16_hi v0, v92 offset:52224
	v_add_u32_e32 v0, s1, v189
	s_add_i32 s1, s0, 0x110
	ds_write_b16 v0, v93 offset:52224
	v_add_u32_e32 v0, s1, v189
	s_add_i32 s1, s0, 0x198
	ds_write_b16_d16_hi v0, v93 offset:52224
	v_add_u32_e32 v0, s1, v189
	s_add_i32 s1, s0, 0x220
	ds_write_b16 v0, v94 offset:52224
	v_add_u32_e32 v0, s1, v189
	s_add_i32 s1, s0, 0x2a8
	ds_write_b16_d16_hi v0, v94 offset:52224
	v_add_u32_e32 v0, s1, v189
	s_addk_i32 s0, 0x330
	ds_write_b16 v0, v95 offset:52224
	v_add_u32_e32 v0, s0, v189
	ds_write_b16_d16_hi v0, v95 offset:52224
	global_load_dwordx4 v[92:95], v[14:15], off offset:16
	global_load_dwordx4 v[96:99], v[14:15], off offset:128
	global_load_dwordx4 v[100:103], v[14:15], off offset:144
	s_lshl_b32 s0, s16, 1
	s_or_b32 s1, s0, 1
	v_lshl_add_u32 v0, s1, 4, v179
	s_lshl_b32 s12, s1, 3
	ds_write2_b64 v0, v[84:85], v[86:87] offset1:1
	v_add_u32_e32 v0, 0x4200, v0
	s_mul_i32 s13, s1, 0x480
	s_or_b32 s12, s12, 1
	ds_write2_b64 v0, v[88:89], v[90:91] offset1:1
	v_add_u32_e32 v0, s13, v189
	s_mul_i32 s13, s12, 0x90
	ds_write_b16 v0, v88 offset:33792
	v_add_u32_e32 v0, s13, v189
	s_add_i32 s14, s13, 0x90
	ds_write_b16_d16_hi v0, v88 offset:33792
	v_add_u32_e32 v0, s14, v189
	s_add_i32 s14, s13, 0x120
	ds_write_b16 v0, v89 offset:33792
	v_add_u32_e32 v0, s14, v189
	s_add_i32 s14, s13, 0x1b0
	ds_write_b16_d16_hi v0, v89 offset:33792
	v_add_u32_e32 v0, s14, v189
	s_add_i32 s14, s13, 0x240
	ds_write_b16 v0, v90 offset:33792
	v_add_u32_e32 v0, s14, v189
	s_add_i32 s14, s13, 0x2d0
	ds_write_b16_d16_hi v0, v90 offset:33792
	v_add_u32_e32 v0, s14, v189
	s_addk_i32 s13, 0x360
	ds_write_b16 v0, v91 offset:33792
	v_add_u32_e32 v0, s13, v189
	s_mulk_i32 s1, 0x440
	ds_write_b16_d16_hi v0, v91 offset:33792
	v_add_u32_e32 v0, s1, v189
	s_mul_i32 s1, s12, 0x88
	s_add_i32 s12, s1, 0x88
	s_waitcnt vmcnt(2)
	ds_write_b16 v0, v92 offset:52224
	v_add_u32_e32 v0, s1, v189
	ds_write_b16_d16_hi v0, v92 offset:52224
	v_add_u32_e32 v0, s12, v189
	s_add_i32 s12, s1, 0x110
	ds_write_b16 v0, v93 offset:52224
	v_add_u32_e32 v0, s12, v189
	s_add_i32 s12, s1, 0x198
	ds_write_b16_d16_hi v0, v93 offset:52224
	v_add_u32_e32 v0, s12, v189
	s_add_i32 s12, s1, 0x220
	ds_write_b16 v0, v94 offset:52224
	v_add_u32_e32 v0, s12, v189
	s_add_i32 s12, s1, 0x2a8
	ds_write_b16_d16_hi v0, v94 offset:52224
	v_add_u32_e32 v0, s12, v189
	s_addk_i32 s1, 0x330
	ds_write_b16 v0, v95 offset:52224
	v_add_u32_e32 v0, s1, v189
	s_or_b32 s1, s0, 8
	ds_write_b16_d16_hi v0, v95 offset:52224
	v_lshl_add_u32 v0, s1, 4, v179
	s_lshl_b32 s12, s1, 3
	ds_write2_b64 v0, v[80:81], v[82:83] offset1:1
	v_add_u32_e32 v0, 0x4200, v0
	s_mul_i32 s13, s1, 0x480
	s_or_b32 s12, s12, 1
	ds_write2_b64 v0, v[10:11], v[12:13] offset1:1
	v_add_u32_e32 v0, s13, v189
	s_mul_i32 s13, s12, 0x90
	ds_write_b16 v0, v10 offset:33792
	v_add_u32_e32 v0, s13, v189
	s_add_i32 s14, s13, 0x90
	ds_write_b16_d16_hi v0, v10 offset:33792
	v_add_u32_e32 v0, s14, v189
	s_add_i32 s14, s13, 0x120
	ds_write_b16 v0, v11 offset:33792
	v_add_u32_e32 v0, s14, v189
	s_add_i32 s14, s13, 0x1b0
	ds_write_b16_d16_hi v0, v11 offset:33792
	v_add_u32_e32 v0, s14, v189
	s_add_i32 s14, s13, 0x240
	ds_write_b16 v0, v12 offset:33792
	v_add_u32_e32 v0, s14, v189
	s_add_i32 s14, s13, 0x2d0
	ds_write_b16_d16_hi v0, v12 offset:33792
	v_add_u32_e32 v0, s14, v189
	s_addk_i32 s13, 0x360
	ds_write_b16 v0, v13 offset:33792
	v_add_u32_e32 v0, s13, v189
	s_mulk_i32 s1, 0x440
	ds_write_b16_d16_hi v0, v13 offset:33792
	v_add_u32_e32 v0, s1, v189
	s_mul_i32 s1, s12, 0x88
	s_waitcnt vmcnt(1)
	ds_write_b16 v0, v96 offset:52224
	v_add_u32_e32 v0, s1, v189
	s_add_i32 s12, s1, 0x88
	ds_write_b16_d16_hi v0, v96 offset:52224
	v_add_u32_e32 v0, s12, v189
	s_add_i32 s12, s1, 0x110
	ds_write_b16 v0, v97 offset:52224
	v_add_u32_e32 v0, s12, v189
	s_add_i32 s12, s1, 0x198
	ds_write_b16_d16_hi v0, v97 offset:52224
	v_add_u32_e32 v0, s12, v189
	s_add_i32 s12, s1, 0x220
	ds_write_b16 v0, v98 offset:52224
	v_add_u32_e32 v0, s12, v189
	s_add_i32 s12, s1, 0x2a8
	ds_write_b16_d16_hi v0, v98 offset:52224
	v_add_u32_e32 v0, s12, v189
	s_addk_i32 s1, 0x330
	ds_write_b16 v0, v99 offset:52224
	v_add_u32_e32 v0, s1, v189
	s_or_b32 s0, s0, 9
	ds_write_b16_d16_hi v0, v99 offset:52224
	v_lshl_add_u32 v0, s0, 4, v179
	s_lshl_b32 s1, s0, 3
	ds_write2_b64 v0, v[6:7], v[8:9] offset1:1
	v_add_u32_e32 v0, 0x4200, v0
	s_mul_i32 s12, s0, 0x480
	s_or_b32 s1, s1, 1
	ds_write2_b64 v0, v[2:3], v[4:5] offset1:1
	v_add_u32_e32 v0, s12, v189
	s_mul_i32 s12, s1, 0x90
	ds_write_b16 v0, v2 offset:33792
	v_add_u32_e32 v0, s12, v189
	s_add_i32 s13, s12, 0x90
	ds_write_b16_d16_hi v0, v2 offset:33792
	v_add_u32_e32 v0, s13, v189
	s_add_i32 s13, s12, 0x120
	ds_write_b16 v0, v3 offset:33792
	v_add_u32_e32 v0, s13, v189
	s_add_i32 s13, s12, 0x1b0
	ds_write_b16_d16_hi v0, v3 offset:33792
	v_add_u32_e32 v0, s13, v189
	s_add_i32 s13, s12, 0x240
	ds_write_b16 v0, v4 offset:33792
	v_add_u32_e32 v0, s13, v189
	s_add_i32 s13, s12, 0x2d0
	ds_write_b16_d16_hi v0, v4 offset:33792
	v_add_u32_e32 v0, s13, v189
	s_addk_i32 s12, 0x360
	ds_write_b16 v0, v5 offset:33792
	v_add_u32_e32 v0, s12, v189
	s_mulk_i32 s0, 0x440
	ds_write_b16_d16_hi v0, v5 offset:33792
	v_add_u32_e32 v0, s0, v189
	s_mul_i32 s0, s1, 0x88
	s_waitcnt vmcnt(0)
	ds_write_b16 v0, v100 offset:52224
	v_add_u32_e32 v0, s0, v189
	s_add_i32 s1, s0, 0x88
	ds_write_b16_d16_hi v0, v100 offset:52224
	v_add_u32_e32 v0, s1, v189
	s_add_i32 s1, s0, 0x110
	ds_write_b16 v0, v101 offset:52224
	v_add_u32_e32 v0, s1, v189
	s_add_i32 s1, s0, 0x198
	ds_write_b16_d16_hi v0, v101 offset:52224
	v_add_u32_e32 v0, s1, v189
	s_add_i32 s1, s0, 0x220
	ds_write_b16 v0, v102 offset:52224
	v_add_u32_e32 v0, s1, v189
	s_add_i32 s1, s0, 0x2a8
	ds_write_b16_d16_hi v0, v102 offset:52224
	v_add_u32_e32 v0, s1, v189
	s_addk_i32 s0, 0x330
	ds_write_b16 v0, v103 offset:52224
	v_add_u32_e32 v0, s0, v189
	ds_write_b16_d16_hi v0, v103 offset:52224

.LBB0_430:
	s_not_b32 s8, s0
	s_add_i32 s12, s68, s8
	s_and_b64 s[8:9], s[10:11], exec
	s_cselect_b32 s8, s0, s12
	s_waitcnt lgkmcnt(0)
	s_barrier
	s_lshl_b32 s8, s8, 6
	s_add_i32 s8, s8, s69
	s_and_b64 vcc, exec, s[54:55]
	s_cbranch_vccz .LBB0_445
	v_or_b32_e32 v2, s8, v170
	v_ashrrev_i32_e32 v3, 31, v2
	v_lshlrev_b64 v[4:5], 11, v[2:3]
	s_lshl_b64 s[12:13], s[38:39], 1
	v_or_b32_e32 v5, s13, v5
	v_or_b32_e32 v4, s12, v4
	v_lshl_add_u64 v[12:13], s[30:31], 0, v[4:5]
	v_lshl_add_u64 v[84:85], s[42:43], 0, v[4:5]
	v_mov_b64_e32 v[4:5], s[74:75]
	v_mad_i64_i32 v[2:3], s[12:13], v2, s85, v[4:5]
	s_lshl_b32 s46, s83, 1
	v_lshl_add_u64 v[2:3], v[2:3], 0, s[46:47]
	s_lshl_b32 s46, s29, 1
	v_lshl_add_u64 v[86:87], v[2:3], 0, s[46:47]
	global_load_dwordx4 v[104:107], v[12:13], off offset:16
	global_load_dwordx4 v[8:11], v[12:13], off
	global_load_dwordx4 v[100:103], v[84:85], off offset:16
	global_load_dwordx4 v[80:83], v[84:85], off
	global_load_dwordx4 v[88:91], v[12:13], off offset:144
	global_load_dwordx4 v[96:99], v[12:13], off offset:128
	global_load_dwordx4 v[2:5], v[84:85], off offset:144
	global_load_dwordx4 v[92:95], v[84:85], off offset:128
	v_or_b32_e32 v12, s8, v206
	v_ashrrev_i32_e32 v13, 31, v12
	v_lshlrev_b64 v[12:13], 5, v[12:13]
	v_lshl_add_u64 v[84:85], s[56:57], 0, v[12:13]
	v_lshl_add_u64 v[12:13], s[2:3], 0, v[12:13]
	global_load_dword v0, v[84:85], off
	global_load_dword v108, v[12:13], off
	v_add_u32_e32 v12, s1, v209
	v_lshl_add_u64 v[6:7], v[86:87], 0, s[40:41]
	v_add_u32_e32 v109, s18, v209
	s_waitcnt vmcnt(0)
	ds_write2_b64 v12, v[8:9], v[10:11] offset1:1
	v_add_u32_e32 v8, 0x4200, v12
	ds_write2_b64 v8, v[80:81], v[82:83] offset1:1
	v_add_u32_e32 v8, s88, v210
	ds_write_b16 v8, v80 offset:33792
	v_add_u32_e32 v8, s27, v210
	ds_write_b16_d16_hi v8, v80 offset:33792
	ds_write_b16 v8, v81 offset:33936
	ds_write_b16_d16_hi v8, v81 offset:34080
	ds_write_b16 v8, v82 offset:34224
	ds_write_b16_d16_hi v8, v82 offset:34368
	ds_write_b16 v8, v83 offset:34512
	ds_write_b16_d16_hi v8, v83 offset:34656
	v_add_co_u32_e32 v8, vcc, s33, v86
	s_nop 1
	v_addc_co_u32_e32 v9, vcc, 0, v87, vcc
	global_load_dwordx4 v[84:87], v[8:9], off
	global_load_dwordx4 v[80:83], v[6:7], off offset:16
	global_load_dwordx4 v[10:13], v[6:7], off offset:128
	global_load_dwordx4 v[6:9], v[6:7], off offset:144
	ds_write2_b64 v109, v[104:105], v[106:107] offset1:1
	v_add_u32_e32 v104, 0x4200, v109
	ds_write2_b64 v104, v[100:101], v[102:103] offset1:1
	v_add_u32_e32 v104, s19, v210
	v_add_u32_e32 v105, s64, v210
	ds_write_b16 v104, v100 offset:33792
	ds_write_b16_d16_hi v105, v100 offset:33792
	ds_write_b16 v105, v101 offset:33936
	ds_write_b16_d16_hi v105, v101 offset:34080
	ds_write_b16 v105, v102 offset:34224
	ds_write_b16_d16_hi v105, v102 offset:34368
	ds_write_b16 v105, v103 offset:34512
	ds_write_b16_d16_hi v105, v103 offset:34656
	v_add_u32_e32 v100, s90, v209
	ds_write2_b64 v100, v[96:97], v[98:99] offset1:1
	v_add_u32_e32 v96, 0x4200, v100
	ds_write2_b64 v96, v[92:93], v[94:95] offset1:1
	ds_write_b16 v104, v92 offset:41856
	v_add_u32_e32 v96, s91, v210
	ds_write_b16_d16_hi v96, v92 offset:33792
	ds_write_b16 v96, v93 offset:33936
	ds_write_b16_d16_hi v96, v93 offset:34080
	ds_write_b16 v96, v94 offset:34224
	ds_write_b16_d16_hi v96, v94 offset:34368
	ds_write_b16 v96, v95 offset:34512
	ds_write_b16_d16_hi v96, v95 offset:34656
	v_add_u32_e32 v92, s67, v209
	ds_write2_b64 v92, v[88:89], v[90:91] offset1:1
	v_add_u32_e32 v88, 0x4200, v92
	ds_write2_b64 v88, v[2:3], v[4:5] offset1:1
	ds_write_b16 v104, v2 offset:43008
	v_add_u32_e32 v88, s24, v210
	ds_write_b16_d16_hi v88, v2 offset:33792
	ds_write_b16 v88, v3 offset:33936
	ds_write_b16_d16_hi v88, v3 offset:34080
	ds_write_b16 v88, v4 offset:34224
	ds_write_b16_d16_hi v88, v4 offset:34368
	ds_write_b16 v88, v5 offset:34512
	ds_write_b16_d16_hi v88, v5 offset:34656
	v_add_f32_dpp v2, v108, v108 row_shr:1 row_mask:0xf bank_mask:0xf bound_ctrl:1
	v_mov_b32_e32 v3, v1
	v_mov_b32_e32 v4, 0xff61b1e6
	v_add_f32_dpp v2, v2, v2 row_shr:2 row_mask:0xf bank_mask:0xf bound_ctrl:1
	s_nop 1
	v_add_f32_dpp v2, v2, v2 row_shr:4 row_mask:0xf bank_mask:0xf bound_ctrl:1
	s_nop 1
	v_add_f32_dpp v2, v2, v2 row_shr:8 row_mask:0xf bank_mask:0xf bound_ctrl:1
	s_nop 1
	v_mov_b32_dpp v3, v2 row_bcast:15 row_mask:0xa bank_mask:0xf
	v_add_f32_e32 v2, v2, v3
	v_mov_b32_e32 v3, v1
	s_nop 1
	v_mov_b32_dpp v3, v2 row_bcast:31 row_mask:0xc bank_mask:0xf
	v_add_f32_e32 v2, v2, v3
	v_sub_f32_e32 v0, v0, v2
	v_mov_b32_e32 v3, 0xff61b1e6
	s_nop 1
	v_mov_b32_dpp v3, v0 row_shr:1 row_mask:0xf bank_mask:0xf
	v_max_f32_e32 v3, v0, v3
	s_nop 1
	v_mov_b32_dpp v4, v3 row_shr:2 row_mask:0xf bank_mask:0xf
	v_max_f32_e32 v3, v3, v4
	v_mov_b32_e32 v4, 0xff61b1e6
	s_nop 1
	v_mov_b32_dpp v4, v3 row_shr:4 row_mask:0xf bank_mask:0xf
	v_max_f32_e32 v3, v3, v4
	v_mov_b32_e32 v4, 0xff61b1e6
	s_nop 1
	v_mov_b32_dpp v4, v3 row_shr:8 row_mask:0xf bank_mask:0xf
	v_max_f32_e32 v3, v3, v4
	v_mov_b32_e32 v4, 0xff61b1e6
	s_nop 1
	v_mov_b32_dpp v4, v3 row_bcast:15 row_mask:0xa bank_mask:0xf
	v_max_f32_e32 v3, v3, v4
	v_mov_b32_e32 v4, 0xff61b1e6
	s_nop 1
	v_mov_b32_dpp v4, v3 row_bcast:31 row_mask:0xc bank_mask:0xf
	v_max3_f32 v3, v217, v3, v4
	s_nop 0
	v_readlane_b32 s9, v3, 63
	s_nop 1
	v_subrev_f32_e32 v4, s9, v0
	v_mul_f32_e32 v4, 0x3fb8aa3b, v4
	v_exp_f32_e32 v4, v4
	ds_write2st64_b32 v211, v0, v3 offset1:1
	ds_write2st64_b32 v211, v2, v4 offset0:2 offset1:3
	v_add_u32_e32 v0, s17, v210
	s_waitcnt vmcnt(3)
	ds_write_b16 v0, v84 offset:52224
	v_add_u32_e32 v0, s78, v210
	ds_write_b16_d16_hi v0, v84 offset:52224
	ds_write_b16 v0, v85 offset:52360
	ds_write_b16_d16_hi v0, v85 offset:52496
	ds_write_b16 v0, v86 offset:52632
	ds_write_b16_d16_hi v0, v86 offset:52768
	ds_write_b16 v0, v87 offset:52904
	ds_write_b16_d16_hi v0, v87 offset:53040
	v_add_u32_e32 v0, s79, v210
	v_add_u32_e32 v2, s65, v210
	s_waitcnt vmcnt(2)
	ds_write_b16 v0, v80 offset:52224
	ds_write_b16_d16_hi v2, v80 offset:52224
	ds_write_b16 v2, v81 offset:52360
	ds_write_b16_d16_hi v2, v81 offset:52496
	ds_write_b16 v2, v82 offset:52632
	ds_write_b16_d16_hi v2, v82 offset:52768
	ds_write_b16 v2, v83 offset:52904
	ds_write_b16_d16_hi v2, v83 offset:53040
	s_waitcnt vmcnt(1)
	ds_write_b16 v0, v10 offset:59840
	v_add_u32_e32 v2, s66, v210
	ds_write_b16_d16_hi v2, v10 offset:52224
	ds_write_b16 v2, v11 offset:52360
	ds_write_b16_d16_hi v2, v11 offset:52496
	ds_write_b16 v2, v12 offset:52632
	ds_write_b16_d16_hi v2, v12 offset:52768
	ds_write_b16 v2, v13 offset:52904
	ds_write_b16_d16_hi v2, v13 offset:53040
	s_waitcnt vmcnt(0)
	ds_write_b16 v0, v6 offset:60928
	v_add_u32_e32 v0, s25, v210
	ds_write_b16_d16_hi v0, v6 offset:52224
	ds_write_b16 v0, v7 offset:52360
	ds_write_b16_d16_hi v0, v7 offset:52496
	ds_write_b16 v0, v8 offset:52632
	ds_write_b16_d16_hi v0, v8 offset:52768
	ds_write_b16 v0, v9 offset:52904
	ds_write_b16_d16_hi v0, v9 offset:53040
	s_waitcnt lgkmcnt(0)
	s_barrier
	s_mov_b64 s[12:13], -1
	s_cbranch_execz .LBB0_446
	s_mov_b32 s46, s28
	s_and_b64 vcc, exec, s[12:13]
	s_cbranch_vccz .LBB0_455

.LBB0_446:
	s_sub_i32 s14, s26, s0
	s_add_i32 s9, s0, 1
	s_and_b64 s[12:13], s[10:11], exec
	s_cselect_b32 s12, s9, s14
	s_lshl_b32 s20, s12, 6
	s_add_i32 s20, s20, s69
	s_cmp_lt_u32 s9, s68
	s_cselect_b64 s[12:13], -1, 0
	v_cndmask_b32_e64 v0, 0, 1, s[12:13]
	s_mov_b64 s[14:15], -1
	s_andn2_b64 vcc, exec, s[36:37]
	v_cmp_ne_u32_e64 s[12:13], 1, v0
	s_cbranch_vccnz .LBB0_450
	s_and_b64 vcc, exec, s[12:13]
	s_cbranch_vccnz .LBB0_449
	s_bitcmp1_b32 s9, 0
	v_or_b32_e32 v2, s20, v170
	s_cselect_b32 s14, 0x11000, 0
	v_ashrrev_i32_e32 v3, 31, v2
	s_add_i32 s21, s14, 0
	v_lshlrev_b64 v[4:5], 11, v[2:3]
	s_lshl_b64 s[14:15], s[38:39], 1
	v_or_b32_e32 v5, s15, v5
	v_or_b32_e32 v4, s14, v4
	v_lshl_add_u64 v[10:11], s[30:31], 0, v[4:5]
	v_lshl_add_u64 v[12:13], s[42:43], 0, v[4:5]
	v_mov_b64_e32 v[4:5], s[74:75]
	v_mad_i64_i32 v[2:3], s[14:15], v2, s85, v[4:5]
	s_lshl_b32 s46, s83, 1
	v_lshl_add_u64 v[2:3], v[2:3], 0, s[46:47]
	s_lshl_b32 s46, s29, 1
	v_lshl_add_u64 v[94:95], v[2:3], 0, s[46:47]
	global_load_dwordx4 v[96:99], v[10:11], off offset:16
	global_load_dwordx4 v[84:87], v[10:11], off
	global_load_dwordx4 v[88:91], v[12:13], off offset:16
	global_load_dwordx4 v[102:105], v[12:13], off
	global_load_dwordx4 v[6:9], v[10:11], off offset:144
	global_load_dwordx4 v[80:83], v[10:11], off offset:128
	global_load_dwordx4 v[2:5], v[12:13], off offset:144
	global_load_dwordx4 v[10:13], v[12:13], off offset:128
	v_add_u32_e32 v100, s21, v175
	v_add_u32_e32 v0, s1, v100
	v_lshl_add_u64 v[92:93], v[94:95], 0, s[40:41]
	s_waitcnt vmcnt(0)
	ds_write2_b64 v0, v[84:85], v[86:87] offset1:1
	v_add_u32_e32 v0, 0x4200, v0
	ds_write2_b64 v0, v[102:103], v[104:105] offset1:1
	v_add_u32_e32 v0, s21, v188
	v_add_u32_e32 v84, s88, v0
	ds_write_b16 v84, v102 offset:33792
	v_add_u32_e32 v84, s27, v0
	ds_write_b16_d16_hi v84, v102 offset:33792
	ds_write_b16 v84, v103 offset:33936
	ds_write_b16_d16_hi v84, v103 offset:34080
	ds_write_b16 v84, v104 offset:34224
	ds_write_b16_d16_hi v84, v104 offset:34368
	ds_write_b16 v84, v105 offset:34512
	ds_write_b16_d16_hi v84, v105 offset:34656
	v_add_co_u32_e32 v84, vcc, s33, v94
	v_add_u32_e32 v101, s17, v0
	s_nop 0
	v_addc_co_u32_e32 v85, vcc, 0, v95, vcc
	global_load_dwordx4 v[84:87], v[84:85], off
	v_add_u32_e32 v94, s78, v0
	s_waitcnt vmcnt(0)
	ds_write_b16 v101, v84 offset:52224
	ds_write_b16_d16_hi v94, v84 offset:52224
	ds_write_b16 v94, v85 offset:52360
	ds_write_b16_d16_hi v94, v85 offset:52496
	ds_write_b16 v94, v86 offset:52632
	ds_write_b16_d16_hi v94, v86 offset:52768
	ds_write_b16 v94, v87 offset:52904
	ds_write_b16_d16_hi v94, v87 offset:53040
	global_load_dwordx4 v[102:105], v[92:93], off offset:16
	global_load_dwordx4 v[84:87], v[92:93], off offset:128
	global_load_dwordx4 v[92:95], v[92:93], off offset:144
	v_add_u32_e32 v101, s18, v100
	ds_write2_b64 v101, v[96:97], v[98:99] offset1:1
	v_add_u32_e32 v96, 0x4200, v101
	ds_write2_b64 v96, v[88:89], v[90:91] offset1:1
	v_add_u32_e32 v96, s19, v0
	v_add_u32_e32 v97, s64, v0
	ds_write_b16 v96, v88 offset:33792
	ds_write_b16_d16_hi v97, v88 offset:33792
	ds_write_b16 v97, v89 offset:33936
	ds_write_b16_d16_hi v97, v89 offset:34080
	ds_write_b16 v97, v90 offset:34224
	ds_write_b16_d16_hi v97, v90 offset:34368
	ds_write_b16 v97, v91 offset:34512
	ds_write_b16_d16_hi v97, v91 offset:34656
	v_add_u32_e32 v88, s79, v0
	v_add_u32_e32 v89, s65, v0
	s_waitcnt vmcnt(2)
	ds_write_b16 v88, v102 offset:52224
	ds_write_b16_d16_hi v89, v102 offset:52224
	ds_write_b16 v89, v103 offset:52360
	ds_write_b16_d16_hi v89, v103 offset:52496
	ds_write_b16 v89, v104 offset:52632
	ds_write_b16_d16_hi v89, v104 offset:52768
	ds_write_b16 v89, v105 offset:52904
	ds_write_b16_d16_hi v89, v105 offset:53040
	v_add_u32_e32 v89, s90, v100
	ds_write2_b64 v89, v[80:81], v[82:83] offset1:1
	v_add_u32_e32 v80, 0x4200, v89
	ds_write2_b64 v80, v[10:11], v[12:13] offset1:1
	ds_write_b16 v96, v10 offset:41856
	v_add_u32_e32 v80, s91, v0
	ds_write_b16_d16_hi v80, v10 offset:33792
	ds_write_b16 v80, v11 offset:33936
	ds_write_b16_d16_hi v80, v11 offset:34080
	ds_write_b16 v80, v12 offset:34224
	ds_write_b16_d16_hi v80, v12 offset:34368
	ds_write_b16 v80, v13 offset:34512
	ds_write_b16_d16_hi v80, v13 offset:34656
	s_waitcnt vmcnt(1)
	ds_write_b16 v88, v84 offset:59840
	v_add_u32_e32 v10, s66, v0
	ds_write_b16_d16_hi v10, v84 offset:52224
	ds_write_b16 v10, v85 offset:52360
	ds_write_b16_d16_hi v10, v85 offset:52496
	ds_write_b16 v10, v86 offset:52632
	ds_write_b16_d16_hi v10, v86 offset:52768
	ds_write_b16 v10, v87 offset:52904
	ds_write_b16_d16_hi v10, v87 offset:53040
	v_add_u32_e32 v10, s67, v100
	ds_write2_b64 v10, v[6:7], v[8:9] offset1:1
	v_add_u32_e32 v6, 0x4200, v10
	ds_write2_b64 v6, v[2:3], v[4:5] offset1:1
	ds_write_b16 v96, v2 offset:43008
	v_add_u32_e32 v6, s24, v0
	v_add_u32_e32 v0, s25, v0
	ds_write_b16_d16_hi v6, v2 offset:33792
	ds_write_b16 v6, v3 offset:33936
	ds_write_b16_d16_hi v6, v3 offset:34080
	ds_write_b16 v6, v4 offset:34224
	ds_write_b16_d16_hi v6, v4 offset:34368
	ds_write_b16 v6, v5 offset:34512
	ds_write_b16_d16_hi v6, v5 offset:34656
	s_waitcnt vmcnt(0)
	ds_write_b16 v88, v92 offset:60928
	ds_write_b16_d16_hi v0, v92 offset:52224
	ds_write_b16 v0, v93 offset:52360
	ds_write_b16_d16_hi v0, v93 offset:52496
	ds_write_b16 v0, v94 offset:52632
	ds_write_b16_d16_hi v0, v94 offset:52768
	ds_write_b16 v0, v95 offset:52904
	ds_write_b16_d16_hi v0, v95 offset:53040

.LBB0_483:
	s_lshl_b32 s33, s30, 10
	s_addk_i32 s33, 0x2000
	s_or_b32 s36, s33, s35
	s_lshl_b32 s34, s30, 8
	s_and_b64 s[30:31], s[12:13], exec
	s_cselect_b32 s31, s36, s34
	s_and_b32 s30, s21, 7
	s_mul_i32 s36, s31, 0xc00
	s_mul_hi_u32 s21, s31, 0xc00
	s_add_u32 s36, s19, s36
	s_addc_u32 s21, s24, s21
	s_mul_i32 s37, s30, 0x180
	s_add_u32 s38, s36, s37
	s_addc_u32 s39, s21, 0
	v_readfirstlane_b32 s21, v168
	s_ashr_i32 s21, s21, 6
	s_lshl_b32 s36, s21, 5
	v_or_b32_e32 v0, s36, v172
	v_mov_b64_e32 v[2:3], s[38:39]
	s_movk_i32 s37, 0xc00
	v_mad_i64_i32 v[2:3], s[38:39], v0, s37, v[2:3]
	v_lshlrev_b32_e32 v0, 1, v174
	v_lshl_add_u64 v[14:15], v[2:3], 0, v[0:1]
	global_load_dwordx4 v[126:129], v[14:15], off
	global_load_dwordx4 v[122:125], v[14:15], off offset:32
	global_load_dwordx4 v[118:121], v[14:15], off offset:64
	global_load_dwordx4 v[114:117], v[14:15], off offset:96
	global_load_dwordx4 v[110:113], v[14:15], off offset:128
	global_load_dwordx4 v[106:109], v[14:15], off offset:160
	global_load_dwordx4 v[102:105], v[14:15], off offset:192
	global_load_dwordx4 v[98:101], v[14:15], off offset:224
	global_load_dwordx4 v[2:5], v[14:15], off offset:256
	global_load_dwordx4 v[6:9], v[14:15], off offset:288
	global_load_dwordx4 v[10:13], v[14:15], off offset:320
	global_load_dwordx4 v[14:17], v[14:15], off offset:352
	s_cmp_lg_u64 s[14:15], 0
	s_cbranch_scc0 .LBB0_493
	v_or_b32_e32 v40, s35, v172
	v_add_u32_e32 v40, s36, v40
	v_ashrrev_i32_e32 v58, 1, v40
	s_movk_i32 s98, 0xffe0
	v_and_or_b32 v60, v58, s98, v171
	v_ashrrev_i32_e32 v61, 31, v60
	v_lshl_add_u64 v[58:59], v[60:61], 3, s[14:15]
	global_load_dwordx2 v[42:43], v[58:59], off
	v_or_b32_e32 v40, s35, v172
	v_add_u32_e32 v40, s36, v40
	v_ashrrev_i32_e32 v58, 1, v40
	s_movk_i32 s98, 0xffe0
	v_and_or_b32 v60, v58, s98, v171
	v_or_b32_e32 v58, 2, v60
	v_ashrrev_i32_e32 v59, 31, v58
	v_lshl_add_u64 v[58:59], v[58:59], 3, s[14:15]
	global_load_dwordx2 v[44:45], v[58:59], off
	v_or_b32_e32 v40, s35, v172
	v_add_u32_e32 v40, s36, v40
	v_ashrrev_i32_e32 v58, 1, v40
	s_movk_i32 s98, 0xffe0
	v_and_or_b32 v60, v58, s98, v171
	v_or_b32_e32 v64, 4, v60
	v_ashrrev_i32_e32 v65, 31, v64
	v_lshl_add_u64 v[64:65], v[64:65], 3, s[14:15]
	global_load_dwordx2 v[46:47], v[64:65], off
	v_or_b32_e32 v40, s35, v172
	v_add_u32_e32 v40, s36, v40
	v_ashrrev_i32_e32 v58, 1, v40
	s_movk_i32 s98, 0xffe0
	v_and_or_b32 v60, v58, s98, v171
	v_or_b32_e32 v66, 6, v60
	v_ashrrev_i32_e32 v67, 31, v66
	v_lshl_add_u64 v[66:67], v[66:67], 3, s[14:15]
	global_load_dwordx2 v[48:49], v[66:67], off
	v_or_b32_e32 v40, s35, v172
	v_add_u32_e32 v40, s36, v40
	v_ashrrev_i32_e32 v58, 1, v40
	s_movk_i32 s98, 0xffe0
	v_and_or_b32 v60, v58, s98, v171
	v_or_b32_e32 v68, 8, v60
	v_ashrrev_i32_e32 v69, 31, v68
	v_lshl_add_u64 v[68:69], v[68:69], 3, s[14:15]
	global_load_dwordx2 v[50:51], v[68:69], off
	v_or_b32_e32 v40, s35, v172
	v_add_u32_e32 v40, s36, v40
	v_ashrrev_i32_e32 v58, 1, v40
	s_movk_i32 s98, 0xffe0
	v_and_or_b32 v60, v58, s98, v171
	v_or_b32_e32 v70, 10, v60
	v_ashrrev_i32_e32 v71, 31, v70
	v_lshl_add_u64 v[70:71], v[70:71], 3, s[14:15]
	global_load_dwordx2 v[52:53], v[70:71], off
	v_or_b32_e32 v40, s35, v172
	v_add_u32_e32 v40, s36, v40
	v_ashrrev_i32_e32 v58, 1, v40
	s_movk_i32 s98, 0xffe0
	v_and_or_b32 v60, v58, s98, v171
	v_or_b32_e32 v72, 12, v60
	v_ashrrev_i32_e32 v73, 31, v72
	v_lshl_add_u64 v[72:73], v[72:73], 3, s[14:15]
	global_load_dwordx2 v[54:55], v[72:73], off
	v_or_b32_e32 v40, s35, v172
	v_add_u32_e32 v40, s36, v40
	v_ashrrev_i32_e32 v58, 1, v40
	s_movk_i32 s98, 0xffe0
	v_and_or_b32 v60, v58, s98, v171
	v_or_b32_e32 v60, 14, v60
	v_ashrrev_i32_e32 v61, 31, v60
	v_lshl_add_u64 v[60:61], v[60:61], 3, s[14:15]
	global_load_dwordx2 v[56:57], v[60:61], off
	v_or_b32_e32 v40, s35, v172
	v_add_u32_e32 v40, s36, v40
	v_lshlrev_b32_e32 v40, 5, v40
	s_movk_i32 s98, 0x7e0
	v_and_or_b32 v40, v40, s98, v171
	v_lshlrev_b32_e32 v40, 3, v40
	global_load_dwordx2 v[58:59], v40, s[14:15]
	v_or_b32_e32 v40, s35, v172
	v_add_u32_e32 v40, s36, v40
	v_lshlrev_b32_e32 v40, 5, v40
	s_movk_i32 s98, 0x7e0
	v_and_or_b32 v40, v40, s98, v171
	v_lshlrev_b32_e32 v40, 3, v40
	global_load_dwordx2 v[60:61], v40, s[14:15] offset:16
	v_or_b32_e32 v40, s35, v172
	v_add_u32_e32 v40, s36, v40
	v_lshlrev_b32_e32 v40, 5, v40
	s_movk_i32 s98, 0x7e0
	v_and_or_b32 v40, v40, s98, v171
	v_lshlrev_b32_e32 v40, 3, v40
	global_load_dwordx2 v[62:63], v40, s[14:15] offset:32
	v_or_b32_e32 v40, s35, v172
	v_add_u32_e32 v40, s36, v40
	v_lshlrev_b32_e32 v40, 5, v40
	s_movk_i32 s98, 0x7e0
	v_and_or_b32 v40, v40, s98, v171
	v_lshlrev_b32_e32 v40, 3, v40
	global_load_dwordx2 v[64:65], v40, s[14:15] offset:48
	v_or_b32_e32 v40, s35, v172
	v_add_u32_e32 v40, s36, v40
	v_lshlrev_b32_e32 v40, 5, v40
	s_movk_i32 s98, 0x7e0
	v_and_or_b32 v40, v40, s98, v171
	v_lshlrev_b32_e32 v40, 3, v40
	global_load_dwordx2 v[66:67], v40, s[14:15] offset:64
	v_or_b32_e32 v40, s35, v172
	v_add_u32_e32 v40, s36, v40
	v_lshlrev_b32_e32 v40, 5, v40
	s_movk_i32 s98, 0x7e0
	v_and_or_b32 v40, v40, s98, v171
	v_lshlrev_b32_e32 v40, 3, v40
	global_load_dwordx2 v[68:69], v40, s[14:15] offset:80
	v_or_b32_e32 v40, s35, v172
	v_add_u32_e32 v40, s36, v40
	v_lshlrev_b32_e32 v40, 5, v40
	s_movk_i32 s98, 0x7e0
	v_and_or_b32 v40, v40, s98, v171
	v_lshlrev_b32_e32 v40, 3, v40
	global_load_dwordx2 v[70:71], v40, s[14:15] offset:96
	v_or_b32_e32 v40, s35, v172
	v_add_u32_e32 v40, s36, v40
	v_lshlrev_b32_e32 v40, 5, v40
	s_movk_i32 s98, 0x7e0
	v_and_or_b32 v40, v40, s98, v171
	v_lshlrev_b32_e32 v40, 3, v40
	global_load_dwordx2 v[72:73], v40, s[14:15] offset:112
	v_or_b32_e32 v0, s35, v172
	v_add_u32_e32 v0, s36, v0
	v_ashrrev_i32_e32 v18, 1, v0
	s_movk_i32 s35, 0xffe0
	v_and_or_b32 v20, v18, s35, v171
	v_ashrrev_i32_e32 v21, 31, v20
	v_lshl_add_u64 v[18:19], v[20:21], 3, s[14:15]
	s_nop 0
	v_or_b32_e32 v18, 2, v20
	v_ashrrev_i32_e32 v19, 31, v18
	v_lshl_add_u64 v[18:19], v[18:19], 3, s[14:15]
	s_nop 0
	s_waitcnt vmcnt(18)
	v_lshlrev_b32_e32 v26, 16, v6
	v_and_b32_e32 v27, 0xffff0000, v6
	v_lshlrev_b32_e32 v24, 16, v2
	v_and_b32_e32 v25, 0xffff0000, v2
	v_lshlrev_b32_e32 v30, 16, v7
	v_and_b32_e32 v31, 0xffff0000, v7
	v_lshlrev_b32_e32 v34, 16, v8
	v_and_b32_e32 v35, 0xffff0000, v8
	v_lshlrev_b32_e32 v0, 5, v0
	s_movk_i32 s35, 0x7e0
	v_and_or_b32 v0, v0, s35, v171
	v_lshlrev_b32_e32 v0, 3, v0
	s_waitcnt vmcnt(16)
	s_waitcnt vmcnt(15)
	v_mov_b32_e32 v28, v43
	s_waitcnt vmcnt(14)
	v_mov_b32_e32 v29, v45
	v_mov_b32_e32 v43, v44
	v_pk_mul_f32 v[44:45], v[42:43], v[26:27]
	v_pk_mul_f32 v[26:27], v[28:29], v[26:27]
	v_pk_fma_f32 v[44:45], v[28:29], v[24:25], v[44:45]
	v_pk_fma_f32 v[42:43], v[42:43], v[24:25], v[26:27] neg_lo:[0,0,1] neg_hi:[0,0,1]
	v_or_b32_e32 v24, 4, v20
	v_or_b32_e32 v26, 6, v20
	v_ashrrev_i32_e32 v25, 31, v24
	v_ashrrev_i32_e32 v27, 31, v26
	v_lshl_add_u64 v[24:25], v[24:25], 3, s[14:15]
	v_lshl_add_u64 v[26:27], v[26:27], 3, s[14:15]
	s_nop 0
	v_lshlrev_b32_e32 v28, 16, v3
	s_nop 0
	v_and_b32_e32 v29, 0xffff0000, v3
	v_cvt_pk_bf16_f32 v130, v44, v45
	v_cvt_pk_bf16_f32 v134, v42, v43
	v_lshlrev_b32_e32 v42, 16, v10
	v_and_b32_e32 v43, 0xffff0000, v10
	s_waitcnt vmcnt(13)
	v_mov_b32_e32 v32, v47
	s_waitcnt vmcnt(12)
	v_mov_b32_e32 v33, v49
	v_mov_b32_e32 v47, v48
	v_pk_mul_f32 v[48:49], v[46:47], v[30:31]
	v_pk_mul_f32 v[30:31], v[32:33], v[30:31]
	v_pk_fma_f32 v[48:49], v[32:33], v[28:29], v[48:49]
	v_pk_fma_f32 v[46:47], v[46:47], v[28:29], v[30:31] neg_lo:[0,0,1] neg_hi:[0,0,1]
	v_or_b32_e32 v28, 8, v20
	v_or_b32_e32 v30, 10, v20
	v_ashrrev_i32_e32 v29, 31, v28
	v_ashrrev_i32_e32 v31, 31, v30
	v_lshl_add_u64 v[28:29], v[28:29], 3, s[14:15]
	v_lshl_add_u64 v[30:31], v[30:31], 3, s[14:15]
	s_nop 0
	v_lshlrev_b32_e32 v32, 16, v4
	s_nop 0
	v_and_b32_e32 v33, 0xffff0000, v4
	v_cvt_pk_bf16_f32 v135, v46, v47
	v_cvt_pk_bf16_f32 v131, v48, v49
	v_lshlrev_b32_e32 v46, 16, v14
	v_and_b32_e32 v47, 0xffff0000, v14
	s_waitcnt vmcnt(11)
	v_mov_b32_e32 v36, v51
	s_waitcnt vmcnt(10)
	v_mov_b32_e32 v37, v53
	v_mov_b32_e32 v51, v52
	v_pk_mul_f32 v[52:53], v[50:51], v[34:35]
	v_pk_mul_f32 v[34:35], v[36:37], v[34:35]
	v_pk_fma_f32 v[52:53], v[36:37], v[32:33], v[52:53]
	v_pk_fma_f32 v[50:51], v[50:51], v[32:33], v[34:35] neg_lo:[0,0,1] neg_hi:[0,0,1]
	v_or_b32_e32 v32, 12, v20
	v_or_b32_e32 v20, 14, v20
	v_ashrrev_i32_e32 v33, 31, v32
	v_ashrrev_i32_e32 v21, 31, v20
	v_lshl_add_u64 v[32:33], v[32:33], 3, s[14:15]
	v_lshl_add_u64 v[20:21], v[20:21], 3, s[14:15]
	s_nop 0
	v_lshlrev_b32_e32 v36, 16, v9
	s_nop 0
	v_and_b32_e32 v37, 0xffff0000, v9
	v_lshlrev_b32_e32 v34, 16, v5
	v_and_b32_e32 v35, 0xffff0000, v5
	v_cvt_pk_bf16_f32 v136, v50, v51
	v_cvt_pk_bf16_f32 v132, v52, v53
	v_lshlrev_b32_e32 v50, 16, v15
	v_and_b32_e32 v51, 0xffff0000, v15
	s_waitcnt vmcnt(9)
	v_mov_b32_e32 v38, v55
	s_waitcnt vmcnt(8)
	v_mov_b32_e32 v55, v56
	v_mov_b32_e32 v39, v57
	v_pk_mul_f32 v[56:57], v[54:55], v[36:37]
	v_pk_mul_f32 v[36:37], v[38:39], v[36:37]
	v_pk_fma_f32 v[56:57], v[38:39], v[34:35], v[56:57]
	v_pk_fma_f32 v[54:55], v[54:55], v[34:35], v[36:37] neg_lo:[0,0,1] neg_hi:[0,0,1]
	v_cvt_pk_bf16_f32 v133, v56, v57
	s_nop 0
	s_nop 0
	v_cvt_pk_bf16_f32 v137, v54, v55
	v_lshlrev_b32_e32 v54, 16, v16
	v_and_b32_e32 v55, 0xffff0000, v16
	v_lshlrev_b32_e32 v36, 16, v17
	v_and_b32_e32 v37, 0xffff0000, v17
	s_waitcnt vmcnt(7)
	v_mov_b32_e32 v48, v59
	s_waitcnt vmcnt(6)
	v_mov_b32_e32 v49, v61
	v_mov_b32_e32 v59, v60
	v_pk_mul_f32 v[60:61], v[58:59], v[46:47]
	v_pk_mul_f32 v[46:47], v[48:49], v[46:47]
	v_pk_fma_f32 v[60:61], v[48:49], v[42:43], v[60:61]
	v_pk_fma_f32 v[58:59], v[58:59], v[42:43], v[46:47] neg_lo:[0,0,1] neg_hi:[0,0,1]
	s_nop 0
	s_nop 0
	v_lshlrev_b32_e32 v48, 16, v11
	v_and_b32_e32 v49, 0xffff0000, v11
	v_cvt_pk_bf16_f32 v142, v58, v59
	v_cvt_pk_bf16_f32 v138, v60, v61
	s_waitcnt vmcnt(5)
	v_mov_b32_e32 v52, v63
	s_waitcnt vmcnt(4)
	v_mov_b32_e32 v53, v65
	v_mov_b32_e32 v63, v64
	v_pk_mul_f32 v[64:65], v[62:63], v[50:51]
	v_pk_mul_f32 v[50:51], v[52:53], v[50:51]
	v_pk_fma_f32 v[64:65], v[52:53], v[48:49], v[64:65]
	v_pk_fma_f32 v[62:63], v[62:63], v[48:49], v[50:51] neg_lo:[0,0,1] neg_hi:[0,0,1]
	s_nop 0
	s_nop 0
	v_lshlrev_b32_e32 v52, 16, v12
	v_and_b32_e32 v53, 0xffff0000, v12
	v_cvt_pk_bf16_f32 v143, v62, v63
	v_cvt_pk_bf16_f32 v139, v64, v65
	s_waitcnt vmcnt(3)
	v_mov_b32_e32 v34, v67
	s_waitcnt vmcnt(2)
	v_mov_b32_e32 v35, v69
	v_mov_b32_e32 v67, v68
	v_pk_mul_f32 v[68:69], v[66:67], v[54:55]
	v_pk_mul_f32 v[54:55], v[34:35], v[54:55]
	v_pk_fma_f32 v[68:69], v[34:35], v[52:53], v[68:69]
	v_pk_fma_f32 v[66:67], v[66:67], v[52:53], v[54:55] neg_lo:[0,0,1] neg_hi:[0,0,1]
	s_nop 0
	s_nop 0
	v_lshlrev_b32_e32 v34, 16, v13
	v_and_b32_e32 v35, 0xffff0000, v13
	v_cvt_pk_bf16_f32 v144, v66, v67
	v_cvt_pk_bf16_f32 v140, v68, v69
	s_waitcnt vmcnt(1)
	v_mov_b32_e32 v38, v71
	s_waitcnt vmcnt(0)
	v_mov_b32_e32 v39, v73
	v_mov_b32_e32 v71, v72
	v_pk_mul_f32 v[72:73], v[70:71], v[36:37]
	v_pk_mul_f32 v[36:37], v[38:39], v[36:37]
	v_pk_fma_f32 v[72:73], v[38:39], v[34:35], v[72:73]
	v_pk_fma_f32 v[70:71], v[70:71], v[34:35], v[36:37] neg_lo:[0,0,1] neg_hi:[0,0,1]
	v_cvt_pk_bf16_f32 v141, v72, v73
	v_cvt_pk_bf16_f32 v145, v70, v71
	s_cbranch_execnz .LBB0_486

.LBB0_523:
	s_load_dwordx2 s[60:61], s[60:61], 0x0
	s_waitcnt lgkmcnt(0)
	s_add_u32 vcc_lo, s60, s96
	s_addc_u32 vcc_hi, s61, s97
	s_add_i32 s7, s46, 63
	s_lshr_b32 s7, s7, 6
	v_cvt_f32_u32_e32 v2, s7
	s_sub_i32 s96, 0, s7
	s_abs_i32 s61, s82
	s_ashr_i32 s60, s82, 31
	v_rcp_iflag_f32_e32 v2, v2
	s_nop 0
	v_mul_f32_e32 v2, 0x4f7ffffe, v2
	v_cvt_u32_f32_e32 v2, v2
	s_nop 0
	v_readfirstlane_b32 s97, v2
	s_mul_i32 s96, s96, s97
	s_mul_hi_u32 s96, s97, s96
	s_add_i32 s97, s97, s96
	s_mul_hi_u32 s96, s61, s97
	s_mul_i32 s97, s96, s7
	s_sub_i32 s61, s61, s97
	s_add_i32 s17, s96, 1
	s_sub_i32 s97, s61, s7
	s_cmp_ge_u32 s61, s7
	s_cselect_b32 s17, s17, s96
	s_cselect_b32 s61, s97, s61
	s_add_i32 s96, s17, 1
	s_cmp_ge_u32 s61, s7
	s_cselect_b32 s17, s96, s17
	s_xor_b32 s17, s17, s60
	s_sub_i32 s17, s17, s60
	s_lshl_b32 s96, s17, 6
	s_ashr_i32 s97, s96, 31
	s_mul_i32 s7, s17, s7
	s_mul_hi_u32 s17, s96, s46
	s_mul_i32 s61, s97, s46
	s_sub_i32 s7, s82, s7
	s_mul_i32 s60, s96, s46
	s_add_i32 s61, s17, s61
	s_lshl_b32 s7, s7, 6
	s_lshl_b64 s[60:61], s[60:61], 2
	v_or_b32_e32 v2, s7, v170
	s_add_u32 s60, vcc_lo, s60
	s_addc_u32 s61, vcc_hi, s61
	v_cmp_gt_i32_e32 vcc, s46, v2
	s_or_b64 s[74:75], s[10:11], s[74:75]
	s_nop 0
	v_cndmask_b32_e32 v2, 0, v2, vcc
	v_ashrrev_i32_e32 v3, 31, v2
	v_lshl_add_u64 v[2:3], v[2:3], 2, s[60:61]
	s_lshl_b32 s60, s46, 1
	s_mov_b32 s61, s47
	v_lshl_add_u64 v[10:11], s[60:61], 2, v[2:3]
	s_mul_i32 s60, s46, 3
	v_lshl_add_u64 v[12:13], s[60:61], 2, v[2:3]
	s_lshl_b32 s60, s46, 2
	v_lshl_add_u64 v[24:25], s[60:61], 2, v[2:3]
	s_mul_i32 s60, s46, 5
	v_lshl_add_u64 v[26:27], s[60:61], 2, v[2:3]
	s_mul_i32 s60, s46, 6
	v_lshl_add_u64 v[28:29], s[60:61], 2, v[2:3]
	s_mul_i32 s60, s46, 7
	v_lshl_add_u64 v[4:5], s[46:47], 2, v[2:3]
	v_lshl_add_u64 v[30:31], s[60:61], 2, v[2:3]
	s_lshl_b32 s60, s46, 3
	global_load_dword v34, v[2:3], off nt
	global_load_dword v35, v[4:5], off nt
	global_load_dword v36, v[10:11], off nt
	global_load_dword v37, v[12:13], off nt
	global_load_dword v38, v[24:25], off nt
	global_load_dword v39, v[26:27], off nt
	global_load_dword v40, v[28:29], off nt
	global_load_dword v41, v[30:31], off nt
	v_lshl_add_u64 v[4:5], s[60:61], 2, v[2:3]
	s_mul_i32 s60, s46, 9
	v_lshl_add_u64 v[10:11], s[60:61], 2, v[2:3]
	s_mul_i32 s60, s46, 10
	v_lshl_add_u64 v[12:13], s[60:61], 2, v[2:3]
	s_mul_i32 s60, s46, 11
	v_lshl_add_u64 v[24:25], s[60:61], 2, v[2:3]
	s_mul_i32 s60, s46, 12
	v_lshl_add_u64 v[26:27], s[60:61], 2, v[2:3]
	s_mul_i32 s60, s46, 13
	v_lshl_add_u64 v[28:29], s[60:61], 2, v[2:3]
	s_mul_i32 s60, s46, 14
	v_lshl_add_u64 v[30:31], s[60:61], 2, v[2:3]
	s_mul_i32 s60, s46, 15
	v_lshl_add_u64 v[32:33], s[60:61], 2, v[2:3]
	s_lshl_b32 s60, s46, 4
	global_load_dword v42, v[4:5], off nt
	global_load_dword v43, v[10:11], off nt
	global_load_dword v44, v[12:13], off nt
	global_load_dword v45, v[24:25], off nt
	global_load_dword v46, v[26:27], off nt
	global_load_dword v47, v[28:29], off nt
	global_load_dword v48, v[30:31], off nt
	global_load_dword v49, v[32:33], off nt
	v_lshl_add_u64 v[4:5], s[60:61], 2, v[2:3]
	s_mul_i32 s60, s46, 17
	v_lshl_add_u64 v[10:11], s[60:61], 2, v[2:3]
	s_mul_i32 s60, s46, 18
	v_lshl_add_u64 v[12:13], s[60:61], 2, v[2:3]
	s_mul_i32 s60, s46, 19
	v_lshl_add_u64 v[24:25], s[60:61], 2, v[2:3]
	s_mul_i32 s60, s46, 20
	v_lshl_add_u64 v[26:27], s[60:61], 2, v[2:3]
	s_mul_i32 s60, s46, 21
	v_lshl_add_u64 v[28:29], s[60:61], 2, v[2:3]
	s_mul_i32 s60, s46, 22
	v_lshl_add_u64 v[30:31], s[60:61], 2, v[2:3]
	s_mul_i32 s60, s46, 23
	v_lshl_add_u64 v[32:33], s[60:61], 2, v[2:3]
	s_mul_i32 s60, s46, 24
	global_load_dword v50, v[4:5], off nt
	global_load_dword v51, v[10:11], off nt
	global_load_dword v52, v[12:13], off nt
	global_load_dword v53, v[24:25], off nt
	global_load_dword v54, v[26:27], off nt
	global_load_dword v55, v[28:29], off nt
	global_load_dword v56, v[30:31], off nt
	global_load_dword v57, v[32:33], off nt
	v_lshl_add_u64 v[4:5], s[60:61], 2, v[2:3]
	s_mul_i32 s60, s46, 25
	v_lshl_add_u64 v[10:11], s[60:61], 2, v[2:3]
	s_mul_i32 s60, s46, 26
	v_lshl_add_u64 v[12:13], s[60:61], 2, v[2:3]
	s_mul_i32 s60, s46, 27
	v_lshl_add_u64 v[24:25], s[60:61], 2, v[2:3]
	s_mul_i32 s60, s46, 28
	v_lshl_add_u64 v[26:27], s[60:61], 2, v[2:3]
	s_mul_i32 s60, s46, 29
	v_lshl_add_u64 v[28:29], s[60:61], 2, v[2:3]
	s_mul_i32 s60, s46, 30
	v_lshl_add_u64 v[30:31], s[60:61], 2, v[2:3]
	s_mul_i32 s60, s46, 31
	v_lshl_add_u64 v[32:33], s[60:61], 2, v[2:3]
	s_lshl_b32 s60, s46, 5
	global_load_dword v58, v[4:5], off nt
	global_load_dword v59, v[10:11], off nt
	global_load_dword v60, v[12:13], off nt
	global_load_dword v61, v[24:25], off nt
	global_load_dword v62, v[26:27], off nt
	global_load_dword v63, v[28:29], off nt
	global_load_dword v64, v[30:31], off nt
	global_load_dword v65, v[32:33], off nt
	v_lshl_add_u64 v[4:5], s[60:61], 2, v[2:3]
	s_mul_i32 s60, s46, 33
	v_lshl_add_u64 v[10:11], s[60:61], 2, v[2:3]
	s_mul_i32 s60, s46, 34
	v_lshl_add_u64 v[12:13], s[60:61], 2, v[2:3]
	s_mul_i32 s60, s46, 35
	v_lshl_add_u64 v[24:25], s[60:61], 2, v[2:3]
	s_mul_i32 s60, s46, 36
	v_lshl_add_u64 v[26:27], s[60:61], 2, v[2:3]
	s_mul_i32 s60, s46, 37
	v_lshl_add_u64 v[28:29], s[60:61], 2, v[2:3]
	s_mul_i32 s60, s46, 38
	v_lshl_add_u64 v[30:31], s[60:61], 2, v[2:3]
	s_mul_i32 s60, s46, 39
	v_lshl_add_u64 v[32:33], s[60:61], 2, v[2:3]
	s_mul_i32 s60, s46, 40
	global_load_dword v66, v[4:5], off nt
	global_load_dword v67, v[10:11], off nt
	global_load_dword v68, v[12:13], off nt
	global_load_dword v69, v[24:25], off nt
	global_load_dword v70, v[26:27], off nt
	global_load_dword v71, v[28:29], off nt
	global_load_dword v72, v[30:31], off nt
	global_load_dword v73, v[32:33], off nt
	v_lshl_add_u64 v[4:5], s[60:61], 2, v[2:3]
	s_mul_i32 s60, s46, 41
	v_lshl_add_u64 v[10:11], s[60:61], 2, v[2:3]
	s_mul_i32 s60, s46, 42
	v_lshl_add_u64 v[12:13], s[60:61], 2, v[2:3]
	s_mul_i32 s60, s46, 43
	v_lshl_add_u64 v[24:25], s[60:61], 2, v[2:3]
	s_mul_i32 s60, s46, 44
	v_lshl_add_u64 v[26:27], s[60:61], 2, v[2:3]
	s_mul_i32 s60, s46, 45
	v_lshl_add_u64 v[28:29], s[60:61], 2, v[2:3]
	s_mul_i32 s60, s46, 46
	v_lshl_add_u64 v[30:31], s[60:61], 2, v[2:3]
	s_mul_i32 s60, s46, 47
	v_lshl_add_u64 v[32:33], s[60:61], 2, v[2:3]
	s_mul_i32 s60, s46, 48
	global_load_dword v74, v[4:5], off nt
	global_load_dword v75, v[10:11], off nt
	global_load_dword v76, v[12:13], off nt
	global_load_dword v77, v[24:25], off nt
	global_load_dword v78, v[26:27], off nt
	global_load_dword v79, v[28:29], off nt
	global_load_dword v80, v[30:31], off nt
	global_load_dword v81, v[32:33], off nt
	v_lshl_add_u64 v[4:5], s[60:61], 2, v[2:3]
	s_mul_i32 s60, s46, 49
	v_lshl_add_u64 v[10:11], s[60:61], 2, v[2:3]
	s_mul_i32 s60, s46, 50
	v_lshl_add_u64 v[12:13], s[60:61], 2, v[2:3]
	s_mul_i32 s60, s46, 51
	v_lshl_add_u64 v[24:25], s[60:61], 2, v[2:3]
	s_mul_i32 s60, s46, 52
	v_lshl_add_u64 v[26:27], s[60:61], 2, v[2:3]
	s_mul_i32 s60, s46, 53
	v_lshl_add_u64 v[28:29], s[60:61], 2, v[2:3]
	s_mul_i32 s60, s46, 54
	v_lshl_add_u64 v[30:31], s[60:61], 2, v[2:3]
	s_mul_i32 s60, s46, 55
	v_lshl_add_u64 v[32:33], s[60:61], 2, v[2:3]
	s_mul_i32 s60, s46, 56
	global_load_dword v82, v[4:5], off nt
	global_load_dword v83, v[10:11], off nt
	global_load_dword v84, v[12:13], off nt
	global_load_dword v85, v[24:25], off nt
	global_load_dword v86, v[26:27], off nt
	global_load_dword v87, v[28:29], off nt
	global_load_dword v88, v[30:31], off nt
	global_load_dword v32, v[32:33], off nt
	v_lshl_add_u64 v[4:5], s[60:61], 2, v[2:3]
	s_mul_i32 s60, s46, 57
	v_lshl_add_u64 v[10:11], s[60:61], 2, v[2:3]
	s_mul_i32 s60, s46, 58
	v_lshl_add_u64 v[12:13], s[60:61], 2, v[2:3]
	s_mul_i32 s60, s46, 59
	v_lshl_add_u64 v[24:25], s[60:61], 2, v[2:3]
	s_mul_i32 s60, s46, 60
	v_lshl_add_u64 v[26:27], s[60:61], 2, v[2:3]
	s_mul_i32 s60, s46, 61
	v_lshl_add_u64 v[28:29], s[60:61], 2, v[2:3]
	s_mul_i32 s60, s46, 62
	v_lshl_add_u64 v[30:31], s[60:61], 2, v[2:3]
	s_mul_i32 s60, s46, 63
	v_lshl_add_u64 v[2:3], s[60:61], 2, v[2:3]
	global_load_dword v33, v[4:5], off nt
	global_load_dword v10, v[10:11], off nt
	global_load_dword v11, v[12:13], off nt
	global_load_dword v12, v[24:25], off nt
	global_load_dword v13, v[26:27], off nt
	global_load_dword v24, v[28:29], off nt
	global_load_dword v25, v[30:31], off nt
	global_load_dword v26, v[2:3], off nt
	s_waitcnt vmcnt(0)
	v_cvt_pk_bf16_f32 v2, v34, v35
	v_cvt_pk_bf16_f32 v3, v36, v37
	v_cvt_pk_bf16_f32 v4, v38, v39
	v_cvt_pk_bf16_f32 v5, v40, v41
	ds_write_b128 v22, v[2:5]
	v_cvt_pk_bf16_f32 v2, v42, v43
	v_cvt_pk_bf16_f32 v3, v44, v45
	v_cvt_pk_bf16_f32 v4, v46, v47
	v_cvt_pk_bf16_f32 v5, v48, v49
	ds_write_b128 v22, v[2:5] offset:16
	v_cvt_pk_bf16_f32 v2, v50, v51
	v_cvt_pk_bf16_f32 v3, v52, v53
	v_cvt_pk_bf16_f32 v4, v54, v55
	v_cvt_pk_bf16_f32 v5, v56, v57
	ds_write_b128 v22, v[2:5] offset:32
	v_cvt_pk_bf16_f32 v2, v58, v59
	v_cvt_pk_bf16_f32 v3, v60, v61
	v_cvt_pk_bf16_f32 v4, v62, v63
	v_cvt_pk_bf16_f32 v5, v64, v65
	ds_write_b128 v22, v[2:5] offset:48
	s_and_b64 s[60:61], s[10:11], s[88:89]
	s_and_b64 s[74:75], s[74:75], exec
	s_cselect_b32 s17, 0, 2
	v_cvt_pk_bf16_f32 v2, v66, v67
	s_and_b64 s[60:61], s[60:61], exec
	v_cvt_pk_bf16_f32 v3, v68, v69
	s_cselect_b32 s74, 1, s17
	v_cvt_pk_bf16_f32 v4, v70, v71
	s_cmp_gt_i32 s74, 1
	v_cvt_pk_bf16_f32 v5, v72, v73
	ds_write_b128 v22, v[2:5] offset:64
	s_mov_b64 s[60:61], -1
	v_cvt_pk_bf16_f32 v2, v74, v75
	v_cvt_pk_bf16_f32 v3, v76, v77
	v_cvt_pk_bf16_f32 v4, v78, v79
	v_cvt_pk_bf16_f32 v5, v80, v81
	ds_write_b128 v22, v[2:5] offset:80
	v_cvt_pk_bf16_f32 v2, v82, v83
	v_cvt_pk_bf16_f32 v3, v84, v85
	v_cvt_pk_bf16_f32 v4, v86, v87
	v_cvt_pk_bf16_f32 v5, v88, v32
	ds_write_b128 v22, v[2:5] offset:96
	v_cvt_pk_bf16_f32 v2, v33, v10
	v_cvt_pk_bf16_f32 v3, v11, v12
	v_or_b32_e32 v12, s7, v14
	v_cvt_pk_bf16_f32 v4, v13, v24
	v_cvt_pk_bf16_f32 v5, v25, v26
	ds_write_b128 v22, v[2:5] offset:112
	ds_read_b128 v[2:5], v23
	s_cbranch_scc0 .LBB0_525
	v_cmp_gt_i32_e32 vcc, s93, v12
	s_mov_b64 s[60:61], 0
	s_nop 0
	v_cndmask_b32_e32 v10, v237, v238, vcc
	v_cmp_lt_i32_e32 vcc, s48, v12
	s_nop 1
	v_cndmask_b32_e32 v10, 0, v10, vcc
	v_add_u32_e32 v13, v10, v12

.LBB0_616:
	v_lshl_add_u64 v[12:13], s[8:9], 0, v[0:1]
	v_add_co_u32_e32 v26, vcc, 0x49200000, v12
	v_lshl_add_u64 v[14:15], s[6:7], 0, v[0:1]
	s_nop 0
	v_addc_co_u32_e32 v27, vcc, 0, v13, vcc
	v_add_co_u32_e32 v30, vcc, 0x4a600000, v12
	v_lshl_add_u64 v[18:19], s[2:3], 0, v[0:1]
	s_mov_b32 s1, 0x25e00000
	v_addc_co_u32_e32 v31, vcc, 0, v13, vcc
	v_add_co_u32_e64 v28, s[4:5], s1, v18
	v_add_co_u32_e32 v32, vcc, 0x1fa01000, v14
	global_load_dwordx4 v[2:5], v[10:11], off offset:16
	global_load_dwordx4 v[6:9], v[10:11], off
	v_addc_co_u32_e64 v29, s[4:5], 0, v19, s[4:5]
	global_load_dwordx4 v[18:21], v[26:27], off
	global_load_dwordx4 v[22:25], v[30:31], off
	v_addc_co_u32_e32 v33, vcc, 0, v15, vcc
	global_load_dwordx4 v[12:15], v[32:33], off offset:2048
	s_add_i32 s0, s0, s82
	s_add_u32 s2, s2, s56
	s_addc_u32 s3, s3, s57
	s_add_u32 s6, s6, s10
	s_addc_u32 s7, s7, s11
	s_add_u32 s8, s8, s28
	s_addc_u32 s9, s9, s29
	s_cmpk_gt_i32 s0, 0x27ff
	s_waitcnt vmcnt(0)
	v_lshlrev_b32_e32 v34, 16, v21
	v_and_b32_e32 v35, 0xffff0000, v21
	v_lshlrev_b32_e32 v36, 16, v20
	v_and_b32_e32 v37, 0xffff0000, v20
	v_lshlrev_b32_e32 v20, 16, v19
	v_and_b32_e32 v21, 0xffff0000, v19
	v_lshlrev_b32_e32 v38, 16, v18
	v_and_b32_e32 v39, 0xffff0000, v18
	v_lshlrev_b32_e32 v18, 16, v25
	v_and_b32_e32 v19, 0xffff0000, v25
	v_lshlrev_b32_e32 v40, 16, v24
	v_and_b32_e32 v41, 0xffff0000, v24
	v_lshlrev_b32_e32 v24, 16, v23
	v_and_b32_e32 v25, 0xffff0000, v23
	v_lshlrev_b32_e32 v42, 16, v22
	v_and_b32_e32 v43, 0xffff0000, v22
	v_lshlrev_b32_e32 v17, 16, v12
	v_and_b32_e32 v22, 0xffff0000, v12
	v_lshlrev_b32_e32 v23, 16, v13
	v_and_b32_e32 v44, 0xffff0000, v13
	v_lshlrev_b32_e32 v45, 16, v14
	v_pk_add_f32 v[12:13], v[34:35], v[18:19]
	v_pk_add_f32 v[18:19], v[20:21], v[24:25]
	v_pk_add_f32 v[20:21], v[38:39], v[42:43]
	v_and_b32_e32 v46, 0xffff0000, v14
	v_lshlrev_b32_e32 v47, 16, v15
	v_and_b32_e32 v48, 0xffff0000, v15
	v_pk_add_f32 v[14:15], v[36:37], v[40:41]
	v_mul_f32_e32 v17, 0xbfb8aa3b, v17
	v_mul_f32_e32 v41, 0xbfb8aa3b, v45
	v_pk_mul_f32 v[36:37], v[20:21], v[20:21]
	v_pk_mul_f32 v[34:35], v[18:19], v[18:19]
	v_exp_f32_e32 v17, v17
	v_exp_f32_e32 v41, v41
	v_add_f32_e32 v36, v36, v37
	v_add_f32_e32 v34, v34, v36
	v_pk_mul_f32 v[24:25], v[14:15], v[14:15]
	v_add_f32_e32 v34, v35, v34
	v_add_f32_e32 v24, v24, v34
	v_mul_f32_e32 v38, 0xbfb8aa3b, v22
	v_mul_f32_e32 v39, 0xbfb8aa3b, v23
	v_pk_mul_f32 v[22:23], v[12:13], v[12:13]
	v_add_f32_e32 v17, 1.0, v17
	v_add_f32_e32 v37, 1.0, v41
	v_add_f32_e32 v41, v25, v24
	v_rcp_f32_e32 v24, v17
	v_add_f32_e32 v17, v22, v41
	v_add_f32_e32 v17, v23, v17
	v_mul_f32_e32 v40, 0xbfb8aa3b, v44
	v_mul_f32_e32 v42, 0xbfb8aa3b, v46
	v_add_f32_dpp v17, v17, v17 quad_perm:[1,0,3,2] row_mask:0xf bank_mask:0xf bound_ctrl:1
	v_mul_f32_e32 v43, 0xbfb8aa3b, v47
	v_mul_f32_e32 v44, 0xbfb8aa3b, v48
	v_add_f32_dpp v17, v17, v17 quad_perm:[2,3,0,1] row_mask:0xf bank_mask:0xf bound_ctrl:1
	v_exp_f32_e32 v38, v38
	v_exp_f32_e32 v39, v39
	v_exp_f32_e32 v40, v40
	v_exp_f32_e32 v42, v42
	v_exp_f32_e32 v43, v43
	v_exp_f32_e32 v44, v44
	v_add_f32_dpp v17, v17, v17 row_half_mirror row_mask:0xf bank_mask:0xf bound_ctrl:1
	v_add_f32_e32 v34, 1.0, v38
	v_add_f32_e32 v35, 1.0, v39
	v_add_f32_dpp v17, v17, v17 row_mirror row_mask:0xf bank_mask:0xf bound_ctrl:1
	v_fmamk_f32 v17, v17, 0x3c000000, v233
	v_rsq_f32_e32 v22, v17
	v_add_f32_e32 v36, 1.0, v40
	v_add_f32_e32 v38, 1.0, v42
	v_add_f32_e32 v39, 1.0, v43
	v_add_f32_e32 v40, 1.0, v44
	v_rcp_f32_e32 v25, v34
	v_rcp_f32_e32 v34, v35
	v_rcp_f32_e32 v35, v36
	v_rcp_f32_e32 v36, v37
	v_rcp_f32_e32 v37, v38
	v_rcp_f32_e32 v38, v39
	v_rcp_f32_e32 v39, v40
	v_pk_mul_f32 v[20:21], v[20:21], v[22:23] op_sel_hi:[1,0]
	v_pk_mul_f32 v[18:19], v[18:19], v[22:23] op_sel_hi:[1,0]
	v_pk_mul_f32 v[14:15], v[14:15], v[22:23] op_sel_hi:[1,0]
	v_pk_mul_f32 v[12:13], v[12:13], v[22:23] op_sel_hi:[1,0]
	v_pk_mul_f32 v[6:7], v[6:7], v[20:21]
	v_pk_mul_f32 v[8:9], v[8:9], v[18:19]
	v_pk_mul_f32 v[2:3], v[2:3], v[14:15]
	v_pk_mul_f32 v[4:5], v[4:5], v[12:13]
	v_pk_mul_f32 v[6:7], v[24:25], v[6:7]
	v_pk_mul_f32 v[8:9], v[34:35], v[8:9]
	v_pk_mul_f32 v[12:13], v[36:37], v[2:3]
	v_pk_mul_f32 v[14:15], v[38:39], v[4:5]
	v_cvt_pk_bf16_f32 v2, v6, v7
	v_cvt_pk_bf16_f32 v3, v8, v9
	v_cvt_pk_bf16_f32 v4, v12, v13
	v_cvt_pk_bf16_f32 v5, v14, v15
	global_store_dwordx4 v[28:29], v[2:5], off
	global_load_dwordx4 v[2:5], v[26:27], off offset:1024
	global_load_dwordx4 v[6:9], v[30:31], off offset:1024
	global_load_dwordx4 v[12:15], v[32:33], off offset:3072
	global_load_dwordx4 v[18:21], v[10:11], off offset:16
	global_load_dwordx4 v[22:25], v[10:11], off
	s_waitcnt vmcnt(4)
	v_lshlrev_b32_e32 v26, 16, v4
	v_and_b32_e32 v27, 0xffff0000, v4
	s_waitcnt vmcnt(2)
	v_lshlrev_b32_e32 v17, 16, v12
	v_and_b32_e32 v34, 0xffff0000, v12
	v_lshlrev_b32_e32 v35, 16, v13
	v_and_b32_e32 v36, 0xffff0000, v13
	v_lshlrev_b32_e32 v37, 16, v14
	v_and_b32_e32 v38, 0xffff0000, v14
	v_lshlrev_b32_e32 v39, 16, v15
	v_and_b32_e32 v40, 0xffff0000, v15
	v_lshlrev_b32_e32 v12, 16, v5
	v_and_b32_e32 v13, 0xffff0000, v5
	v_lshlrev_b32_e32 v14, 16, v9
	v_and_b32_e32 v15, 0xffff0000, v9
	v_lshlrev_b32_e32 v4, 16, v8
	v_and_b32_e32 v5, 0xffff0000, v8
	v_lshlrev_b32_e32 v8, 16, v3
	v_and_b32_e32 v9, 0xffff0000, v3
	v_lshlrev_b32_e32 v32, 16, v2
	v_and_b32_e32 v33, 0xffff0000, v2
	v_lshlrev_b32_e32 v2, 16, v6
	v_and_b32_e32 v3, 0xffff0000, v6
	v_lshlrev_b32_e32 v30, 16, v7
	v_and_b32_e32 v31, 0xffff0000, v7
	v_pk_add_f32 v[2:3], v[32:33], v[2:3]
	v_pk_add_f32 v[8:9], v[8:9], v[30:31]
	v_pk_mul_f32 v[30:31], v[2:3], v[2:3]
	v_pk_add_f32 v[4:5], v[26:27], v[4:5]
	v_pk_mul_f32 v[26:27], v[8:9], v[8:9]
	v_add_f32_e32 v30, v30, v31
	v_add_f32_e32 v26, v26, v30
	v_pk_add_f32 v[6:7], v[12:13], v[14:15]
	v_pk_mul_f32 v[14:15], v[4:5], v[4:5]
	v_add_f32_e32 v26, v27, v26
	v_add_f32_e32 v14, v14, v26
	v_pk_mul_f32 v[12:13], v[6:7], v[6:7]
	v_add_f32_e32 v14, v15, v14
	v_add_f32_e32 v12, v12, v14
	v_add_f32_e32 v12, v13, v12
	v_mul_f32_e32 v17, 0xbfb8aa3b, v17
	v_mul_f32_e32 v34, 0xbfb8aa3b, v34
	v_add_f32_dpp v12, v12, v12 quad_perm:[1,0,3,2] row_mask:0xf bank_mask:0xf bound_ctrl:1
	v_mul_f32_e32 v35, 0xbfb8aa3b, v35
	v_mul_f32_e32 v36, 0xbfb8aa3b, v36
	v_mul_f32_e32 v37, 0xbfb8aa3b, v37
	v_mul_f32_e32 v38, 0xbfb8aa3b, v38
	v_mul_f32_e32 v39, 0xbfb8aa3b, v39
	v_mul_f32_e32 v40, 0xbfb8aa3b, v40
	v_add_f32_dpp v12, v12, v12 quad_perm:[2,3,0,1] row_mask:0xf bank_mask:0xf bound_ctrl:1
	v_exp_f32_e32 v17, v17
	v_exp_f32_e32 v32, v34
	v_exp_f32_e32 v33, v35
	v_exp_f32_e32 v34, v36
	v_exp_f32_e32 v35, v37
	v_exp_f32_e32 v36, v38
	v_exp_f32_e32 v37, v39
	v_exp_f32_e32 v38, v40
	v_add_f32_dpp v12, v12, v12 row_half_mirror row_mask:0xf bank_mask:0xf bound_ctrl:1
	v_add_f32_e32 v17, 1.0, v17
	v_add_f32_e32 v27, 1.0, v32
	v_add_f32_dpp v12, v12, v12 row_mirror row_mask:0xf bank_mask:0xf bound_ctrl:1
	v_fmamk_f32 v12, v12, 0x3c000000, v233
	v_rsq_f32_e32 v12, v12
	v_add_f32_e32 v30, 1.0, v33
	v_add_f32_e32 v31, 1.0, v34
	v_add_f32_e32 v32, 1.0, v35
	v_add_f32_e32 v33, 1.0, v36
	v_add_f32_e32 v34, 1.0, v37
	v_add_f32_e32 v35, 1.0, v38
	v_rcp_f32_e32 v26, v17
	v_rcp_f32_e32 v27, v27
	v_rcp_f32_e32 v30, v30
	v_rcp_f32_e32 v31, v31
	v_rcp_f32_e32 v32, v32
	v_rcp_f32_e32 v33, v33
	v_rcp_f32_e32 v34, v34
	v_rcp_f32_e32 v35, v35
	v_pk_mul_f32 v[2:3], v[2:3], v[12:13] op_sel_hi:[1,0]
	v_pk_mul_f32 v[8:9], v[8:9], v[12:13] op_sel_hi:[1,0]
	v_pk_mul_f32 v[4:5], v[4:5], v[12:13] op_sel_hi:[1,0]
	v_pk_mul_f32 v[6:7], v[6:7], v[12:13] op_sel_hi:[1,0]
	s_waitcnt vmcnt(0)
	v_pk_mul_f32 v[2:3], v[22:23], v[2:3]
	v_pk_mul_f32 v[8:9], v[24:25], v[8:9]
	v_pk_mul_f32 v[4:5], v[18:19], v[4:5]
	v_pk_mul_f32 v[6:7], v[20:21], v[6:7]
	v_pk_mul_f32 v[2:3], v[26:27], v[2:3]
	v_pk_mul_f32 v[8:9], v[30:31], v[8:9]
	v_pk_mul_f32 v[4:5], v[32:33], v[4:5]
	v_pk_mul_f32 v[6:7], v[34:35], v[6:7]
	v_cvt_pk_bf16_f32 v2, v2, v3
	v_cvt_pk_bf16_f32 v3, v8, v9
	v_cvt_pk_bf16_f32 v4, v4, v5
	v_cvt_pk_bf16_f32 v5, v6, v7
	global_store_dwordx4 v[28:29], v[2:5], off offset:1024
	s_cbranch_scc0 .LBB0_616

.LBB0_653:
	v_add_co_u32_e32 v14, vcc, 0xfffff000, v50
	s_add_i32 s2, s16, 0xffffe000
	s_nop 0
	v_addc_co_u32_e32 v15, vcc, -1, v51, vcc
	global_load_dwordx4 v[18:21], v[14:15], off offset:-2048 nt
	global_load_dwordx4 v[10:13], v[50:51], off offset:-4096 nt
	global_load_dwordx4 v[6:9], v[50:51], off offset:-3072 nt
	global_load_dwordx4 v[2:5], v[50:51], off nt
	global_load_dwordx4 v[14:17], v[14:15], off offset:-1024 nt
	s_ashr_i32 s14, s16, 8
	s_lshr_b32 s15, s2, 10
	s_cmpk_lt_i32 s16, 0x2000
	s_cselect_b64 s[26:27], -1, 0
	s_and_b64 s[2:3], s[26:27], exec
	s_movk_i32 s2, 0x3ff
	s_cselect_b32 s2, 0xff, s2
	s_cselect_b32 s3, s14, s15
	s_and_b32 s29, s2, s16
	s_mul_i32 s2, s3, 0x500
	s_cmpk_gt_i32 s16, 0x1fff
	s_cselect_b64 s[20:21], -1, 0
	s_add_i32 s14, s29, s2
	s_lshl_b32 s3, s3, 1
	v_readlane_b32 s22, v254, 54
	s_addk_i32 s14, 0x100
	v_readlane_b32 s23, v254, 55
	s_add_i32 s2, s3, s22
	s_ashr_i32 s15, s14, 31
	s_lshl_b32 s46, s29, 8
	s_ashr_i32 s3, s2, 31
	s_lshl_b64 s[22:23], s[14:15], 11
	s_add_u32 s24, s17, s22
	s_mov_b64 s[12:13], -1
	v_lshl_add_u64 v[56:57], v[28:29], 0, s[46:47]
	s_addc_u32 s25, s18, s23
	s_and_b64 vcc, exec, s[20:21]
	s_waitcnt vmcnt(0)
	v_lshlrev_b32_e32 v22, 16, v18
	v_and_b32_e32 v23, 0xffff0000, v18
	v_lshlrev_b32_e32 v24, 16, v19
	v_and_b32_e32 v25, 0xffff0000, v19
	v_lshlrev_b32_e32 v18, 16, v20
	v_and_b32_e32 v19, 0xffff0000, v20
	v_lshlrev_b32_e32 v20, 16, v21
	v_and_b32_e32 v21, 0xffff0000, v21
	s_cbranch_vccnz .LBB0_655
	s_lshl_b64 s[12:13], s[2:3], 20
	v_lshl_add_u64 v[52:53], v[56:57], 0, v[30:31]
	v_lshl_add_u64 v[52:53], v[52:53], 0, s[12:13]
	v_lshl_add_u64 v[52:53], v[52:53], 0, v[32:33]
	s_mov_b64 s[12:13], 0
	global_store_dwordx4 v[52:53], v[22:25], off
	global_store_dwordx4 v[52:53], v[18:21], off offset:16

.LBB0_659:
	s_andn2_b64 vcc, exec, s[26:27]
	s_cbranch_vccnz .LBB0_661
	global_load_dwordx2 v[22:23], v[66:67], off
	global_load_dwordx2 v[24:25], v[68:69], off
	global_load_dwordx2 v[56:57], v[62:63], off
	global_load_dwordx2 v[62:63], v[64:65], off
	global_load_dwordx2 v[54:55], v[54:55], off
	global_load_dwordx2 v[60:61], v[60:61], off
	global_load_dwordx2 v[52:53], v[52:53], off
	global_load_dwordx2 v[58:59], v[58:59], off
	v_mov_b32_dpp v64, v18 quad_perm:[2,3,0,1] row_mask:0xf bank_mask:0xf bound_ctrl:1
	v_mov_b32_dpp v65, v19 quad_perm:[2,3,0,1] row_mask:0xf bank_mask:0xf bound_ctrl:1
	v_mov_b32_dpp v66, v20 quad_perm:[2,3,0,1] row_mask:0xf bank_mask:0xf bound_ctrl:1
	v_mov_b32_dpp v67, v21 quad_perm:[2,3,0,1] row_mask:0xf bank_mask:0xf bound_ctrl:1
	v_mov_b32_dpp v68, v14 quad_perm:[2,3,0,1] row_mask:0xf bank_mask:0xf bound_ctrl:1
	v_mov_b32_dpp v69, v15 quad_perm:[2,3,0,1] row_mask:0xf bank_mask:0xf bound_ctrl:1
	v_mov_b32_dpp v72, v16 quad_perm:[2,3,0,1] row_mask:0xf bank_mask:0xf bound_ctrl:1
	v_mov_b32_dpp v73, v17 quad_perm:[2,3,0,1] row_mask:0xf bank_mask:0xf bound_ctrl:1
	v_lshlrev_b32_e32 v0, 1, v26
	s_waitcnt vmcnt(7)
	v_mov_b32_e32 v74, v23
	s_waitcnt vmcnt(6)
	v_mov_b32_e32 v75, v25
	v_mov_b32_e32 v23, v24
	s_waitcnt vmcnt(5)
	v_mov_b32_e32 v24, v57
	s_waitcnt vmcnt(4)
	v_mov_b32_e32 v25, v63
	v_mov_b32_e32 v57, v62
	s_waitcnt vmcnt(3)
	v_mov_b32_e32 v62, v55
	s_waitcnt vmcnt(2)
	v_mov_b32_e32 v63, v61
	v_mov_b32_e32 v55, v60
	s_waitcnt vmcnt(1)
	v_mov_b32_e32 v60, v53
	s_waitcnt vmcnt(0)
	v_mov_b32_e32 v61, v59
	v_mov_b32_e32 v53, v58
	v_pk_mul_f32 v[58:59], v[74:75], v[64:65]
	v_pk_mul_f32 v[24:25], v[24:25], v[66:67]
	v_pk_mul_f32 v[62:63], v[62:63], v[68:69]
	v_pk_mul_f32 v[60:61], v[60:61], v[72:73]
	v_cndmask_b32_e64 v59, v59, -v59, s[10:11]
	v_cndmask_b32_e64 v58, v58, -v58, s[10:11]
	v_cndmask_b32_e64 v25, v25, -v25, s[10:11]
	v_cndmask_b32_e64 v24, v24, -v24, s[10:11]
	v_cndmask_b32_e64 v63, v63, -v63, s[10:11]
	v_cndmask_b32_e64 v62, v62, -v62, s[10:11]
	v_cndmask_b32_e64 v61, v61, -v61, s[10:11]
	v_cndmask_b32_e64 v60, v60, -v60, s[10:11]
	v_pk_fma_f32 v[18:19], v[22:23], v[18:19], v[58:59]
	v_pk_fma_f32 v[20:21], v[56:57], v[20:21], v[24:25]
	v_pk_fma_f32 v[22:23], v[54:55], v[14:15], v[62:63]
	v_pk_fma_f32 v[24:25], v[52:53], v[16:17], v[60:61]
	v_cvt_pk_bf16_f32 v14, v18, v19
	v_cvt_pk_bf16_f32 v15, v20, v21
	v_cvt_pk_bf16_f32 v16, v22, v23
	v_cvt_pk_bf16_f32 v17, v24, v25
	global_store_dwordx4 v0, v[14:17], s[24:25] offset:1024

.LBB0_669:
	global_load_dwordx4 v[10:13], v[40:41], off offset:16
	global_load_dwordx4 v[14:17], v[40:41], off
	v_lshlrev_b32_e32 v6, 16, v2
	v_and_b32_e32 v7, 0xffff0000, v2
	v_pk_mul_f32 v[24:25], v[6:7], v[6:7]
	v_lshlrev_b32_e32 v8, 16, v3
	v_and_b32_e32 v9, 0xffff0000, v3
	v_pk_mul_f32 v[52:53], v[8:9], v[8:9]
	v_add_f32_e32 v0, v24, v25
	v_lshlrev_b32_e32 v18, 16, v4
	v_and_b32_e32 v19, 0xffff0000, v4
	v_add_f32_e32 v0, v52, v0
	v_pk_mul_f32 v[54:55], v[18:19], v[18:19]
	v_add_f32_e32 v0, v53, v0
	v_and_b32_e32 v22, 0xffff0000, v5
	v_lshlrev_b32_e32 v23, 16, v5
	v_add_f32_e32 v0, v54, v0
	v_pk_mul_f32 v[20:21], v[22:23], v[22:23]
	v_add_f32_e32 v0, v55, v0
	v_add_f32_e32 v0, v21, v0
	v_add_f32_e32 v0, v20, v0
	s_andn2_b64 vcc, exec, s[20:21]
	s_nop 0
	v_add_f32_dpp v0, v0, v0 quad_perm:[1,0,3,2] row_mask:0xf bank_mask:0xf bound_ctrl:1
	s_nop 1
	v_add_f32_dpp v0, v0, v0 quad_perm:[2,3,0,1] row_mask:0xf bank_mask:0xf bound_ctrl:1
	s_nop 1
	v_add_f32_dpp v0, v0, v0 row_half_mirror row_mask:0xf bank_mask:0xf bound_ctrl:1
	s_nop 1
	v_add_f32_dpp v0, v0, v0 row_mirror row_mask:0xf bank_mask:0xf bound_ctrl:1
	v_fmamk_f32 v0, v0, 0x3c000000, v233
	v_rsq_f32_e32 v0, v0
	s_nop 0
	v_pk_mul_f32 v[20:21], v[0:1], v[6:7] op_sel_hi:[0,1]
	s_waitcnt vmcnt(0)
	v_pk_mul_f32 v[14:15], v[14:15], v[20:21]
	v_pk_mul_f32 v[20:21], v[0:1], v[8:9] op_sel_hi:[0,1]
	v_pk_mul_f32 v[16:17], v[16:17], v[20:21]
	v_pk_mul_f32 v[20:21], v[0:1], v[18:19] op_sel_hi:[0,1]
	v_pk_mul_f32 v[10:11], v[10:11], v[20:21]
	v_pk_mul_f32 v[20:21], v[0:1], v[22:23] op_sel_hi:[0,1]
	v_pk_mul_f32 v[12:13], v[20:21], v[12:13] op_sel:[1,0] op_sel_hi:[0,1]
	s_cbranch_vccnz .LBB0_671
	v_mov_b32_e32 v0, s31
	v_mov_b32_e32 v20, s30
	v_cndmask_b32_e64 v0, v0, v20, s[4:5]
	v_lshl_or_b32 v0, v0, 8, v71
	v_or_b32_e32 v72, 8, v0
	global_load_dwordx2 v[68:69], v0, s[0:1]
	global_load_dwordx4 v[52:55], v72, s[0:1] offset:32
	global_load_dwordx4 v[56:59], v72, s[0:1] offset:16
	global_load_dwordx4 v[60:63], v72, s[0:1]
	global_load_dwordx2 v[72:73], v72, s[0:1] offset:48
	ds_swizzle_b32 v20, v14 offset:swizzle(SWAP,4)
	ds_swizzle_b32 v21, v15 offset:swizzle(SWAP,4)
	ds_swizzle_b32 v24, v16 offset:swizzle(SWAP,4)
	ds_swizzle_b32 v25, v17 offset:swizzle(SWAP,4)
	ds_swizzle_b32 v64, v10 offset:swizzle(SWAP,4)
	ds_swizzle_b32 v65, v11 offset:swizzle(SWAP,4)
	ds_swizzle_b32 v66, v12 offset:swizzle(SWAP,4)
	ds_swizzle_b32 v67, v13 offset:swizzle(SWAP,4)
	s_waitcnt vmcnt(4)
	v_mov_b32_e32 v74, v69
	s_waitcnt vmcnt(1)
	v_mov_b32_e32 v75, v61
	s_waitcnt lgkmcnt(6)
	v_pk_mul_f32 v[20:21], v[74:75], v[20:21]
	v_mov_b32_e32 v69, v60
	v_cndmask_b32_e64 v21, v21, -v21, s[6:7]
	v_cndmask_b32_e64 v20, v20, -v20, s[6:7]
	v_pk_fma_f32 v[14:15], v[14:15], v[68:69], v[20:21]
	v_mov_b32_e32 v20, v63
	v_mov_b32_e32 v21, v57
	s_waitcnt lgkmcnt(4)
	v_pk_mul_f32 v[20:21], v[20:21], v[24:25]
	v_mov_b32_e32 v63, v56
	v_cndmask_b32_e64 v21, v21, -v21, s[6:7]
	v_cndmask_b32_e64 v20, v20, -v20, s[6:7]
	v_pk_fma_f32 v[16:17], v[16:17], v[62:63], v[20:21]
	v_mov_b32_e32 v20, v59
	v_mov_b32_e32 v21, v53
	s_waitcnt lgkmcnt(2)
	v_pk_mul_f32 v[20:21], v[20:21], v[64:65]
	v_mov_b32_e32 v59, v52
	v_cndmask_b32_e64 v21, v21, -v21, s[6:7]
	v_cndmask_b32_e64 v20, v20, -v20, s[6:7]
	v_pk_fma_f32 v[10:11], v[10:11], v[58:59], v[20:21]
	v_mov_b32_e32 v20, v55
	s_waitcnt vmcnt(0)
	v_mov_b32_e32 v21, v73
	s_waitcnt lgkmcnt(0)
	v_pk_mul_f32 v[20:21], v[20:21], v[66:67]
	v_mov_b32_e32 v55, v72
	v_cndmask_b32_e64 v21, v21, -v21, s[6:7]
	v_cndmask_b32_e64 v20, v20, -v20, s[6:7]
	v_pk_fma_f32 v[12:13], v[12:13], v[54:55], v[20:21]

.LBB0_778:
	s_lshl_b64 s[6:7], s[6:7], 1
	s_add_u32 s36, s28, s6
	v_readfirstlane_b32 s33, v164
	s_addc_u32 s37, s29, s7
	s_ashr_i32 s33, s33, 6
	s_lshl_b32 s40, s33, 5
	v_or_b32_e32 v0, s40, v179
	v_mov_b64_e32 v[2:3], s[36:37]
	s_movk_i32 s36, 0x2400
	v_mad_i64_i32 v[2:3], s[36:37], v0, s36, v[2:3]
	v_lshlrev_b32_e32 v0, 1, v168
	v_lshl_add_u64 v[14:15], v[2:3], 0, v[0:1]
	global_load_dwordx4 v[2:5], v[14:15], off
	global_load_dwordx4 v[6:9], v[14:15], off offset:32
	global_load_dwordx4 v[10:13], v[14:15], off offset:64
	global_load_dwordx4 v[14:17], v[14:15], off offset:96
	s_and_b64 vcc, exec, s[0:1]
	s_mov_b64 s[36:37], -1
	s_cbranch_vccz .LBB0_780
	v_add_u32_e32 v40, s40, v142
	v_ashrrev_i32_e32 v58, 1, v40
	s_movk_i32 s98, 0xffe0
	v_and_or_b32 v60, v58, s98, v212
	v_ashrrev_i32_e32 v61, 31, v60
	v_lshl_add_u64 v[58:59], v[60:61], 3, s[22:23]
	global_load_dwordx2 v[42:43], v[58:59], off
	v_add_u32_e32 v40, s40, v142
	v_ashrrev_i32_e32 v58, 1, v40
	s_movk_i32 s98, 0xffe0
	v_and_or_b32 v60, v58, s98, v212
	v_or_b32_e32 v58, 2, v60
	v_ashrrev_i32_e32 v59, 31, v58
	v_lshl_add_u64 v[58:59], v[58:59], 3, s[22:23]
	global_load_dwordx2 v[44:45], v[58:59], off
	v_add_u32_e32 v40, s40, v142
	v_ashrrev_i32_e32 v58, 1, v40
	s_movk_i32 s98, 0xffe0
	v_and_or_b32 v60, v58, s98, v212
	v_or_b32_e32 v64, 4, v60
	v_ashrrev_i32_e32 v65, 31, v64
	v_lshl_add_u64 v[64:65], v[64:65], 3, s[22:23]
	global_load_dwordx2 v[46:47], v[64:65], off
	v_add_u32_e32 v40, s40, v142
	v_ashrrev_i32_e32 v58, 1, v40
	s_movk_i32 s98, 0xffe0
	v_and_or_b32 v60, v58, s98, v212
	v_or_b32_e32 v66, 6, v60
	v_ashrrev_i32_e32 v67, 31, v66
	v_lshl_add_u64 v[66:67], v[66:67], 3, s[22:23]
	global_load_dwordx2 v[48:49], v[66:67], off
	v_add_u32_e32 v40, s40, v142
	v_ashrrev_i32_e32 v58, 1, v40
	s_movk_i32 s98, 0xffe0
	v_and_or_b32 v60, v58, s98, v212
	v_or_b32_e32 v68, 8, v60
	v_ashrrev_i32_e32 v69, 31, v68
	v_lshl_add_u64 v[68:69], v[68:69], 3, s[22:23]
	global_load_dwordx2 v[50:51], v[68:69], off
	v_add_u32_e32 v40, s40, v142
	v_ashrrev_i32_e32 v58, 1, v40
	s_movk_i32 s98, 0xffe0
	v_and_or_b32 v60, v58, s98, v212
	v_or_b32_e32 v70, 10, v60
	v_ashrrev_i32_e32 v71, 31, v70
	v_lshl_add_u64 v[70:71], v[70:71], 3, s[22:23]
	global_load_dwordx2 v[52:53], v[70:71], off
	v_add_u32_e32 v40, s40, v142
	v_ashrrev_i32_e32 v58, 1, v40
	s_movk_i32 s98, 0xffe0
	v_and_or_b32 v60, v58, s98, v212
	v_or_b32_e32 v72, 12, v60
	v_ashrrev_i32_e32 v73, 31, v72
	v_lshl_add_u64 v[72:73], v[72:73], 3, s[22:23]
	global_load_dwordx2 v[54:55], v[72:73], off
	v_add_u32_e32 v40, s40, v142
	v_ashrrev_i32_e32 v58, 1, v40
	s_movk_i32 s98, 0xffe0
	v_and_or_b32 v60, v58, s98, v212
	v_or_b32_e32 v60, 14, v60
	v_ashrrev_i32_e32 v61, 31, v60
	v_lshl_add_u64 v[60:61], v[60:61], 3, s[22:23]
	global_load_dwordx2 v[56:57], v[60:61], off
	v_add_u32_e32 v40, s40, v142
	v_lshlrev_b32_e32 v40, 5, v40
	s_movk_i32 s98, 0x7e0
	v_and_or_b32 v40, v40, s98, v212
	v_lshlrev_b32_e32 v40, 3, v40
	global_load_dwordx2 v[58:59], v40, s[22:23]
	v_add_u32_e32 v40, s40, v142
	v_lshlrev_b32_e32 v40, 5, v40
	s_movk_i32 s98, 0x7e0
	v_and_or_b32 v40, v40, s98, v212
	v_lshlrev_b32_e32 v40, 3, v40
	global_load_dwordx2 v[60:61], v40, s[22:23] offset:16
	v_add_u32_e32 v40, s40, v142
	v_lshlrev_b32_e32 v40, 5, v40
	s_movk_i32 s98, 0x7e0
	v_and_or_b32 v40, v40, s98, v212
	v_lshlrev_b32_e32 v40, 3, v40
	global_load_dwordx2 v[62:63], v40, s[22:23] offset:32
	v_add_u32_e32 v40, s40, v142
	v_lshlrev_b32_e32 v40, 5, v40
	s_movk_i32 s98, 0x7e0
	v_and_or_b32 v40, v40, s98, v212
	v_lshlrev_b32_e32 v40, 3, v40
	global_load_dwordx2 v[64:65], v40, s[22:23] offset:48
	v_add_u32_e32 v40, s40, v142
	v_lshlrev_b32_e32 v40, 5, v40
	s_movk_i32 s98, 0x7e0
	v_and_or_b32 v40, v40, s98, v212
	v_lshlrev_b32_e32 v40, 3, v40
	global_load_dwordx2 v[66:67], v40, s[22:23] offset:64
	v_add_u32_e32 v40, s40, v142
	v_lshlrev_b32_e32 v40, 5, v40
	s_movk_i32 s98, 0x7e0
	v_and_or_b32 v40, v40, s98, v212
	v_lshlrev_b32_e32 v40, 3, v40
	global_load_dwordx2 v[68:69], v40, s[22:23] offset:80
	v_add_u32_e32 v40, s40, v142
	v_lshlrev_b32_e32 v40, 5, v40
	s_movk_i32 s98, 0x7e0
	v_and_or_b32 v40, v40, s98, v212
	v_lshlrev_b32_e32 v40, 3, v40
	global_load_dwordx2 v[70:71], v40, s[22:23] offset:96
	v_add_u32_e32 v40, s40, v142
	v_lshlrev_b32_e32 v40, 5, v40
	s_movk_i32 s98, 0x7e0
	v_and_or_b32 v40, v40, s98, v212
	v_lshlrev_b32_e32 v40, 3, v40
	global_load_dwordx2 v[72:73], v40, s[22:23] offset:112
	v_add_u32_e32 v0, s40, v142
	v_ashrrev_i32_e32 v18, 1, v0
	s_movk_i32 s36, 0xffe0
	v_and_or_b32 v20, v18, s36, v212
	v_ashrrev_i32_e32 v21, 31, v20
	v_lshl_add_u64 v[18:19], v[20:21], 3, s[22:23]
	s_nop 0
	v_or_b32_e32 v18, 2, v20
	v_ashrrev_i32_e32 v19, 31, v18
	v_lshl_add_u64 v[18:19], v[18:19], 3, s[22:23]
	s_nop 0
	s_waitcnt vmcnt(18)
	v_lshlrev_b32_e32 v26, 16, v6
	v_and_b32_e32 v27, 0xffff0000, v6
	v_lshlrev_b32_e32 v24, 16, v2
	v_and_b32_e32 v25, 0xffff0000, v2
	v_lshlrev_b32_e32 v30, 16, v7
	v_and_b32_e32 v31, 0xffff0000, v7
	v_lshlrev_b32_e32 v34, 16, v8
	v_and_b32_e32 v35, 0xffff0000, v8
	v_lshlrev_b32_e32 v0, 5, v0
	s_movk_i32 s36, 0x7e0
	v_and_or_b32 v0, v0, s36, v212
	v_lshlrev_b32_e32 v0, 3, v0
	s_mov_b64 s[36:37], 0
	s_waitcnt vmcnt(16)
	s_waitcnt vmcnt(15)
	v_mov_b32_e32 v28, v43
	s_waitcnt vmcnt(14)
	v_mov_b32_e32 v29, v45
	v_mov_b32_e32 v43, v44
	v_pk_mul_f32 v[44:45], v[42:43], v[26:27]
	v_pk_mul_f32 v[26:27], v[28:29], v[26:27]
	v_pk_fma_f32 v[44:45], v[28:29], v[24:25], v[44:45]
	v_pk_fma_f32 v[42:43], v[42:43], v[24:25], v[26:27] neg_lo:[0,0,1] neg_hi:[0,0,1]
	v_or_b32_e32 v24, 4, v20
	v_or_b32_e32 v26, 6, v20
	v_ashrrev_i32_e32 v25, 31, v24
	v_ashrrev_i32_e32 v27, 31, v26
	v_lshl_add_u64 v[24:25], v[24:25], 3, s[22:23]
	v_lshl_add_u64 v[26:27], v[26:27], 3, s[22:23]
	s_nop 0
	v_lshlrev_b32_e32 v28, 16, v3
	s_nop 0
	v_and_b32_e32 v29, 0xffff0000, v3
	v_cvt_pk_bf16_f32 v112, v44, v45
	v_cvt_pk_bf16_f32 v116, v42, v43
	v_lshlrev_b32_e32 v42, 16, v10
	v_and_b32_e32 v43, 0xffff0000, v10
	s_waitcnt vmcnt(13)
	v_mov_b32_e32 v32, v47
	s_waitcnt vmcnt(12)
	v_mov_b32_e32 v33, v49
	v_mov_b32_e32 v47, v48
	v_pk_mul_f32 v[48:49], v[46:47], v[30:31]
	v_pk_mul_f32 v[30:31], v[32:33], v[30:31]
	v_pk_fma_f32 v[48:49], v[32:33], v[28:29], v[48:49]
	v_pk_fma_f32 v[46:47], v[46:47], v[28:29], v[30:31] neg_lo:[0,0,1] neg_hi:[0,0,1]
	v_or_b32_e32 v28, 8, v20
	v_or_b32_e32 v30, 10, v20
	v_ashrrev_i32_e32 v29, 31, v28
	v_ashrrev_i32_e32 v31, 31, v30
	v_lshl_add_u64 v[28:29], v[28:29], 3, s[22:23]
	v_lshl_add_u64 v[30:31], v[30:31], 3, s[22:23]
	s_nop 0
	v_lshlrev_b32_e32 v32, 16, v4
	s_nop 0
	v_and_b32_e32 v33, 0xffff0000, v4
	v_cvt_pk_bf16_f32 v117, v46, v47
	v_cvt_pk_bf16_f32 v113, v48, v49
	v_lshlrev_b32_e32 v46, 16, v14
	v_and_b32_e32 v47, 0xffff0000, v14
	s_waitcnt vmcnt(11)
	v_mov_b32_e32 v36, v51
	s_waitcnt vmcnt(10)
	v_mov_b32_e32 v37, v53
	v_mov_b32_e32 v51, v52
	v_pk_mul_f32 v[52:53], v[50:51], v[34:35]
	v_pk_mul_f32 v[34:35], v[36:37], v[34:35]
	v_pk_fma_f32 v[52:53], v[36:37], v[32:33], v[52:53]
	v_pk_fma_f32 v[50:51], v[50:51], v[32:33], v[34:35] neg_lo:[0,0,1] neg_hi:[0,0,1]
	v_or_b32_e32 v32, 12, v20
	v_or_b32_e32 v20, 14, v20
	v_ashrrev_i32_e32 v33, 31, v32
	v_ashrrev_i32_e32 v21, 31, v20
	v_lshl_add_u64 v[32:33], v[32:33], 3, s[22:23]
	v_lshl_add_u64 v[20:21], v[20:21], 3, s[22:23]
	s_nop 0
	v_lshlrev_b32_e32 v36, 16, v9
	s_nop 0
	v_and_b32_e32 v37, 0xffff0000, v9
	v_lshlrev_b32_e32 v34, 16, v5
	v_and_b32_e32 v35, 0xffff0000, v5
	v_cvt_pk_bf16_f32 v118, v50, v51
	v_cvt_pk_bf16_f32 v114, v52, v53
	v_lshlrev_b32_e32 v50, 16, v15
	v_and_b32_e32 v51, 0xffff0000, v15
	s_waitcnt vmcnt(9)
	v_mov_b32_e32 v38, v55
	s_waitcnt vmcnt(8)
	v_mov_b32_e32 v55, v56
	v_mov_b32_e32 v39, v57
	v_pk_mul_f32 v[56:57], v[54:55], v[36:37]
	v_pk_mul_f32 v[36:37], v[38:39], v[36:37]
	v_pk_fma_f32 v[56:57], v[38:39], v[34:35], v[56:57]
	v_pk_fma_f32 v[54:55], v[54:55], v[34:35], v[36:37] neg_lo:[0,0,1] neg_hi:[0,0,1]
	v_cvt_pk_bf16_f32 v115, v56, v57
	s_nop 0
	s_nop 0
	v_cvt_pk_bf16_f32 v119, v54, v55
	v_lshlrev_b32_e32 v54, 16, v16
	v_and_b32_e32 v55, 0xffff0000, v16
	v_lshlrev_b32_e32 v36, 16, v17
	v_and_b32_e32 v37, 0xffff0000, v17
	s_waitcnt vmcnt(7)
	v_mov_b32_e32 v48, v59
	s_waitcnt vmcnt(6)
	v_mov_b32_e32 v49, v61
	v_mov_b32_e32 v59, v60
	v_pk_mul_f32 v[60:61], v[58:59], v[46:47]
	v_pk_mul_f32 v[46:47], v[48:49], v[46:47]
	v_pk_fma_f32 v[60:61], v[48:49], v[42:43], v[60:61]
	v_pk_fma_f32 v[58:59], v[58:59], v[42:43], v[46:47] neg_lo:[0,0,1] neg_hi:[0,0,1]
	s_nop 0
	s_nop 0
	v_lshlrev_b32_e32 v48, 16, v11
	v_and_b32_e32 v49, 0xffff0000, v11
	v_cvt_pk_bf16_f32 v124, v58, v59
	v_cvt_pk_bf16_f32 v120, v60, v61
	s_waitcnt vmcnt(5)
	v_mov_b32_e32 v52, v63
	s_waitcnt vmcnt(4)
	v_mov_b32_e32 v53, v65
	v_mov_b32_e32 v63, v64
	v_pk_mul_f32 v[64:65], v[62:63], v[50:51]
	v_pk_mul_f32 v[50:51], v[52:53], v[50:51]
	v_pk_fma_f32 v[64:65], v[52:53], v[48:49], v[64:65]
	v_pk_fma_f32 v[62:63], v[62:63], v[48:49], v[50:51] neg_lo:[0,0,1] neg_hi:[0,0,1]
	s_nop 0
	s_nop 0
	v_lshlrev_b32_e32 v52, 16, v12
	v_and_b32_e32 v53, 0xffff0000, v12
	v_cvt_pk_bf16_f32 v125, v62, v63
	v_cvt_pk_bf16_f32 v121, v64, v65
	s_waitcnt vmcnt(3)
	v_mov_b32_e32 v34, v67
	s_waitcnt vmcnt(2)
	v_mov_b32_e32 v35, v69
	v_mov_b32_e32 v67, v68
	v_pk_mul_f32 v[68:69], v[66:67], v[54:55]
	v_pk_mul_f32 v[54:55], v[34:35], v[54:55]
	v_pk_fma_f32 v[68:69], v[34:35], v[52:53], v[68:69]
	v_pk_fma_f32 v[66:67], v[66:67], v[52:53], v[54:55] neg_lo:[0,0,1] neg_hi:[0,0,1]
	s_nop 0
	s_nop 0
	v_lshlrev_b32_e32 v34, 16, v13
	v_and_b32_e32 v35, 0xffff0000, v13
	v_cvt_pk_bf16_f32 v126, v66, v67
	v_cvt_pk_bf16_f32 v122, v68, v69
	s_waitcnt vmcnt(1)
	v_mov_b32_e32 v38, v71
	s_waitcnt vmcnt(0)
	v_mov_b32_e32 v39, v73
	v_mov_b32_e32 v71, v72
	v_pk_mul_f32 v[72:73], v[70:71], v[36:37]
	v_pk_mul_f32 v[36:37], v[38:39], v[36:37]
	v_pk_fma_f32 v[72:73], v[38:39], v[34:35], v[72:73]
	v_pk_fma_f32 v[70:71], v[70:71], v[34:35], v[36:37] neg_lo:[0,0,1] neg_hi:[0,0,1]
	v_cvt_pk_bf16_f32 v123, v72, v73
	v_cvt_pk_bf16_f32 v127, v70, v71

.LBB0_783:
	s_and_b32 s36, s33, 1
	s_mul_i32 s37, s36, 0x6800
	s_add_i32 s37, s37, 0
	v_add3_u32 v0, s37, v215, v212
	ds_read_b128 v[2:5], v0
	ds_read_b128 v[6:9], v0 offset:32
	s_waitcnt lgkmcnt(1)
	v_mfma_f32_32x32x16_bf16 v[96:111], v[2:5], v[116:119], 0
	ds_read_b128 v[2:5], v0 offset:4608
	ds_read_b128 v[10:13], v0 offset:4640
	s_waitcnt lgkmcnt(1)
	v_mfma_f32_32x32x16_bf16 v[80:95], v[2:5], v[116:119], 0
	ds_read_b128 v[2:5], v0 offset:64
	ds_read_b128 v[146:149], v0 offset:96
	v_mfma_f32_32x32x16_bf16 v[96:111], v[6:9], v[112:115], v[96:111]
	s_waitcnt lgkmcnt(2)
	v_mfma_f32_32x32x16_bf16 v[80:95], v[10:13], v[112:115], v[80:95]
	s_waitcnt lgkmcnt(1)
	v_mfma_f32_32x32x16_bf16 v[96:111], v[2:5], v[124:127], v[96:111]
	ds_read_b128 v[2:5], v0 offset:4672
	ds_read_b128 v[6:9], v0 offset:4704
	v_mov_b32_e32 v0, v137
	s_waitcnt lgkmcnt(1)
	v_mfma_f32_32x32x16_bf16 v[80:95], v[2:5], v[124:127], v[80:95]
	v_lshl_add_u64 v[2:3], v[138:139], 0, s[6:7]
	v_lshl_add_u64 v[4:5], v[140:141], 0, s[6:7]
	global_load_dwordx4 v[10:13], v[2:3], off
	s_waitcnt lgkmcnt(0)
	v_mfma_f32_32x32x16_bf16 v[80:95], v[6:9], v[120:123], v[80:95]
	global_load_dwordx4 v[6:9], v[4:5], off offset:-16
	global_load_dwordx4 v[2:5], v[4:5], off
	v_mfma_f32_32x32x16_bf16 v[96:111], v[146:149], v[120:123], v[96:111]
	s_nop 7
	s_nop 2
	s_nop 0
	v_max_f32_e32 v14, v97, v81
	v_max_f32_e32 v15, v98, v82
	v_max3_f32 v14, v96, v80, v14
	v_max_f32_e32 v136, v99, v83
	v_max3_f32 v14, v14, v15, v136
	v_max_f32_e32 v15, v100, v84
	v_max_f32_e32 v136, v101, v85
	v_max3_f32 v14, v14, v15, v136
	v_max_f32_e32 v15, v102, v86
	v_max_f32_e32 v136, v103, v87
	v_max3_f32 v14, v14, v15, v136
	v_max_f32_e32 v15, v104, v88
	v_max_f32_e32 v136, v105, v89
	v_max3_f32 v14, v14, v15, v136
	v_max_f32_e32 v15, v106, v90
	v_max_f32_e32 v136, v107, v91
	v_max3_f32 v14, v14, v15, v136
	v_max_f32_e32 v15, v108, v92
	v_max_f32_e32 v136, v109, v93
	v_max3_f32 v14, v14, v15, v136
	v_max_f32_e32 v15, v110, v94
	v_max_f32_e32 v136, v111, v95
	v_max3_f32 v14, v14, v15, v136
	v_mov_b32_e32 v15, v14
	s_nop 1
	v_permlane32_swap_b32_e32 v14, v15
	v_max3_f32 v137, v0, v14, v15
	v_sub_f32_e32 v0, v0, v137
	v_mul_f32_e32 v0, 0x3e38aa3b, v0
	v_exp_f32_e32 v14, v0
	s_nop 0
	v_cmp_eq_f32_e32 vcc, 1.0, v14
	s_cmp_eq_u64 vcc, exec
	s_cbranch_scc1 .LBB0_785
	v_pk_mul_f32 v[78:79], v[78:79], v[14:15] op_sel_hi:[1,0]
	v_pk_mul_f32 v[76:77], v[76:77], v[14:15] op_sel_hi:[1,0]
	v_pk_mul_f32 v[74:75], v[74:75], v[14:15] op_sel_hi:[1,0]
	v_pk_mul_f32 v[72:73], v[72:73], v[14:15] op_sel_hi:[1,0]
	v_pk_mul_f32 v[70:71], v[70:71], v[14:15] op_sel_hi:[1,0]
	v_pk_mul_f32 v[68:69], v[68:69], v[14:15] op_sel_hi:[1,0]
	v_pk_mul_f32 v[66:67], v[66:67], v[14:15] op_sel_hi:[1,0]
	v_pk_mul_f32 v[64:65], v[64:65], v[14:15] op_sel_hi:[1,0]
	v_pk_mul_f32 v[62:63], v[62:63], v[14:15] op_sel_hi:[1,0]
	v_pk_mul_f32 v[60:61], v[60:61], v[14:15] op_sel_hi:[1,0]
	v_pk_mul_f32 v[58:59], v[58:59], v[14:15] op_sel_hi:[1,0]
	v_pk_mul_f32 v[56:57], v[56:57], v[14:15] op_sel_hi:[1,0]
	v_pk_mul_f32 v[54:55], v[54:55], v[14:15] op_sel_hi:[1,0]
	v_pk_mul_f32 v[52:53], v[52:53], v[14:15] op_sel_hi:[1,0]
	v_pk_mul_f32 v[50:51], v[50:51], v[14:15] op_sel_hi:[1,0]
	v_pk_mul_f32 v[48:49], v[48:49], v[14:15] op_sel_hi:[1,0]
	v_pk_mul_f32 v[46:47], v[46:47], v[14:15] op_sel_hi:[1,0]
	v_pk_mul_f32 v[44:45], v[44:45], v[14:15] op_sel_hi:[1,0]
	v_pk_mul_f32 v[42:43], v[42:43], v[14:15] op_sel_hi:[1,0]
	v_pk_mul_f32 v[40:41], v[40:41], v[14:15] op_sel_hi:[1,0]
	v_pk_mul_f32 v[38:39], v[38:39], v[14:15] op_sel_hi:[1,0]
	v_pk_mul_f32 v[36:37], v[36:37], v[14:15] op_sel_hi:[1,0]
	v_pk_mul_f32 v[34:35], v[34:35], v[14:15] op_sel_hi:[1,0]
	v_pk_mul_f32 v[32:33], v[32:33], v[14:15] op_sel_hi:[1,0]
	v_pk_mul_f32 v[30:31], v[30:31], v[14:15] op_sel_hi:[1,0]
	v_pk_mul_f32 v[28:29], v[28:29], v[14:15] op_sel_hi:[1,0]
	v_pk_mul_f32 v[26:27], v[26:27], v[14:15] op_sel_hi:[1,0]
	v_pk_mul_f32 v[24:25], v[24:25], v[14:15] op_sel_hi:[1,0]
	v_pk_mul_f32 v[22:23], v[22:23], v[14:15] op_sel_hi:[1,0]
	v_pk_mul_f32 v[20:21], v[20:21], v[14:15] op_sel_hi:[1,0]
	v_pk_mul_f32 v[18:19], v[18:19], v[14:15] op_sel_hi:[1,0]
	v_pk_mul_f32 v[16:17], v[16:17], v[14:15] op_sel_hi:[1,0]

.LBB0_795:
	s_lshl_b32 s19, s19, 10
	s_or_b32 s19, s19, s33
	s_and_b32 s46, s28, 7
	s_addk_i32 s19, 0x2000
	s_and_b64 s[6:7], s[6:7], exec
	s_cselect_b32 s19, s19, s35
	s_mul_i32 s7, s19, 0x2400
	s_mul_hi_i32 s6, s19, 0x2400
	s_add_u32 s7, s39, s7
	s_addc_u32 s6, s50, s6
	s_lshl_b32 s35, s46, 8
	s_add_u32 s7, s7, s35
	s_addc_u32 s35, s6, 0
	s_add_u32 s6, s7, 0x1800
	s_addc_u32 s7, s35, 0
	v_readfirstlane_b32 s35, v164
	s_ashr_i32 s35, s35, 6
	s_lshl_b32 s40, s35, 5
	v_or_b32_e32 v0, s40, v179
	v_mov_b64_e32 v[2:3], s[6:7]
	s_movk_i32 s6, 0x2400
	v_mad_i64_i32 v[2:3], s[6:7], v0, s6, v[2:3]
	v_lshlrev_b32_e32 v0, 1, v168
	v_lshl_add_u64 v[22:23], v[2:3], 0, v[0:1]
	global_load_dwordx4 v[2:5], v[22:23], off
	global_load_dwordx4 v[6:9], v[22:23], off offset:32
	global_load_dwordx4 v[26:29], v[22:23], off offset:64
	global_load_dwordx4 v[30:33], v[22:23], off offset:96
	global_load_dwordx4 v[10:13], v[22:23], off offset:128
	global_load_dwordx4 v[14:17], v[22:23], off offset:160
	global_load_dwordx4 v[18:21], v[22:23], off offset:192
	global_load_dwordx4 v[22:25], v[22:23], off offset:224
	s_load_dwordx2 s[36:37], s[20:21], 0xa8
	s_mov_b64 s[6:7], -1
	s_waitcnt lgkmcnt(0)
	s_cmp_lg_u64 s[36:37], 0
	s_cbranch_scc0 .LBB0_805
	s_lshl_b64 s[6:7], s[30:31], 2
	s_waitcnt vmcnt(0)
	v_and_b32_e32 v50, 0xffff0000, v25
	s_add_u32 s6, s36, s6
	v_lshlrev_b32_e32 v55, 16, v25
	v_mov_b32_e32 v54, v50
	v_or_b32_e32 v0, s33, v179
	s_addc_u32 s7, s37, s7
	v_pk_mul_f32 v[140:141], v[54:55], v[54:55]
	v_add_u32_e32 v54, s40, v0
	v_lshlrev_b32_e32 v0, 2, v168
	global_load_dwordx4 v[112:115], v0, s[6:7] offset:16
	global_load_dwordx4 v[34:37], v0, s[6:7]
	global_load_dwordx4 v[116:119], v0, s[6:7] offset:144
	global_load_dwordx4 v[44:47], v0, s[6:7] offset:128
	v_lshlrev_b32_e32 v146, 16, v2
	v_and_b32_e32 v147, 0xffff0000, v2
	v_pk_mul_f32 v[148:149], v[146:147], v[146:147]
	v_lshlrev_b32_e32 v154, 16, v3
	v_and_b32_e32 v155, 0xffff0000, v3
	v_pk_mul_f32 v[156:157], v[154:155], v[154:155]
	v_add_f32_e32 v148, v148, v149
	v_lshlrev_b32_e32 v162, 16, v4
	v_and_b32_e32 v163, 0xffff0000, v4
	v_add_f32_e32 v148, v156, v148
	v_pk_mul_f32 v[208:209], v[162:163], v[162:163]
	v_add_f32_e32 v148, v157, v148
	v_add_f32_e32 v148, v208, v148
	v_lshlrev_b32_e32 v111, 16, v5
	v_and_b32_e32 v143, 0xffff0000, v5
	v_and_b32_e32 v142, 0xffff0000, v29
	v_add_f32_e32 v148, v209, v148
	v_lshlrev_b32_e32 v72, 16, v6
	v_and_b32_e32 v73, 0xffff0000, v6
	v_pk_mul_f32 v[144:145], v[142:143], v[142:143]
	v_fmac_f32_e32 v148, v111, v111
	v_pk_mul_f32 v[38:39], v[72:73], v[72:73]
	v_add_f32_e32 v145, v145, v148
	v_lshlrev_b32_e32 v74, 16, v7
	v_and_b32_e32 v75, 0xffff0000, v7
	v_add_f32_e32 v38, v38, v145
	v_pk_mul_f32 v[40:41], v[74:75], v[74:75]
	v_add_f32_e32 v38, v39, v38
	v_lshlrev_b32_e32 v78, 16, v8
	v_and_b32_e32 v79, 0xffff0000, v8
	v_add_f32_e32 v38, v40, v38
	v_pk_mul_f32 v[42:43], v[78:79], v[78:79]
	v_add_f32_e32 v38, v41, v38
	v_add_f32_e32 v38, v42, v38
	v_lshlrev_b32_e32 v108, 16, v9
	v_and_b32_e32 v87, 0xffff0000, v9
	v_and_b32_e32 v86, 0xffff0000, v33
	v_add_f32_e32 v38, v43, v38
	v_pk_mul_f32 v[48:49], v[86:87], v[86:87]
	v_lshlrev_b32_e32 v150, 16, v26
	v_and_b32_e32 v151, 0xffff0000, v26
	v_fmac_f32_e32 v38, v108, v108
	v_pk_mul_f32 v[152:153], v[150:151], v[150:151]
	v_add_f32_e32 v38, v49, v38
	v_lshlrev_b32_e32 v158, 16, v27
	v_and_b32_e32 v159, 0xffff0000, v27
	v_add_f32_e32 v38, v152, v38
	v_pk_mul_f32 v[160:161], v[158:159], v[158:159]
	v_add_f32_e32 v38, v153, v38
	v_lshlrev_b32_e32 v218, 16, v28
	v_and_b32_e32 v219, 0xffff0000, v28
	v_add_f32_e32 v38, v160, v38
	v_pk_mul_f32 v[220:221], v[218:219], v[218:219]
	v_add_f32_e32 v38, v161, v38
	v_add_f32_e32 v38, v220, v38
	v_lshlrev_b32_e32 v175, 16, v29
	v_add_f32_e32 v38, v221, v38
	v_lshlrev_b32_e32 v70, 16, v30
	v_and_b32_e32 v71, 0xffff0000, v30
	v_fmac_f32_e32 v38, v175, v175
	v_pk_mul_f32 v[52:53], v[70:71], v[70:71]
	v_add_f32_e32 v38, v144, v38
	v_lshlrev_b32_e32 v76, 16, v31
	v_and_b32_e32 v77, 0xffff0000, v31
	v_add_f32_e32 v38, v52, v38
	v_pk_mul_f32 v[68:69], v[76:77], v[76:77]
	v_add_f32_e32 v38, v53, v38
	v_lshlrev_b32_e32 v82, 16, v32
	v_and_b32_e32 v83, 0xffff0000, v32
	v_add_f32_e32 v38, v68, v38
	v_pk_mul_f32 v[80:81], v[82:83], v[82:83]
	v_add_f32_e32 v38, v69, v38
	v_add_f32_e32 v38, v80, v38
	v_lshlrev_b32_e32 v109, 16, v33
	v_add_f32_e32 v38, v81, v38
	v_lshlrev_b32_e32 v100, 16, v10
	v_and_b32_e32 v101, 0xffff0000, v10
	v_fmac_f32_e32 v38, v109, v109
	v_pk_mul_f32 v[84:85], v[100:101], v[100:101]
	v_add_f32_e32 v38, v48, v38
	v_lshlrev_b32_e32 v90, 16, v11
	v_and_b32_e32 v91, 0xffff0000, v11
	v_add_f32_e32 v38, v84, v38
	v_pk_mul_f32 v[102:103], v[90:91], v[90:91]
	v_add_f32_e32 v38, v85, v38
	v_lshlrev_b32_e32 v94, 16, v12
	v_and_b32_e32 v95, 0xffff0000, v12
	v_add_f32_e32 v38, v102, v38
	v_pk_mul_f32 v[104:105], v[94:95], v[94:95]
	v_add_f32_e32 v38, v103, v38
	v_add_f32_e32 v38, v104, v38
	v_lshlrev_b32_e32 v107, 16, v13
	v_and_b32_e32 v97, 0xffff0000, v13
	v_and_b32_e32 v96, 0xffff0000, v21
	v_add_f32_e32 v38, v105, v38
	v_pk_mul_f32 v[120:121], v[96:97], v[96:97]
	v_lshlrev_b32_e32 v66, 16, v14
	v_and_b32_e32 v67, 0xffff0000, v14
	v_fmac_f32_e32 v38, v107, v107
	v_pk_mul_f32 v[128:129], v[66:67], v[66:67]
	v_add_f32_e32 v38, v121, v38
	v_lshlrev_b32_e32 v62, 16, v15
	v_and_b32_e32 v63, 0xffff0000, v15
	v_add_f32_e32 v38, v128, v38
	v_pk_mul_f32 v[130:131], v[62:63], v[62:63]
	v_add_f32_e32 v38, v129, v38
	v_lshlrev_b32_e32 v58, 16, v16
	v_and_b32_e32 v59, 0xffff0000, v16
	v_add_f32_e32 v38, v130, v38
	v_pk_mul_f32 v[132:133], v[58:59], v[58:59]
	v_add_f32_e32 v38, v131, v38
	v_add_f32_e32 v38, v132, v38
	v_lshlrev_b32_e32 v106, 16, v17
	v_add_f32_e32 v38, v133, v38
	v_lshlrev_b32_e32 v88, 16, v18
	v_and_b32_e32 v89, 0xffff0000, v18
	v_and_b32_e32 v51, 0xffff0000, v17
	v_fmac_f32_e32 v38, v106, v106
	v_pk_mul_f32 v[122:123], v[88:89], v[88:89]
	v_fmac_f32_e32 v38, v51, v51
	v_lshlrev_b32_e32 v92, 16, v19
	v_and_b32_e32 v93, 0xffff0000, v19
	v_add_f32_e32 v38, v122, v38
	v_pk_mul_f32 v[124:125], v[92:93], v[92:93]
	v_add_f32_e32 v38, v123, v38
	v_lshlrev_b32_e32 v98, 16, v20
	v_and_b32_e32 v99, 0xffff0000, v20
	v_add_f32_e32 v38, v124, v38
	v_pk_mul_f32 v[126:127], v[98:99], v[98:99]
	v_add_f32_e32 v38, v125, v38
	v_add_f32_e32 v38, v126, v38
	v_lshlrev_b32_e32 v110, 16, v21
	v_add_f32_e32 v38, v127, v38
	v_lshlrev_b32_e32 v64, 16, v22
	v_and_b32_e32 v65, 0xffff0000, v22
	v_fmac_f32_e32 v38, v110, v110
	v_pk_mul_f32 v[134:135], v[64:65], v[64:65]
	v_add_f32_e32 v38, v120, v38
	v_lshlrev_b32_e32 v60, 16, v23
	v_and_b32_e32 v61, 0xffff0000, v23
	v_add_f32_e32 v38, v134, v38
	v_pk_mul_f32 v[136:137], v[60:61], v[60:61]
	v_add_f32_e32 v38, v135, v38
	v_lshlrev_b32_e32 v56, 16, v24
	v_and_b32_e32 v57, 0xffff0000, v24
	v_add_f32_e32 v38, v136, v38
	v_pk_mul_f32 v[138:139], v[56:57], v[56:57]
	v_add_f32_e32 v38, v137, v38
	v_add_f32_e32 v38, v138, v38
	v_add_f32_e32 v38, v139, v38
	v_add_f32_e32 v38, v141, v38
	v_add_f32_e32 v38, v140, v38
	v_mov_b32_e32 v39, v38
	s_nop 1
	v_permlane32_swap_b32_e32 v38, v39
	v_add_f32_e32 v38, v38, v39
	v_fmamk_f32 v38, v38, 0x3c000000, v233
	v_rsq_f32_e32 v68, v38
	v_ashrrev_i32_e32 v38, 1, v54
	s_movk_i32 s33, 0xffe0
	v_and_or_b32 v104, v38, s33, v168
	s_waitcnt vmcnt(2)
	v_pk_mul_f32 v[34:35], v[34:35], v[68:69] op_sel_hi:[1,0]
	v_pk_mul_f32 v[36:37], v[36:37], v[68:69] op_sel_hi:[1,0]
	v_pk_mul_f32 v[38:39], v[68:69], v[112:113] op_sel_hi:[0,1]
	v_mul_f32_e32 v42, v68, v114
	s_waitcnt vmcnt(1)
	v_mov_b32_e32 v114, v119
	s_cmp_lg_u64 s[10:11], 0
	v_pk_mul_f32 v[40:41], v[34:35], v[146:147]
	s_waitcnt vmcnt(0)
	v_pk_mul_f32 v[34:35], v[44:45], v[68:69] op_sel_hi:[1,0]
	v_pk_mul_f32 v[44:45], v[36:37], v[154:155]
	v_pk_mul_f32 v[36:37], v[68:69], v[46:47] op_sel_hi:[0,1]
	v_pk_mul_f32 v[48:49], v[38:39], v[162:163]
	v_pk_mul_f32 v[38:39], v[68:69], v[116:117] op_sel_hi:[0,1]
	v_mul_f32_e32 v46, v42, v111
	v_mul_f32_e32 v42, v68, v118
	v_pk_mul_f32 v[52:53], v[68:69], v[114:115] op_sel_hi:[0,1]
	s_cselect_b64 s[36:37], -1, 0
	s_cmp_eq_u64 s[10:11], 0
	v_pk_mul_f32 v[34:35], v[34:35], v[150:151]
	v_pk_mul_f32 v[36:37], v[36:37], v[158:159]
	v_pk_mul_f32 v[38:39], v[38:39], v[218:219]
	v_mul_f32_e32 v42, v42, v175
	v_pk_mul_f32 v[52:53], v[52:53], v[142:143]
	s_cbranch_scc1 .LBB0_798
	v_ashrrev_i32_e32 v105, 31, v104
	v_lshl_add_u64 v[80:81], v[104:105], 3, s[10:11]
	global_load_dwordx4 v[112:115], v[80:81], off
	global_load_dwordx4 v[116:119], v[80:81], off offset:16
	global_load_dwordx4 v[120:123], v[80:81], off offset:32
	global_load_dwordx4 v[124:127], v[80:81], off offset:48
	s_waitcnt vmcnt(3)
	v_mov_b32_e32 v80, v112
	v_mov_b32_e32 v81, v114
	v_mov_b32_e32 v114, v113
	s_waitcnt vmcnt(2)
	v_mov_b32_e32 v85, v118
	v_mov_b32_e32 v118, v117
	s_waitcnt vmcnt(1)
	v_mov_b32_e32 v102, v120
	v_mov_b32_e32 v103, v122
	v_mov_b32_e32 v122, v121
	s_waitcnt vmcnt(0)
	v_mul_f32_e32 v112, v46, v124
	v_mul_f32_e32 v120, v46, v125
	v_pk_mul_f32 v[46:47], v[52:53], v[126:127] op_sel:[1,0] op_sel_hi:[0,1]
	v_pk_mul_f32 v[52:53], v[52:53], v[126:127]
	v_mov_b32_e32 v84, v116
	v_mul_f32_e32 v116, v42, v125
	v_mul_f32_e32 v42, v42, v124
	v_pk_mul_f32 v[124:125], v[34:35], v[114:115]
	v_pk_mul_f32 v[126:127], v[36:37], v[118:119]
	v_pk_mul_f32 v[128:129], v[38:39], v[122:123]
	v_mov_b32_e32 v113, v46
	v_mov_b32_e32 v117, v47
	v_mov_b32_e32 v121, v53
	v_mov_b32_e32 v43, v52
	v_pk_mul_f32 v[34:35], v[34:35], v[80:81]
	v_pk_mul_f32 v[36:37], v[36:37], v[84:85]
	v_pk_mul_f32 v[38:39], v[38:39], v[102:103]
	v_pk_fma_f32 v[80:81], v[40:41], v[80:81], v[124:125] neg_lo:[0,0,1] neg_hi:[0,0,1]
	v_pk_fma_f32 v[84:85], v[44:45], v[84:85], v[126:127] neg_lo:[0,0,1] neg_hi:[0,0,1]
	v_pk_fma_f32 v[102:103], v[48:49], v[102:103], v[128:129] neg_lo:[0,0,1] neg_hi:[0,0,1]
	v_pk_add_f32 v[46:47], v[112:113], v[116:117] neg_lo:[0,1] neg_hi:[0,1]
	v_pk_add_f32 v[42:43], v[120:121], v[42:43]
	v_pk_fma_f32 v[34:35], v[40:41], v[114:115], v[34:35]
	v_pk_fma_f32 v[36:37], v[44:45], v[118:119], v[36:37]
	v_pk_fma_f32 v[38:39], v[48:49], v[122:123], v[38:39]
	v_mov_b32_e32 v52, v43
	v_mov_b32_e32 v40, v80
	v_mov_b32_e32 v41, v81
	v_mov_b32_e32 v44, v84
	v_mov_b32_e32 v45, v85
	v_mov_b32_e32 v48, v102
	v_mov_b32_e32 v49, v103
	v_mov_b32_e32 v53, v47

.LBB0_808:
	s_and_b32 s10, s7, 1
	s_mul_i32 s11, s10, 0x8800
	s_add_i32 s11, s11, 0
	v_add3_u32 v0, s11, v211, v212
	ds_read_b128 v[66:69], v0
	ds_read_b128 v[130:133], v0 offset:32
	s_waitcnt lgkmcnt(1)
	v_mfma_f32_32x32x16_bf16 v[82:97], v[66:69], v[126:129], 0
	ds_read_b128 v[66:69], v0 offset:8704
	ds_read_b128 v[134:137], v0 offset:8736
	s_waitcnt lgkmcnt(1)
	v_mfma_f32_32x32x16_bf16 v[66:81], v[66:69], v[126:129], 0
	v_mfma_f32_32x32x16_bf16 v[82:97], v[130:133], v[118:121], v[82:97]
	s_waitcnt lgkmcnt(0)
	v_mfma_f32_32x32x16_bf16 v[66:81], v[134:137], v[118:121], v[66:81]
	ds_read_b128 v[130:133], v0 offset:64
	ds_read_b128 v[134:137], v0 offset:96
	s_waitcnt lgkmcnt(1)
	v_mfma_f32_32x32x16_bf16 v[82:97], v[130:133], v[122:125], v[82:97]
	ds_read_b128 v[130:133], v0 offset:8768
	ds_read_b128 v[138:141], v0 offset:8800
	s_waitcnt lgkmcnt(1)
	v_mfma_f32_32x32x16_bf16 v[66:81], v[130:133], v[122:125], v[66:81]
	v_mfma_f32_32x32x16_bf16 v[82:97], v[134:137], v[114:117], v[82:97]
	ds_read_b128 v[130:133], v0 offset:128
	ds_read_b128 v[134:137], v0 offset:160
	s_waitcnt lgkmcnt(2)
	v_mfma_f32_32x32x16_bf16 v[66:81], v[138:141], v[114:117], v[66:81]
	s_waitcnt lgkmcnt(1)
	v_mfma_f32_32x32x16_bf16 v[82:97], v[130:133], v[106:109], v[82:97]
	ds_read_b128 v[130:133], v0 offset:8832
	ds_read_b128 v[138:141], v0 offset:8864
	s_waitcnt lgkmcnt(1)
	v_mfma_f32_32x32x16_bf16 v[66:81], v[130:133], v[106:109], v[66:81]
	ds_read_b128 v[130:133], v0 offset:192
	ds_read_b128 v[158:161], v0 offset:224
	v_mfma_f32_32x32x16_bf16 v[82:97], v[134:137], v[110:113], v[82:97]
	s_waitcnt lgkmcnt(2)
	v_mfma_f32_32x32x16_bf16 v[66:81], v[138:141], v[110:113], v[66:81]
	v_lshl_add_u64 v[138:139], v[148:149], 0, s[2:3]
	s_waitcnt lgkmcnt(1)
	v_mfma_f32_32x32x16_bf16 v[82:97], v[130:133], v[98:101], v[82:97]
	ds_read_b128 v[130:133], v0 offset:8896
	ds_read_b128 v[134:137], v0 offset:8928
	v_mov_b32_e32 v0, v147
	s_waitcnt lgkmcnt(1)
	v_mfma_f32_32x32x16_bf16 v[66:81], v[130:133], v[98:101], v[66:81]
	v_lshl_add_u64 v[130:131], v[152:153], 0, s[2:3]
	v_lshl_add_u64 v[132:133], v[150:151], 0, s[2:3]
	global_load_dwordx4 v[142:145], v[132:133], off
	global_load_dwordx4 v[138:141], v[138:139], off
	s_waitcnt lgkmcnt(0)
	v_mfma_f32_32x32x16_bf16 v[66:81], v[134:137], v[102:105], v[66:81]
	global_load_dwordx4 v[134:137], v[130:131], off offset:-16
	global_load_dwordx4 v[130:133], v[130:131], off
	v_mfma_f32_32x32x16_bf16 v[82:97], v[158:161], v[102:105], v[82:97]
	s_nop 7
	s_nop 2
	s_nop 0
	v_max_f32_e32 v146, v83, v67
	v_max_f32_e32 v147, v84, v68
	v_max3_f32 v146, v82, v66, v146
	v_max_f32_e32 v154, v85, v69
	v_max3_f32 v146, v146, v147, v154
	v_max_f32_e32 v147, v86, v70
	v_max_f32_e32 v154, v87, v71
	v_max3_f32 v146, v146, v147, v154
	v_max_f32_e32 v147, v88, v72
	v_max_f32_e32 v154, v89, v73
	v_max3_f32 v146, v146, v147, v154
	v_max_f32_e32 v147, v90, v74
	v_max_f32_e32 v154, v91, v75
	v_max3_f32 v146, v146, v147, v154
	v_max_f32_e32 v147, v92, v76
	v_max_f32_e32 v154, v93, v77
	v_max3_f32 v146, v146, v147, v154
	v_max_f32_e32 v147, v94, v78
	v_max_f32_e32 v154, v95, v79
	v_max3_f32 v146, v146, v147, v154
	v_max_f32_e32 v147, v96, v80
	v_max_f32_e32 v157, v97, v97
	v_max_f32_e32 v154, v157, v81
	v_max3_f32 v146, v146, v147, v154
	v_mov_b32_e32 v147, v146
	s_nop 1
	v_permlane32_swap_b32_e32 v146, v147
	v_max3_f32 v147, v0, v146, v147
	v_sub_f32_e32 v0, v0, v147
	v_mul_f32_e32 v0, 0x3e0293ee, v0
	v_exp_f32_e32 v154, v0
	s_nop 0
	v_cmp_eq_f32_e32 vcc, 1.0, v154
	s_cmp_eq_u64 vcc, exec
	s_cbranch_scc1 .LBB0_810
	v_pk_mul_f32 v[64:65], v[64:65], v[154:155] op_sel_hi:[1,0]
	v_pk_mul_f32 v[62:63], v[62:63], v[154:155] op_sel_hi:[1,0]
	v_pk_mul_f32 v[60:61], v[60:61], v[154:155] op_sel_hi:[1,0]
	v_pk_mul_f32 v[58:59], v[58:59], v[154:155] op_sel_hi:[1,0]
	v_pk_mul_f32 v[56:57], v[56:57], v[154:155] op_sel_hi:[1,0]
	v_pk_mul_f32 v[54:55], v[54:55], v[154:155] op_sel_hi:[1,0]
	v_pk_mul_f32 v[52:53], v[52:53], v[154:155] op_sel_hi:[1,0]
	v_pk_mul_f32 v[50:51], v[50:51], v[154:155] op_sel_hi:[1,0]
	v_pk_mul_f32 v[48:49], v[48:49], v[154:155] op_sel_hi:[1,0]
	v_pk_mul_f32 v[46:47], v[46:47], v[154:155] op_sel_hi:[1,0]
	v_pk_mul_f32 v[44:45], v[44:45], v[154:155] op_sel_hi:[1,0]
	v_pk_mul_f32 v[42:43], v[42:43], v[154:155] op_sel_hi:[1,0]
	v_pk_mul_f32 v[40:41], v[40:41], v[154:155] op_sel_hi:[1,0]
	v_pk_mul_f32 v[38:39], v[38:39], v[154:155] op_sel_hi:[1,0]
	v_pk_mul_f32 v[36:37], v[36:37], v[154:155] op_sel_hi:[1,0]
	v_pk_mul_f32 v[34:35], v[34:35], v[154:155] op_sel_hi:[1,0]
	v_pk_mul_f32 v[32:33], v[32:33], v[154:155] op_sel_hi:[1,0]
	v_pk_mul_f32 v[30:31], v[30:31], v[154:155] op_sel_hi:[1,0]
	v_pk_mul_f32 v[28:29], v[28:29], v[154:155] op_sel_hi:[1,0]
	v_pk_mul_f32 v[26:27], v[26:27], v[154:155] op_sel_hi:[1,0]
	v_pk_mul_f32 v[24:25], v[24:25], v[154:155] op_sel_hi:[1,0]
	v_pk_mul_f32 v[22:23], v[22:23], v[154:155] op_sel_hi:[1,0]
	v_pk_mul_f32 v[20:21], v[20:21], v[154:155] op_sel_hi:[1,0]
	v_pk_mul_f32 v[18:19], v[18:19], v[154:155] op_sel_hi:[1,0]
	v_pk_mul_f32 v[16:17], v[16:17], v[154:155] op_sel_hi:[1,0]
	v_pk_mul_f32 v[14:15], v[14:15], v[154:155] op_sel_hi:[1,0]
	v_pk_mul_f32 v[12:13], v[12:13], v[154:155] op_sel_hi:[1,0]
	v_pk_mul_f32 v[10:11], v[10:11], v[154:155] op_sel_hi:[1,0]
	v_pk_mul_f32 v[8:9], v[8:9], v[154:155] op_sel_hi:[1,0]
	v_pk_mul_f32 v[6:7], v[6:7], v[154:155] op_sel_hi:[1,0]
	v_pk_mul_f32 v[4:5], v[4:5], v[154:155] op_sel_hi:[1,0]
	v_pk_mul_f32 v[2:3], v[2:3], v[154:155] op_sel_hi:[1,0]

.LBB0_847:
	s_load_dwordx2 s[66:67], s[96:97], 0x0
	s_waitcnt lgkmcnt(0)
	s_add_u32 s59, s66, s88
	s_addc_u32 s65, s67, s89
	s_add_i32 s66, s46, 63
	s_lshr_b32 s66, s66, 6
	v_cvt_f32_u32_e32 v2, s66
	s_sub_i32 s79, 0, s66
	s_abs_i32 s78, s58
	s_ashr_i32 s67, s58, 31
	v_rcp_iflag_f32_e32 v2, v2
	s_nop 0
	v_mul_f32_e32 v2, 0x4f7ffffe, v2
	v_cvt_u32_f32_e32 v2, v2
	s_nop 0
	v_readfirstlane_b32 s80, v2
	s_mul_i32 s79, s79, s80
	s_mul_hi_u32 s79, s80, s79
	s_add_i32 s80, s80, s79
	s_mul_hi_u32 s79, s78, s80
	s_mul_i32 s80, s79, s66
	s_sub_i32 s78, s78, s80
	s_add_i32 s81, s79, 1
	s_sub_i32 s80, s78, s66
	s_cmp_ge_u32 s78, s66
	s_cselect_b32 s79, s81, s79
	s_cselect_b32 s78, s80, s78
	s_add_i32 s80, s79, 1
	s_cmp_ge_u32 s78, s66
	s_cselect_b32 s78, s80, s79
	s_xor_b32 s78, s78, s67
	s_sub_i32 s67, s78, s67
	s_mul_i32 s66, s67, s66
	s_lshl_b32 s88, s67, 6
	s_sub_i32 s58, s58, s66
	s_ashr_i32 s89, s88, 31
	s_mul_hi_u32 s67, s88, s46
	s_lshl_b32 s58, s58, 6
	s_mul_i32 s78, s89, s46
	s_mul_i32 s66, s88, s46
	v_or_b32_e32 v2, s58, v166
	s_add_i32 s67, s67, s78
	s_lshl_b64 s[66:67], s[66:67], 2
	v_cmp_gt_i32_e32 vcc, s46, v2
	s_add_u32 s66, s59, s66
	s_addc_u32 s67, s65, s67
	v_cndmask_b32_e32 v2, 0, v2, vcc
	v_ashrrev_i32_e32 v3, 31, v2
	v_lshl_add_u64 v[2:3], v[2:3], 2, s[66:67]
	s_lshl_b32 s66, s46, 1
	s_mov_b32 s67, s47
	v_lshl_add_u64 v[6:7], s[66:67], 2, v[2:3]
	s_mul_i32 s66, s46, 3
	v_lshl_add_u64 v[18:19], s[66:67], 2, v[2:3]
	s_lshl_b32 s66, s46, 2
	v_lshl_add_u64 v[20:21], s[66:67], 2, v[2:3]
	s_mul_i32 s66, s46, 5
	v_lshl_add_u64 v[22:23], s[66:67], 2, v[2:3]
	s_mul_i32 s66, s46, 6
	v_lshl_add_u64 v[24:25], s[66:67], 2, v[2:3]
	s_mul_i32 s66, s46, 7
	v_lshl_add_u64 v[4:5], s[46:47], 2, v[2:3]
	v_lshl_add_u64 v[26:27], s[66:67], 2, v[2:3]
	s_lshl_b32 s66, s46, 3
	global_load_dword v30, v[2:3], off nt
	global_load_dword v31, v[4:5], off nt
	global_load_dword v32, v[6:7], off nt
	global_load_dword v33, v[18:19], off nt
	global_load_dword v34, v[20:21], off nt
	global_load_dword v35, v[22:23], off nt
	global_load_dword v36, v[24:25], off nt
	global_load_dword v37, v[26:27], off nt
	v_lshl_add_u64 v[4:5], s[66:67], 2, v[2:3]
	s_mul_i32 s66, s46, 9
	v_lshl_add_u64 v[6:7], s[66:67], 2, v[2:3]
	s_mul_i32 s66, s46, 10
	v_lshl_add_u64 v[18:19], s[66:67], 2, v[2:3]
	s_mul_i32 s66, s46, 11
	v_lshl_add_u64 v[20:21], s[66:67], 2, v[2:3]
	s_mul_i32 s66, s46, 12
	v_lshl_add_u64 v[22:23], s[66:67], 2, v[2:3]
	s_mul_i32 s66, s46, 13
	v_lshl_add_u64 v[24:25], s[66:67], 2, v[2:3]
	s_mul_i32 s66, s46, 14
	v_lshl_add_u64 v[26:27], s[66:67], 2, v[2:3]
	s_mul_i32 s66, s46, 15
	v_lshl_add_u64 v[28:29], s[66:67], 2, v[2:3]
	s_lshl_b32 s66, s46, 4
	global_load_dword v38, v[4:5], off nt
	global_load_dword v39, v[6:7], off nt
	global_load_dword v40, v[18:19], off nt
	global_load_dword v41, v[20:21], off nt
	global_load_dword v42, v[22:23], off nt
	global_load_dword v43, v[24:25], off nt
	global_load_dword v44, v[26:27], off nt
	global_load_dword v45, v[28:29], off nt
	v_lshl_add_u64 v[4:5], s[66:67], 2, v[2:3]
	s_mul_i32 s66, s46, 17
	v_lshl_add_u64 v[6:7], s[66:67], 2, v[2:3]
	s_mul_i32 s66, s46, 18
	v_lshl_add_u64 v[18:19], s[66:67], 2, v[2:3]
	s_mul_i32 s66, s46, 19
	v_lshl_add_u64 v[20:21], s[66:67], 2, v[2:3]
	s_mul_i32 s66, s46, 20
	v_lshl_add_u64 v[22:23], s[66:67], 2, v[2:3]
	s_mul_i32 s66, s46, 21
	v_lshl_add_u64 v[24:25], s[66:67], 2, v[2:3]
	s_mul_i32 s66, s46, 22
	v_lshl_add_u64 v[26:27], s[66:67], 2, v[2:3]
	s_mul_i32 s66, s46, 23
	v_lshl_add_u64 v[28:29], s[66:67], 2, v[2:3]
	s_mul_i32 s66, s46, 24
	global_load_dword v46, v[4:5], off nt
	global_load_dword v47, v[6:7], off nt
	global_load_dword v48, v[18:19], off nt
	global_load_dword v49, v[20:21], off nt
	global_load_dword v50, v[22:23], off nt
	global_load_dword v51, v[24:25], off nt
	global_load_dword v52, v[26:27], off nt
	global_load_dword v53, v[28:29], off nt
	v_lshl_add_u64 v[4:5], s[66:67], 2, v[2:3]
	s_mul_i32 s66, s46, 25
	v_lshl_add_u64 v[6:7], s[66:67], 2, v[2:3]
	s_mul_i32 s66, s46, 26
	v_lshl_add_u64 v[18:19], s[66:67], 2, v[2:3]
	s_mul_i32 s66, s46, 27
	v_lshl_add_u64 v[20:21], s[66:67], 2, v[2:3]
	s_mul_i32 s66, s46, 28
	v_lshl_add_u64 v[22:23], s[66:67], 2, v[2:3]
	s_mul_i32 s66, s46, 29
	v_lshl_add_u64 v[24:25], s[66:67], 2, v[2:3]
	s_mul_i32 s66, s46, 30
	v_lshl_add_u64 v[26:27], s[66:67], 2, v[2:3]
	s_mul_i32 s66, s46, 31
	v_lshl_add_u64 v[28:29], s[66:67], 2, v[2:3]
	s_lshl_b32 s66, s46, 5
	global_load_dword v54, v[4:5], off nt
	global_load_dword v55, v[6:7], off nt
	global_load_dword v56, v[18:19], off nt
	global_load_dword v57, v[20:21], off nt
	global_load_dword v58, v[22:23], off nt
	global_load_dword v59, v[24:25], off nt
	global_load_dword v60, v[26:27], off nt
	global_load_dword v61, v[28:29], off nt
	v_lshl_add_u64 v[4:5], s[66:67], 2, v[2:3]
	s_mul_i32 s66, s46, 33
	v_lshl_add_u64 v[6:7], s[66:67], 2, v[2:3]
	s_mul_i32 s66, s46, 34
	v_lshl_add_u64 v[18:19], s[66:67], 2, v[2:3]
	s_mul_i32 s66, s46, 35
	v_lshl_add_u64 v[20:21], s[66:67], 2, v[2:3]
	s_mul_i32 s66, s46, 36
	v_lshl_add_u64 v[22:23], s[66:67], 2, v[2:3]
	s_mul_i32 s66, s46, 37
	v_lshl_add_u64 v[24:25], s[66:67], 2, v[2:3]
	s_mul_i32 s66, s46, 38
	v_lshl_add_u64 v[26:27], s[66:67], 2, v[2:3]
	s_mul_i32 s66, s46, 39
	v_lshl_add_u64 v[28:29], s[66:67], 2, v[2:3]
	s_mul_i32 s66, s46, 40
	global_load_dword v62, v[4:5], off nt
	global_load_dword v63, v[6:7], off nt
	global_load_dword v64, v[18:19], off nt
	global_load_dword v65, v[20:21], off nt
	global_load_dword v66, v[22:23], off nt
	global_load_dword v67, v[24:25], off nt
	global_load_dword v68, v[26:27], off nt
	global_load_dword v69, v[28:29], off nt
	v_lshl_add_u64 v[4:5], s[66:67], 2, v[2:3]
	s_mul_i32 s66, s46, 41
	v_lshl_add_u64 v[6:7], s[66:67], 2, v[2:3]
	s_mul_i32 s66, s46, 42
	v_lshl_add_u64 v[18:19], s[66:67], 2, v[2:3]
	s_mul_i32 s66, s46, 43
	v_lshl_add_u64 v[20:21], s[66:67], 2, v[2:3]
	s_mul_i32 s66, s46, 44
	v_lshl_add_u64 v[22:23], s[66:67], 2, v[2:3]
	s_mul_i32 s66, s46, 45
	v_lshl_add_u64 v[24:25], s[66:67], 2, v[2:3]
	s_mul_i32 s66, s46, 46
	v_lshl_add_u64 v[26:27], s[66:67], 2, v[2:3]
	s_mul_i32 s66, s46, 47
	v_lshl_add_u64 v[28:29], s[66:67], 2, v[2:3]
	s_mul_i32 s66, s46, 48
	global_load_dword v70, v[4:5], off nt
	global_load_dword v71, v[6:7], off nt
	global_load_dword v72, v[18:19], off nt
	global_load_dword v73, v[20:21], off nt
	global_load_dword v74, v[22:23], off nt
	global_load_dword v75, v[24:25], off nt
	global_load_dword v76, v[26:27], off nt
	global_load_dword v77, v[28:29], off nt
	v_lshl_add_u64 v[4:5], s[66:67], 2, v[2:3]
	s_mul_i32 s66, s46, 49
	v_lshl_add_u64 v[6:7], s[66:67], 2, v[2:3]
	s_mul_i32 s66, s46, 50
	v_lshl_add_u64 v[18:19], s[66:67], 2, v[2:3]
	s_mul_i32 s66, s46, 51
	v_lshl_add_u64 v[20:21], s[66:67], 2, v[2:3]
	s_mul_i32 s66, s46, 52
	v_lshl_add_u64 v[22:23], s[66:67], 2, v[2:3]
	s_mul_i32 s66, s46, 53
	v_lshl_add_u64 v[24:25], s[66:67], 2, v[2:3]
	s_mul_i32 s66, s46, 54
	v_lshl_add_u64 v[26:27], s[66:67], 2, v[2:3]
	s_mul_i32 s66, s46, 55
	v_lshl_add_u64 v[28:29], s[66:67], 2, v[2:3]
	s_mul_i32 s66, s46, 56
	global_load_dword v78, v[4:5], off nt
	global_load_dword v79, v[6:7], off nt
	global_load_dword v80, v[18:19], off nt
	global_load_dword v81, v[20:21], off nt
	global_load_dword v82, v[22:23], off nt
	global_load_dword v83, v[24:25], off nt
	global_load_dword v84, v[26:27], off nt
	global_load_dword v28, v[28:29], off nt
	v_lshl_add_u64 v[4:5], s[66:67], 2, v[2:3]
	s_mul_i32 s66, s46, 57
	v_lshl_add_u64 v[6:7], s[66:67], 2, v[2:3]
	s_mul_i32 s66, s46, 58
	v_lshl_add_u64 v[18:19], s[66:67], 2, v[2:3]
	s_mul_i32 s66, s46, 59
	v_lshl_add_u64 v[20:21], s[66:67], 2, v[2:3]
	s_mul_i32 s66, s46, 60
	v_lshl_add_u64 v[22:23], s[66:67], 2, v[2:3]
	s_mul_i32 s66, s46, 61
	v_lshl_add_u64 v[24:25], s[66:67], 2, v[2:3]
	s_mul_i32 s66, s46, 62
	v_lshl_add_u64 v[26:27], s[66:67], 2, v[2:3]
	s_mul_i32 s66, s46, 63
	v_lshl_add_u64 v[2:3], s[66:67], 2, v[2:3]
	global_load_dword v29, v[4:5], off nt
	global_load_dword v6, v[6:7], off nt
	global_load_dword v7, v[18:19], off nt
	global_load_dword v18, v[20:21], off nt
	global_load_dword v19, v[22:23], off nt
	global_load_dword v20, v[24:25], off nt
	global_load_dword v21, v[26:27], off nt
	global_load_dword v22, v[2:3], off nt
	s_waitcnt vmcnt(0)
	v_cvt_pk_bf16_f32 v2, v30, v31
	v_cvt_pk_bf16_f32 v3, v32, v33
	v_cvt_pk_bf16_f32 v4, v34, v35
	v_cvt_pk_bf16_f32 v5, v36, v37
	ds_write_b128 v16, v[2:5]
	v_cvt_pk_bf16_f32 v2, v38, v39
	v_cvt_pk_bf16_f32 v3, v40, v41
	v_cvt_pk_bf16_f32 v4, v42, v43
	v_cvt_pk_bf16_f32 v5, v44, v45
	ds_write_b128 v16, v[2:5] offset:16
	v_cvt_pk_bf16_f32 v2, v46, v47
	v_cvt_pk_bf16_f32 v3, v48, v49
	v_cvt_pk_bf16_f32 v4, v50, v51
	v_cvt_pk_bf16_f32 v5, v52, v53
	ds_write_b128 v16, v[2:5] offset:32
	v_cvt_pk_bf16_f32 v2, v54, v55
	v_cvt_pk_bf16_f32 v3, v56, v57
	v_cvt_pk_bf16_f32 v4, v58, v59
	v_cvt_pk_bf16_f32 v5, v60, v61
	ds_write_b128 v16, v[2:5] offset:48
	s_and_b64 s[66:67], s[8:9], s[74:75]
	s_or_b64 s[70:71], s[8:9], s[70:71]
	s_and_b64 s[70:71], s[70:71], exec
	v_cvt_pk_bf16_f32 v2, v62, v63
	s_cselect_b32 s59, 0, 2
	v_cvt_pk_bf16_f32 v3, v64, v65
	s_and_b64 s[66:67], s[66:67], exec
	v_cvt_pk_bf16_f32 v4, v66, v67
	s_cselect_b32 s59, 1, s59
	v_cvt_pk_bf16_f32 v5, v68, v69
	ds_write_b128 v16, v[2:5] offset:64
	s_cmp_gt_i32 s59, 1
	s_mov_b64 s[70:71], -1
	v_cvt_pk_bf16_f32 v2, v70, v71
	v_cvt_pk_bf16_f32 v3, v72, v73
	v_cvt_pk_bf16_f32 v4, v74, v75
	v_cvt_pk_bf16_f32 v5, v76, v77
	ds_write_b128 v16, v[2:5] offset:80
	v_cvt_pk_bf16_f32 v2, v78, v79
	v_cvt_pk_bf16_f32 v3, v80, v81
	v_cvt_pk_bf16_f32 v4, v82, v83
	v_cvt_pk_bf16_f32 v5, v84, v28
	ds_write_b128 v16, v[2:5] offset:96
	v_cvt_pk_bf16_f32 v2, v29, v6
	v_cvt_pk_bf16_f32 v3, v7, v18
	v_or_b32_e32 v18, s58, v8
	v_cvt_pk_bf16_f32 v4, v19, v20
	v_cvt_pk_bf16_f32 v5, v21, v22
	ds_write_b128 v16, v[2:5] offset:112
	ds_read_b128 v[2:5], v17
	s_cbranch_scc0 .LBB0_849
	v_cmp_gt_i32_e32 vcc, s93, v18
	s_mov_b64 s[70:71], 0
	s_nop 0
	v_cndmask_b32_e32 v6, v237, v238, vcc
	v_cmp_lt_i32_e32 vcc, s48, v18
	s_nop 1
	v_cndmask_b32_e32 v6, 0, v6, vcc
	v_add_u32_e32 v19, v6, v18

.LBB0_983:
	v_lshl_add_u64 v[126:127], v[176:177], 2, s[8:9]
	global_load_dwordx4 v[130:133], v[126:127], off offset:16
	global_load_dwordx4 v[134:137], v[126:127], off
	global_load_dwordx4 v[122:125], v[126:127], off offset:528
	global_load_dwordx4 v[126:129], v[126:127], off offset:512
	v_readlane_b32 s26, v254, 46
	v_readlane_b32 s27, v254, 47
	s_and_b64 vcc, exec, s[26:27]
	s_mov_b64 s[26:27], -1
	s_cbranch_vccnz .LBB0_985
	v_lshl_add_u64 v[148:149], v[176:177], 2, s[2:3]
	v_lshlrev_b64 v[146:147], 13, v[150:151]
	v_lshl_add_u64 v[146:147], v[148:149], 0, v[146:147]
	global_load_dwordx4 v[152:155], v[146:147], off offset:16
	global_load_dwordx4 v[156:159], v[146:147], off
	global_load_dwordx4 v[160:163], v[146:147], off offset:528
	global_load_dwordx4 v[178:181], v[146:147], off offset:512
	v_lshlrev_b64 v[146:147], 12, v[150:151]
	s_mov_b64 s[26:27], 0
	s_waitcnt vmcnt(0)
	v_pk_fma_f32 v[164:165], v[140:141], v[132:133], v[154:155]
	v_pk_fma_f32 v[156:157], v[142:143], v[134:135], v[156:157]
	v_pk_fma_f32 v[158:159], v[144:145], v[136:137], v[158:159]
	v_pk_fma_f32 v[154:155], v[138:139], v[130:131], v[152:153]
	v_cvt_pk_bf16_f32 v152, v156, v157
	v_lshl_add_u64 v[156:157], s[0:1], 0, v[146:147]
	v_lshlrev_b64 v[146:147], 1, v[176:177]
	v_cvt_pk_bf16_f32 v153, v158, v159
	v_cvt_pk_bf16_f32 v154, v154, v155
	v_cvt_pk_bf16_f32 v155, v164, v165
	v_lshl_add_u64 v[156:157], v[156:157], 0, v[146:147]
	global_store_dwordx4 v[156:157], v[152:155], off
	v_pk_fma_f32 v[158:159], v[108:109], v[124:125], v[162:163]
	v_pk_fma_f32 v[160:161], v[106:107], v[122:123], v[160:161]
	v_pk_fma_f32 v[154:155], v[116:117], v[128:129], v[180:181]
	v_pk_fma_f32 v[152:153], v[114:115], v[126:127], v[178:179]
	v_or_b32_e32 v164, 16, v150
	v_cvt_pk_bf16_f32 v152, v152, v153
	v_cvt_pk_bf16_f32 v153, v154, v155
	v_cvt_pk_bf16_f32 v154, v160, v161
	v_cvt_pk_bf16_f32 v155, v158, v159
	v_ashrrev_i32_e32 v165, 31, v164
	global_store_dwordx4 v[156:157], v[152:155], off offset:256
	s_nop 1
	v_lshlrev_b64 v[152:153], 13, v[164:165]
	v_lshl_add_u64 v[178:179], v[148:149], 0, v[152:153]
	global_load_dwordx4 v[152:155], v[178:179], off offset:16
	global_load_dwordx4 v[156:159], v[178:179], off
	global_load_dwordx4 v[160:163], v[178:179], off offset:528
	global_load_dwordx4 v[178:181], v[178:179], off offset:512
	v_lshlrev_b64 v[164:165], 12, v[164:165]
	s_waitcnt vmcnt(3)
	v_pk_fma_f32 v[182:183], v[112:113], v[132:133], v[154:155]
	s_waitcnt vmcnt(2)
	v_pk_fma_f32 v[156:157], v[118:119], v[134:135], v[156:157]
	v_pk_fma_f32 v[158:159], v[120:121], v[136:137], v[158:159]
	v_pk_fma_f32 v[154:155], v[110:111], v[130:131], v[152:153]
	v_cvt_pk_bf16_f32 v152, v156, v157
	v_lshl_add_u64 v[156:157], s[0:1], 0, v[164:165]
	v_cvt_pk_bf16_f32 v153, v158, v159
	v_cvt_pk_bf16_f32 v154, v154, v155
	v_cvt_pk_bf16_f32 v155, v182, v183
	v_lshl_add_u64 v[156:157], v[156:157], 0, v[146:147]
	global_store_dwordx4 v[156:157], v[152:155], off
	s_waitcnt vmcnt(2)
	v_pk_fma_f32 v[158:159], v[96:97], v[124:125], v[162:163]
	v_pk_fma_f32 v[160:161], v[94:95], v[122:123], v[160:161]
	s_waitcnt vmcnt(1)
	v_pk_fma_f32 v[154:155], v[104:105], v[128:129], v[180:181]
	v_pk_fma_f32 v[152:153], v[102:103], v[126:127], v[178:179]
	v_or_b32_e32 v164, 32, v150
	v_cvt_pk_bf16_f32 v152, v152, v153
	v_cvt_pk_bf16_f32 v153, v154, v155
	v_cvt_pk_bf16_f32 v154, v160, v161
	v_cvt_pk_bf16_f32 v155, v158, v159
	v_ashrrev_i32_e32 v165, 31, v164
	global_store_dwordx4 v[156:157], v[152:155], off offset:256
	s_nop 1
	v_lshlrev_b64 v[152:153], 13, v[164:165]
	v_lshl_add_u64 v[178:179], v[148:149], 0, v[152:153]
	global_load_dwordx4 v[152:155], v[178:179], off offset:16
	global_load_dwordx4 v[156:159], v[178:179], off
	global_load_dwordx4 v[160:163], v[178:179], off offset:528
	global_load_dwordx4 v[178:181], v[178:179], off offset:512
	v_lshlrev_b64 v[164:165], 12, v[164:165]
	s_waitcnt vmcnt(3)
	v_pk_fma_f32 v[182:183], v[92:93], v[132:133], v[154:155]
	s_waitcnt vmcnt(2)
	v_pk_fma_f32 v[156:157], v[98:99], v[134:135], v[156:157]
	v_pk_fma_f32 v[158:159], v[100:101], v[136:137], v[158:159]
	v_pk_fma_f32 v[154:155], v[90:91], v[130:131], v[152:153]
	v_cvt_pk_bf16_f32 v152, v156, v157
	v_lshl_add_u64 v[156:157], s[0:1], 0, v[164:165]
	v_cvt_pk_bf16_f32 v153, v158, v159
	v_cvt_pk_bf16_f32 v154, v154, v155
	v_cvt_pk_bf16_f32 v155, v182, v183
	v_lshl_add_u64 v[156:157], v[156:157], 0, v[146:147]
	global_store_dwordx4 v[156:157], v[152:155], off
	s_waitcnt vmcnt(2)
	v_pk_fma_f32 v[158:159], v[80:81], v[124:125], v[162:163]
	v_pk_fma_f32 v[160:161], v[78:79], v[122:123], v[160:161]
	s_waitcnt vmcnt(1)
	v_pk_fma_f32 v[154:155], v[88:89], v[128:129], v[180:181]
	v_pk_fma_f32 v[152:153], v[86:87], v[126:127], v[178:179]
	v_or_b32_e32 v164, 48, v150
	v_cvt_pk_bf16_f32 v152, v152, v153
	v_cvt_pk_bf16_f32 v153, v154, v155
	v_cvt_pk_bf16_f32 v154, v160, v161
	v_cvt_pk_bf16_f32 v155, v158, v159
	v_ashrrev_i32_e32 v165, 31, v164
	global_store_dwordx4 v[156:157], v[152:155], off offset:256
	s_nop 1
	v_lshlrev_b64 v[152:153], 13, v[164:165]
	v_lshl_add_u64 v[178:179], v[148:149], 0, v[152:153]
	global_load_dwordx4 v[152:155], v[178:179], off offset:16
	global_load_dwordx4 v[156:159], v[178:179], off
	global_load_dwordx4 v[160:163], v[178:179], off offset:528
	global_load_dwordx4 v[178:181], v[178:179], off offset:512
	v_lshlrev_b64 v[164:165], 12, v[164:165]
	s_waitcnt vmcnt(3)
	v_pk_fma_f32 v[182:183], v[76:77], v[132:133], v[154:155]
	s_waitcnt vmcnt(2)
	v_pk_fma_f32 v[156:157], v[82:83], v[134:135], v[156:157]
	v_pk_fma_f32 v[158:159], v[84:85], v[136:137], v[158:159]
	v_pk_fma_f32 v[154:155], v[74:75], v[130:131], v[152:153]
	v_cvt_pk_bf16_f32 v152, v156, v157
	v_lshl_add_u64 v[156:157], s[0:1], 0, v[164:165]
	v_cvt_pk_bf16_f32 v153, v158, v159
	v_cvt_pk_bf16_f32 v154, v154, v155
	v_cvt_pk_bf16_f32 v155, v182, v183
	v_lshl_add_u64 v[156:157], v[156:157], 0, v[146:147]
	global_store_dwordx4 v[156:157], v[152:155], off
	s_waitcnt vmcnt(2)
	v_pk_fma_f32 v[158:159], v[68:69], v[124:125], v[162:163]
	v_pk_fma_f32 v[160:161], v[66:67], v[122:123], v[160:161]
	s_waitcnt vmcnt(1)
	v_pk_fma_f32 v[154:155], v[72:73], v[128:129], v[180:181]
	v_pk_fma_f32 v[152:153], v[70:71], v[126:127], v[178:179]
	v_add_u32_e32 v164, 0x80, v150
	v_cvt_pk_bf16_f32 v152, v152, v153
	v_cvt_pk_bf16_f32 v153, v154, v155
	v_cvt_pk_bf16_f32 v154, v160, v161
	v_cvt_pk_bf16_f32 v155, v158, v159
	v_ashrrev_i32_e32 v165, 31, v164
	global_store_dwordx4 v[156:157], v[152:155], off offset:256
	s_nop 1
	v_lshlrev_b64 v[152:153], 13, v[164:165]
	v_lshl_add_u64 v[178:179], v[148:149], 0, v[152:153]
	global_load_dwordx4 v[152:155], v[178:179], off offset:16
	global_load_dwordx4 v[156:159], v[178:179], off
	global_load_dwordx4 v[160:163], v[178:179], off offset:528
	global_load_dwordx4 v[178:181], v[178:179], off offset:512
	v_lshlrev_b64 v[164:165], 12, v[164:165]
	s_waitcnt vmcnt(3)
	v_pk_fma_f32 v[182:183], v[60:61], v[132:133], v[154:155]
	s_waitcnt vmcnt(2)
	v_pk_fma_f32 v[156:157], v[62:63], v[134:135], v[156:157]
	v_pk_fma_f32 v[158:159], v[64:65], v[136:137], v[158:159]
	v_pk_fma_f32 v[154:155], v[58:59], v[130:131], v[152:153]
	v_cvt_pk_bf16_f32 v152, v156, v157
	v_lshl_add_u64 v[156:157], s[0:1], 0, v[164:165]
	v_cvt_pk_bf16_f32 v153, v158, v159
	v_cvt_pk_bf16_f32 v154, v154, v155
	v_cvt_pk_bf16_f32 v155, v182, v183
	v_lshl_add_u64 v[156:157], v[156:157], 0, v[146:147]
	global_store_dwordx4 v[156:157], v[152:155], off
	s_waitcnt vmcnt(2)
	v_pk_fma_f32 v[158:159], v[48:49], v[124:125], v[162:163]
	v_pk_fma_f32 v[160:161], v[46:47], v[122:123], v[160:161]
	s_waitcnt vmcnt(1)
	v_pk_fma_f32 v[154:155], v[56:57], v[128:129], v[180:181]
	v_pk_fma_f32 v[152:153], v[54:55], v[126:127], v[178:179]
	v_add_u32_e32 v164, 0x90, v150
	v_cvt_pk_bf16_f32 v152, v152, v153
	v_cvt_pk_bf16_f32 v153, v154, v155
	v_cvt_pk_bf16_f32 v154, v160, v161
	v_cvt_pk_bf16_f32 v155, v158, v159
	v_ashrrev_i32_e32 v165, 31, v164
	global_store_dwordx4 v[156:157], v[152:155], off offset:256
	s_nop 1
	v_lshlrev_b64 v[152:153], 13, v[164:165]
	v_lshl_add_u64 v[178:179], v[148:149], 0, v[152:153]
	global_load_dwordx4 v[152:155], v[178:179], off offset:16
	global_load_dwordx4 v[156:159], v[178:179], off
	global_load_dwordx4 v[160:163], v[178:179], off offset:528
	global_load_dwordx4 v[178:181], v[178:179], off offset:512
	v_lshlrev_b64 v[164:165], 12, v[164:165]
	s_waitcnt vmcnt(3)
	v_pk_fma_f32 v[182:183], v[44:45], v[132:133], v[154:155]
	s_waitcnt vmcnt(2)
	v_pk_fma_f32 v[156:157], v[50:51], v[134:135], v[156:157]
	v_pk_fma_f32 v[158:159], v[52:53], v[136:137], v[158:159]
	v_pk_fma_f32 v[154:155], v[42:43], v[130:131], v[152:153]
	v_cvt_pk_bf16_f32 v152, v156, v157
	v_lshl_add_u64 v[156:157], s[0:1], 0, v[164:165]
	v_cvt_pk_bf16_f32 v153, v158, v159
	v_cvt_pk_bf16_f32 v154, v154, v155
	v_cvt_pk_bf16_f32 v155, v182, v183
	v_lshl_add_u64 v[156:157], v[156:157], 0, v[146:147]
	global_store_dwordx4 v[156:157], v[152:155], off
	s_waitcnt vmcnt(2)
	v_pk_fma_f32 v[158:159], v[32:33], v[124:125], v[162:163]
	v_pk_fma_f32 v[160:161], v[30:31], v[122:123], v[160:161]
	s_waitcnt vmcnt(1)
	v_pk_fma_f32 v[154:155], v[40:41], v[128:129], v[180:181]
	v_pk_fma_f32 v[152:153], v[38:39], v[126:127], v[178:179]
	v_add_u32_e32 v164, 0xa0, v150
	v_cvt_pk_bf16_f32 v152, v152, v153
	v_cvt_pk_bf16_f32 v153, v154, v155
	v_cvt_pk_bf16_f32 v154, v160, v161
	v_cvt_pk_bf16_f32 v155, v158, v159
	v_ashrrev_i32_e32 v165, 31, v164
	global_store_dwordx4 v[156:157], v[152:155], off offset:256
	s_nop 1
	v_lshlrev_b64 v[152:153], 13, v[164:165]
	v_lshl_add_u64 v[178:179], v[148:149], 0, v[152:153]
	global_load_dwordx4 v[152:155], v[178:179], off offset:16
	global_load_dwordx4 v[156:159], v[178:179], off
	global_load_dwordx4 v[160:163], v[178:179], off offset:528
	global_load_dwordx4 v[178:181], v[178:179], off offset:512
	v_lshlrev_b64 v[164:165], 12, v[164:165]
	s_waitcnt vmcnt(3)
	v_pk_fma_f32 v[182:183], v[28:29], v[132:133], v[154:155]
	s_waitcnt vmcnt(2)
	v_pk_fma_f32 v[156:157], v[34:35], v[134:135], v[156:157]
	v_pk_fma_f32 v[158:159], v[36:37], v[136:137], v[158:159]
	v_pk_fma_f32 v[154:155], v[26:27], v[130:131], v[152:153]
	v_cvt_pk_bf16_f32 v152, v156, v157
	v_lshl_add_u64 v[156:157], s[0:1], 0, v[164:165]
	v_cvt_pk_bf16_f32 v153, v158, v159
	v_cvt_pk_bf16_f32 v154, v154, v155
	v_cvt_pk_bf16_f32 v155, v182, v183
	v_lshl_add_u64 v[156:157], v[156:157], 0, v[146:147]
	global_store_dwordx4 v[156:157], v[152:155], off
	s_waitcnt vmcnt(2)
	v_pk_fma_f32 v[158:159], v[16:17], v[124:125], v[162:163]
	v_pk_fma_f32 v[160:161], v[14:15], v[122:123], v[160:161]
	s_waitcnt vmcnt(1)
	v_pk_fma_f32 v[154:155], v[24:25], v[128:129], v[180:181]
	v_pk_fma_f32 v[152:153], v[22:23], v[126:127], v[178:179]
	s_nop 0
	v_cvt_pk_bf16_f32 v152, v152, v153
	v_cvt_pk_bf16_f32 v153, v154, v155
	v_cvt_pk_bf16_f32 v154, v160, v161
	v_cvt_pk_bf16_f32 v155, v158, v159
	global_store_dwordx4 v[156:157], v[152:155], off offset:256
	s_nop 1
	v_add_u32_e32 v152, 0xb0, v150
	v_ashrrev_i32_e32 v153, 31, v152
	v_lshlrev_b64 v[154:155], 13, v[152:153]
	v_lshl_add_u64 v[148:149], v[148:149], 0, v[154:155]
	global_load_dwordx4 v[154:157], v[148:149], off offset:16
	global_load_dwordx4 v[158:161], v[148:149], off
	global_load_dwordx4 v[162:165], v[148:149], off offset:528
	global_load_dwordx4 v[178:181], v[148:149], off offset:512
	v_lshlrev_b64 v[152:153], 12, v[152:153]
	s_waitcnt vmcnt(2)
	v_pk_fma_f32 v[148:149], v[20:21], v[136:137], v[160:161]
	v_pk_fma_f32 v[158:159], v[18:19], v[134:135], v[158:159]
	v_pk_fma_f32 v[160:161], v[12:13], v[132:133], v[156:157]
	v_pk_fma_f32 v[156:157], v[10:11], v[130:131], v[154:155]
	v_cvt_pk_bf16_f32 v155, v148, v149
	v_lshl_add_u64 v[148:149], s[0:1], 0, v[152:153]
	v_cvt_pk_bf16_f32 v154, v158, v159
	v_cvt_pk_bf16_f32 v156, v156, v157
	v_cvt_pk_bf16_f32 v157, v160, v161
	v_lshl_add_u64 v[146:147], v[148:149], 0, v[146:147]
	global_store_dwordx4 v[146:147], v[154:157], off
	s_waitcnt vmcnt(1)
	v_pk_fma_f32 v[148:149], v[8:9], v[128:129], v[180:181]
	v_pk_fma_f32 v[146:147], v[6:7], v[126:127], v[178:179]
	v_pk_fma_f32 v[156:157], v[2:3], v[122:123], v[162:163]
	v_pk_fma_f32 v[154:155], v[4:5], v[124:125], v[164:165]
	v_cvt_pk_bf16_f32 v146, v146, v147
	v_cvt_pk_bf16_f32 v147, v148, v149
	v_cvt_pk_bf16_f32 v148, v156, v157
.LBB0_985:
	s_andn2_b64 vcc, exec, s[26:27]
	s_cbranch_vccnz .LBB0_987
	v_lshlrev_b64 v[178:179], 1, v[176:177]
	v_lshl_add_u64 v[180:181], s[2:3], 0, v[178:179]
	v_lshlrev_b64 v[182:183], 12, v[150:151]
	v_lshl_add_u64 v[146:147], v[180:181], 0, v[182:183]
	global_load_dwordx4 v[206:209], v[146:147], off
	global_load_dwordx4 v[210:213], v[146:147], off offset:256
	v_or_b32_e32 v146, 16, v150
	v_ashrrev_i32_e32 v147, 31, v146
	v_lshlrev_b64 v[188:189], 12, v[146:147]
	v_lshl_add_u64 v[146:147], v[180:181], 0, v[188:189]
	global_load_dwordx4 v[214:217], v[146:147], off
	global_load_dwordx4 v[162:165], v[146:147], off offset:256
	v_or_b32_e32 v146, 32, v150
	v_ashrrev_i32_e32 v147, 31, v146
	v_lshlrev_b64 v[186:187], 12, v[146:147]
	v_lshl_add_u64 v[146:147], v[180:181], 0, v[186:187]
	global_load_dwordx4 v[158:161], v[146:147], off
	global_load_dwordx4 v[154:157], v[146:147], off offset:256
	v_or_b32_e32 v146, 48, v150
	v_ashrrev_i32_e32 v147, 31, v146
	v_lshlrev_b64 v[184:185], 12, v[146:147]
	v_lshl_add_u64 v[146:147], v[180:181], 0, v[184:185]
	global_load_dwordx4 v[150:153], v[146:147], off
	global_load_dwordx4 v[146:149], v[146:147], off offset:256
	s_mov_b64 s[26:27], 0x80000
	s_waitcnt vmcnt(0)
	v_lshlrev_b32_e32 v218, 16, v206
	v_and_b32_e32 v219, 0xffff0000, v206
	v_lshlrev_b32_e32 v206, 16, v207
	v_and_b32_e32 v207, 0xffff0000, v207
	v_pk_fma_f32 v[144:145], v[144:145], v[136:137], v[206:207]
	v_lshlrev_b32_e32 v206, 16, v208
	v_and_b32_e32 v207, 0xffff0000, v208
	v_pk_fma_f32 v[142:143], v[142:143], v[134:135], v[218:219]
	v_pk_fma_f32 v[206:207], v[138:139], v[130:131], v[206:207]
	v_lshlrev_b32_e32 v138, 16, v209
	v_and_b32_e32 v139, 0xffff0000, v209
	v_pk_fma_f32 v[208:209], v[140:141], v[132:133], v[138:139]
	v_cvt_pk_bf16_f32 v138, v142, v143
	v_lshl_add_u64 v[142:143], s[0:1], 0, v[182:183]
	v_cvt_pk_bf16_f32 v139, v144, v145
	v_cvt_pk_bf16_f32 v140, v206, v207
	v_cvt_pk_bf16_f32 v141, v208, v209
	v_lshl_add_u64 v[142:143], v[142:143], 0, v[178:179]
	global_store_dwordx4 v[142:143], v[138:141], off
	s_nop 1
	v_lshlrev_b32_e32 v138, 16, v210
	v_and_b32_e32 v139, 0xffff0000, v210
	v_pk_fma_f32 v[114:115], v[114:115], v[126:127], v[138:139]
	v_lshlrev_b32_e32 v138, 16, v211
	v_and_b32_e32 v139, 0xffff0000, v211
	v_pk_fma_f32 v[116:117], v[116:117], v[128:129], v[138:139]
	v_lshlrev_b32_e32 v138, 16, v212
	v_and_b32_e32 v139, 0xffff0000, v212
	v_pk_fma_f32 v[138:139], v[106:107], v[122:123], v[138:139]
	v_lshlrev_b32_e32 v106, 16, v213
	v_and_b32_e32 v107, 0xffff0000, v213
	v_pk_fma_f32 v[140:141], v[108:109], v[124:125], v[106:107]
	v_cvt_pk_bf16_f32 v106, v114, v115
	v_cvt_pk_bf16_f32 v107, v116, v117
	v_cvt_pk_bf16_f32 v108, v138, v139
	v_cvt_pk_bf16_f32 v109, v140, v141
	global_store_dwordx4 v[142:143], v[106:109], off offset:256
	s_nop 1
	v_lshlrev_b32_e32 v108, 16, v215
	v_and_b32_e32 v109, 0xffff0000, v215
	v_lshlrev_b32_e32 v106, 16, v214
	v_and_b32_e32 v107, 0xffff0000, v214
	v_pk_fma_f32 v[114:115], v[120:121], v[136:137], v[108:109]
	v_lshlrev_b32_e32 v108, 16, v216
	v_and_b32_e32 v109, 0xffff0000, v216
	v_pk_fma_f32 v[106:107], v[118:119], v[134:135], v[106:107]
	v_pk_fma_f32 v[110:111], v[110:111], v[130:131], v[108:109]
	v_lshlrev_b32_e32 v108, 16, v217
	v_and_b32_e32 v109, 0xffff0000, v217
	v_pk_fma_f32 v[112:113], v[112:113], v[132:133], v[108:109]
	v_cvt_pk_bf16_f32 v108, v106, v107
	v_lshl_add_u64 v[106:107], s[0:1], 0, v[188:189]
	v_cvt_pk_bf16_f32 v109, v114, v115
	v_cvt_pk_bf16_f32 v110, v110, v111
	v_cvt_pk_bf16_f32 v111, v112, v113
	v_lshl_add_u64 v[106:107], v[106:107], 0, v[178:179]
	global_store_dwordx4 v[106:107], v[108:111], off
	s_nop 1
	v_lshlrev_b32_e32 v108, 16, v162
	v_and_b32_e32 v109, 0xffff0000, v162
	v_pk_fma_f32 v[102:103], v[102:103], v[126:127], v[108:109]
	v_lshlrev_b32_e32 v108, 16, v163
	v_and_b32_e32 v109, 0xffff0000, v163
	v_pk_fma_f32 v[104:105], v[104:105], v[128:129], v[108:109]
	v_lshlrev_b32_e32 v108, 16, v164
	v_and_b32_e32 v109, 0xffff0000, v164
	v_pk_fma_f32 v[108:109], v[94:95], v[122:123], v[108:109]
	v_lshlrev_b32_e32 v94, 16, v165
	v_and_b32_e32 v95, 0xffff0000, v165
	v_pk_fma_f32 v[110:111], v[96:97], v[124:125], v[94:95]
	v_cvt_pk_bf16_f32 v94, v102, v103
	v_cvt_pk_bf16_f32 v95, v104, v105
	v_cvt_pk_bf16_f32 v96, v108, v109
	v_cvt_pk_bf16_f32 v97, v110, v111
	global_store_dwordx4 v[106:107], v[94:97], off offset:256
	s_nop 1
	v_lshlrev_b32_e32 v94, 16, v158
	v_and_b32_e32 v95, 0xffff0000, v158
	v_pk_fma_f32 v[94:95], v[98:99], v[134:135], v[94:95]
	v_lshlrev_b32_e32 v98, 16, v160
	v_and_b32_e32 v99, 0xffff0000, v160
	v_lshlrev_b32_e32 v96, 16, v159
	v_and_b32_e32 v97, 0xffff0000, v159
	v_pk_fma_f32 v[98:99], v[90:91], v[130:131], v[98:99]
	v_lshlrev_b32_e32 v90, 16, v161
	v_and_b32_e32 v91, 0xffff0000, v161
	v_pk_fma_f32 v[96:97], v[100:101], v[136:137], v[96:97]
	v_pk_fma_f32 v[100:101], v[92:93], v[132:133], v[90:91]
	v_cvt_pk_bf16_f32 v90, v94, v95
	v_lshl_add_u64 v[94:95], s[0:1], 0, v[186:187]
	v_cvt_pk_bf16_f32 v91, v96, v97
	v_cvt_pk_bf16_f32 v92, v98, v99
	v_cvt_pk_bf16_f32 v93, v100, v101
	v_lshl_add_u64 v[94:95], v[94:95], 0, v[178:179]
	global_store_dwordx4 v[94:95], v[90:93], off
	v_lshl_add_u64 v[98:99], v[182:183], 0, s[26:27]
	s_mov_b64 s[26:27], 0x90000
	v_lshlrev_b32_e32 v90, 16, v154
	v_and_b32_e32 v91, 0xffff0000, v154
	v_pk_fma_f32 v[86:87], v[86:87], v[126:127], v[90:91]
	v_lshlrev_b32_e32 v90, 16, v155
	v_and_b32_e32 v91, 0xffff0000, v155
	v_pk_fma_f32 v[88:89], v[88:89], v[128:129], v[90:91]
	v_lshlrev_b32_e32 v90, 16, v156
	v_and_b32_e32 v91, 0xffff0000, v156
	v_pk_fma_f32 v[90:91], v[78:79], v[122:123], v[90:91]
	v_lshlrev_b32_e32 v78, 16, v157
	v_and_b32_e32 v79, 0xffff0000, v157
	v_pk_fma_f32 v[92:93], v[80:81], v[124:125], v[78:79]
	v_cvt_pk_bf16_f32 v78, v86, v87
	v_cvt_pk_bf16_f32 v79, v88, v89
	v_cvt_pk_bf16_f32 v80, v90, v91
	v_cvt_pk_bf16_f32 v81, v92, v93
	global_store_dwordx4 v[94:95], v[78:81], off offset:256
	v_lshl_add_u64 v[100:101], v[182:183], 0, s[26:27]
	s_mov_b64 s[26:27], 0xa0000
	v_lshlrev_b32_e32 v78, 16, v150
	v_and_b32_e32 v79, 0xffff0000, v150
	v_pk_fma_f32 v[78:79], v[82:83], v[134:135], v[78:79]
	v_lshlrev_b32_e32 v82, 16, v152
	v_and_b32_e32 v83, 0xffff0000, v152
	v_lshlrev_b32_e32 v80, 16, v151
	v_and_b32_e32 v81, 0xffff0000, v151
	v_pk_fma_f32 v[82:83], v[74:75], v[130:131], v[82:83]
	v_lshlrev_b32_e32 v74, 16, v153
	v_and_b32_e32 v75, 0xffff0000, v153
	v_pk_fma_f32 v[80:81], v[84:85], v[136:137], v[80:81]
	v_pk_fma_f32 v[84:85], v[76:77], v[132:133], v[74:75]
	v_cvt_pk_bf16_f32 v74, v78, v79
	v_lshl_add_u64 v[78:79], s[0:1], 0, v[184:185]
	v_cvt_pk_bf16_f32 v75, v80, v81
	v_cvt_pk_bf16_f32 v76, v82, v83
	v_cvt_pk_bf16_f32 v77, v84, v85
	v_lshl_add_u64 v[78:79], v[78:79], 0, v[178:179]
	global_store_dwordx4 v[78:79], v[74:77], off
	v_lshl_add_u64 v[102:103], v[182:183], 0, s[26:27]
	s_mov_b64 s[26:27], 0xb0000
	v_lshlrev_b32_e32 v74, 16, v146
	v_and_b32_e32 v75, 0xffff0000, v146
	v_pk_fma_f32 v[70:71], v[70:71], v[126:127], v[74:75]
	v_lshlrev_b32_e32 v74, 16, v147
	v_and_b32_e32 v75, 0xffff0000, v147
	v_pk_fma_f32 v[72:73], v[72:73], v[128:129], v[74:75]
	v_lshlrev_b32_e32 v74, 16, v148
	v_and_b32_e32 v75, 0xffff0000, v148
	v_pk_fma_f32 v[74:75], v[66:67], v[122:123], v[74:75]
	v_lshlrev_b32_e32 v66, 16, v149
	v_and_b32_e32 v67, 0xffff0000, v149
	v_pk_fma_f32 v[76:77], v[68:69], v[124:125], v[66:67]
	v_cvt_pk_bf16_f32 v66, v70, v71
	v_cvt_pk_bf16_f32 v67, v72, v73
	v_cvt_pk_bf16_f32 v68, v74, v75
	v_cvt_pk_bf16_f32 v69, v76, v77
	global_store_dwordx4 v[78:79], v[66:69], off offset:256
	v_lshl_add_u64 v[152:153], v[182:183], 0, s[26:27]
	s_nop 0
	v_lshl_add_u64 v[66:67], v[180:181], 0, v[98:99]
	global_load_dwordx4 v[70:73], v[66:67], off
	global_load_dwordx4 v[74:77], v[66:67], off offset:256
	v_lshl_add_u64 v[66:67], v[180:181], 0, v[100:101]
	global_load_dwordx4 v[78:81], v[66:67], off
	global_load_dwordx4 v[82:85], v[66:67], off offset:256
	v_lshl_add_u64 v[66:67], v[180:181], 0, v[102:103]
	global_load_dwordx4 v[86:89], v[66:67], off
	global_load_dwordx4 v[90:93], v[66:67], off offset:256
	v_lshl_add_u64 v[66:67], v[180:181], 0, v[152:153]
	global_load_dwordx4 v[94:97], v[66:67], off
	global_load_dwordx4 v[66:69], v[66:67], off offset:256
	s_waitcnt vmcnt(7)
	v_lshlrev_b32_e32 v104, 16, v70
	v_and_b32_e32 v105, 0xffff0000, v70
	v_lshlrev_b32_e32 v70, 16, v71
	v_and_b32_e32 v71, 0xffff0000, v71
	v_pk_fma_f32 v[64:65], v[64:65], v[136:137], v[70:71]
	v_lshlrev_b32_e32 v70, 16, v72
	v_and_b32_e32 v71, 0xffff0000, v72
	v_pk_fma_f32 v[62:63], v[62:63], v[134:135], v[104:105]
	v_pk_fma_f32 v[70:71], v[58:59], v[130:131], v[70:71]
	v_lshlrev_b32_e32 v58, 16, v73
	v_and_b32_e32 v59, 0xffff0000, v73
	v_pk_fma_f32 v[72:73], v[60:61], v[132:133], v[58:59]
	v_cvt_pk_bf16_f32 v58, v62, v63
	v_lshl_add_u64 v[62:63], s[0:1], 0, v[98:99]
	v_cvt_pk_bf16_f32 v59, v64, v65
	v_cvt_pk_bf16_f32 v60, v70, v71
	v_cvt_pk_bf16_f32 v61, v72, v73
	v_lshl_add_u64 v[62:63], v[62:63], 0, v[178:179]
	global_store_dwordx4 v[62:63], v[58:61], off
	s_waitcnt vmcnt(7)
	s_nop 0
	v_lshlrev_b32_e32 v58, 16, v74
	v_and_b32_e32 v59, 0xffff0000, v74
	v_pk_fma_f32 v[54:55], v[54:55], v[126:127], v[58:59]
	v_lshlrev_b32_e32 v58, 16, v75
	v_and_b32_e32 v59, 0xffff0000, v75
	v_pk_fma_f32 v[56:57], v[56:57], v[128:129], v[58:59]
	v_lshlrev_b32_e32 v58, 16, v76
	v_and_b32_e32 v59, 0xffff0000, v76
	v_pk_fma_f32 v[58:59], v[46:47], v[122:123], v[58:59]
	v_lshlrev_b32_e32 v46, 16, v77
	v_and_b32_e32 v47, 0xffff0000, v77
	v_pk_fma_f32 v[60:61], v[48:49], v[124:125], v[46:47]
	v_cvt_pk_bf16_f32 v46, v54, v55
	v_cvt_pk_bf16_f32 v47, v56, v57
	v_cvt_pk_bf16_f32 v48, v58, v59
	v_cvt_pk_bf16_f32 v49, v60, v61
	global_store_dwordx4 v[62:63], v[46:49], off offset:256
	s_waitcnt vmcnt(7)
	s_nop 0
	v_lshlrev_b32_e32 v46, 16, v78
	v_and_b32_e32 v47, 0xffff0000, v78
	v_pk_fma_f32 v[46:47], v[50:51], v[134:135], v[46:47]
	v_lshlrev_b32_e32 v50, 16, v80
	v_and_b32_e32 v51, 0xffff0000, v80
	v_lshlrev_b32_e32 v48, 16, v79
	v_and_b32_e32 v49, 0xffff0000, v79
	v_pk_fma_f32 v[50:51], v[42:43], v[130:131], v[50:51]
	v_lshlrev_b32_e32 v42, 16, v81
	v_and_b32_e32 v43, 0xffff0000, v81
	v_pk_fma_f32 v[48:49], v[52:53], v[136:137], v[48:49]
	v_pk_fma_f32 v[52:53], v[44:45], v[132:133], v[42:43]
	v_cvt_pk_bf16_f32 v42, v46, v47
	v_lshl_add_u64 v[46:47], s[0:1], 0, v[100:101]
	v_cvt_pk_bf16_f32 v43, v48, v49
	v_cvt_pk_bf16_f32 v44, v50, v51
	v_cvt_pk_bf16_f32 v45, v52, v53
	v_lshl_add_u64 v[46:47], v[46:47], 0, v[178:179]
	global_store_dwordx4 v[46:47], v[42:45], off
	s_waitcnt vmcnt(7)
	s_nop 0
	v_lshlrev_b32_e32 v42, 16, v82
	v_and_b32_e32 v43, 0xffff0000, v82
	v_pk_fma_f32 v[38:39], v[38:39], v[126:127], v[42:43]
	v_lshlrev_b32_e32 v42, 16, v83
	v_and_b32_e32 v43, 0xffff0000, v83
	v_pk_fma_f32 v[40:41], v[40:41], v[128:129], v[42:43]
	v_lshlrev_b32_e32 v42, 16, v84
	v_and_b32_e32 v43, 0xffff0000, v84
	v_pk_fma_f32 v[42:43], v[30:31], v[122:123], v[42:43]
	v_lshlrev_b32_e32 v30, 16, v85
	v_and_b32_e32 v31, 0xffff0000, v85
	v_pk_fma_f32 v[44:45], v[32:33], v[124:125], v[30:31]
	v_cvt_pk_bf16_f32 v30, v38, v39
	v_cvt_pk_bf16_f32 v31, v40, v41
	v_cvt_pk_bf16_f32 v32, v42, v43
	v_cvt_pk_bf16_f32 v33, v44, v45
	global_store_dwordx4 v[46:47], v[30:33], off offset:256
	s_waitcnt vmcnt(7)
	s_nop 0
	v_lshlrev_b32_e32 v30, 16, v86
	v_and_b32_e32 v31, 0xffff0000, v86
	v_pk_fma_f32 v[30:31], v[34:35], v[134:135], v[30:31]
	v_lshlrev_b32_e32 v34, 16, v88
	v_and_b32_e32 v35, 0xffff0000, v88
	v_lshlrev_b32_e32 v32, 16, v87
	v_and_b32_e32 v33, 0xffff0000, v87
	v_pk_fma_f32 v[34:35], v[26:27], v[130:131], v[34:35]
	v_lshlrev_b32_e32 v26, 16, v89
	v_and_b32_e32 v27, 0xffff0000, v89
	v_pk_fma_f32 v[32:33], v[36:37], v[136:137], v[32:33]
	v_pk_fma_f32 v[36:37], v[28:29], v[132:133], v[26:27]
	v_cvt_pk_bf16_f32 v26, v30, v31
	v_lshl_add_u64 v[30:31], s[0:1], 0, v[102:103]
	v_cvt_pk_bf16_f32 v27, v32, v33
	v_cvt_pk_bf16_f32 v28, v34, v35
	v_cvt_pk_bf16_f32 v29, v36, v37
	v_lshl_add_u64 v[30:31], v[30:31], 0, v[178:179]
	global_store_dwordx4 v[30:31], v[26:29], off
	s_waitcnt vmcnt(7)
	s_nop 0
	v_lshlrev_b32_e32 v26, 16, v90
	v_and_b32_e32 v27, 0xffff0000, v90
	v_pk_fma_f32 v[22:23], v[22:23], v[126:127], v[26:27]
	v_lshlrev_b32_e32 v26, 16, v91
	v_and_b32_e32 v27, 0xffff0000, v91
	v_pk_fma_f32 v[24:25], v[24:25], v[128:129], v[26:27]
	v_lshlrev_b32_e32 v26, 16, v92
	v_and_b32_e32 v27, 0xffff0000, v92
	v_pk_fma_f32 v[26:27], v[14:15], v[122:123], v[26:27]
	v_lshlrev_b32_e32 v14, 16, v93
	v_and_b32_e32 v15, 0xffff0000, v93
	v_pk_fma_f32 v[28:29], v[16:17], v[124:125], v[14:15]
	v_cvt_pk_bf16_f32 v14, v22, v23
	v_cvt_pk_bf16_f32 v15, v24, v25
	v_cvt_pk_bf16_f32 v16, v26, v27
	v_cvt_pk_bf16_f32 v17, v28, v29
	global_store_dwordx4 v[30:31], v[14:17], off offset:256
	s_waitcnt vmcnt(7)
	s_nop 0
	v_lshlrev_b32_e32 v14, 16, v94
	v_and_b32_e32 v15, 0xffff0000, v94
	v_pk_fma_f32 v[14:15], v[18:19], v[134:135], v[14:15]
	v_lshlrev_b32_e32 v18, 16, v96
	v_and_b32_e32 v19, 0xffff0000, v96
	v_lshlrev_b32_e32 v16, 16, v95
	v_and_b32_e32 v17, 0xffff0000, v95
	v_pk_fma_f32 v[18:19], v[10:11], v[130:131], v[18:19]
	v_lshlrev_b32_e32 v10, 16, v97
	v_and_b32_e32 v11, 0xffff0000, v97
	v_pk_fma_f32 v[16:17], v[20:21], v[136:137], v[16:17]
	v_pk_fma_f32 v[20:21], v[12:13], v[132:133], v[10:11]
	v_cvt_pk_bf16_f32 v10, v14, v15
	v_lshl_add_u64 v[14:15], s[0:1], 0, v[152:153]
	v_cvt_pk_bf16_f32 v11, v16, v17
	v_cvt_pk_bf16_f32 v12, v18, v19
	v_cvt_pk_bf16_f32 v13, v20, v21
	v_lshl_add_u64 v[14:15], v[14:15], 0, v[178:179]
	global_store_dwordx4 v[14:15], v[10:13], off
	s_waitcnt vmcnt(7)
	s_nop 0
	v_lshlrev_b32_e32 v10, 16, v66
	v_and_b32_e32 v11, 0xffff0000, v66
	v_pk_fma_f32 v[6:7], v[6:7], v[126:127], v[10:11]
	v_lshlrev_b32_e32 v10, 16, v67
	v_and_b32_e32 v11, 0xffff0000, v67
	v_pk_fma_f32 v[8:9], v[8:9], v[128:129], v[10:11]
	v_lshlrev_b32_e32 v10, 16, v68
	v_and_b32_e32 v11, 0xffff0000, v68
	v_pk_fma_f32 v[2:3], v[2:3], v[122:123], v[10:11]
	v_lshlrev_b32_e32 v10, 16, v69
	v_and_b32_e32 v11, 0xffff0000, v69
	v_pk_fma_f32 v[154:155], v[4:5], v[124:125], v[10:11]
	v_cvt_pk_bf16_f32 v146, v6, v7
	v_cvt_pk_bf16_f32 v147, v8, v9
	v_cvt_pk_bf16_f32 v148, v2, v3

.LBB0_1030:
	s_cmpk_gt_i32 s2, 0x1fff
	s_cselect_b64 s[10:11], -1, 0
	s_add_i32 s46, s2, 0xffffe000
	s_cmpk_lt_i32 s2, 0x2000
	s_cselect_b64 s[4:5], -1, 0
	v_readlane_b32 s12, v254, 44
	s_and_b64 s[8:9], s[4:5], exec
	v_readlane_b32 s13, v254, 45
	s_cselect_b32 s8, s2, s46
	s_or_b64 s[18:19], s[12:13], s[4:5]
	s_ashr_i32 s9, s8, 31
	s_mov_b64 s[12:13], -1
	s_and_b64 vcc, exec, s[18:19]
	s_cbranch_vccnz .LBB0_1032
	s_lshl_b64 s[12:13], s[8:9], 13
	v_lshl_add_u64 v[2:3], v[138:139], 0, s[12:13]
	s_mov_b64 s[12:13], 0x1000
	global_load_dwordx4 v[26:29], v[2:3], off offset:16
	global_load_dwordx4 v[30:33], v[2:3], off
	global_load_dwordx4 v[18:21], v[2:3], off offset:2064
	global_load_dwordx4 v[22:25], v[2:3], off offset:2048
	v_lshl_add_u64 v[4:5], v[2:3], 0, s[12:13]
	v_add_co_u32_e32 v6, vcc, 0x1000, v2
	s_mov_b64 s[12:13], 0x1800
	s_nop 0
	v_addc_co_u32_e32 v7, vcc, 0, v3, vcc
	v_lshl_add_u64 v[2:3], v[2:3], 0, s[12:13]
	global_load_dwordx4 v[14:17], v[6:7], off
	global_load_dwordx4 v[10:13], v[4:5], off offset:16
	global_load_dwordx4 v[6:9], v[6:7], off offset:2048
	global_load_dwordx4 v[2:5], v[2:3], off offset:16
	s_mov_b64 s[12:13], 0

.LBB0_1034:
	s_ashr_i32 s3, s8, 10
	s_add_i32 s3, s3, 1
	s_and_b64 s[4:5], s[4:5], exec
	s_cselect_b32 s3, 0, s3
	v_cndmask_b32_e64 v34, 0, 1, s[10:11]
	s_mul_hi_i32 s9, s3, 0x3000
	v_cmp_ne_u32_e64 s[4:5], 1, v34
	s_andn2_b64 vcc, exec, s[10:11]
	s_mul_i32 s8, s3, 0x3000
	s_cbranch_vccnz .LBB0_1036
	s_lshl_b64 s[10:11], s[46:47], 12
	v_lshl_add_u64 v[34:35], v[140:141], 0, s[10:11]
	s_mov_b32 s3, 0x800000
	v_add_co_u32_e32 v46, vcc, s3, v34
	s_mov_b32 s3, 0x1000000
	s_nop 0
	v_addc_co_u32_e32 v47, vcc, 0, v35, vcc
	v_add_co_u32_e32 v50, vcc, s3, v34
	s_mov_b32 s3, 0x1800000
	s_nop 0
	v_addc_co_u32_e32 v51, vcc, 0, v35, vcc
	v_add_co_u32_e32 v52, vcc, s3, v34
	global_load_dwordx4 v[82:85], v[34:35], off nt
	global_load_dwordx4 v[86:89], v[46:47], off nt
	v_addc_co_u32_e32 v53, vcc, 0, v35, vcc
	global_load_dwordx4 v[90:93], v[50:51], off nt
	global_load_dwordx4 v[94:97], v[52:53], off nt
	s_lshl_b64 s[10:11], s[8:9], 2
	s_add_u32 s10, s14, s10
	s_addc_u32 s11, s15, s11
	global_load_dwordx4 v[98:101], v0, s[10:11]
	global_load_dwordx4 v[102:105], v0, s[10:11] offset:16
	global_load_dwordx4 v[106:109], v[46:47], off offset:1024 nt
	global_load_dwordx4 v[110:113], v[34:35], off offset:1024 nt
	global_load_dwordx4 v[114:117], v[50:51], off offset:1024 nt
	global_load_dwordx4 v[118:121], v[52:53], off offset:1024 nt
	global_load_dwordx4 v[66:69], v[34:35], off offset:2048 nt
	global_load_dwordx4 v[42:45], v[34:35], off offset:3072 nt
	global_load_dwordx4 v[122:125], v0, s[10:11] offset:2064
	global_load_dwordx4 v[126:129], v0, s[10:11] offset:2048
	global_load_dwordx4 v[58:61], v147, s[10:11] offset:16
	global_load_dwordx4 v[62:65], v147, s[10:11]
	global_load_dwordx4 v[34:37], v148, s[10:11] offset:16
	global_load_dwordx4 v[38:41], v148, s[10:11]
	global_load_dwordx4 v[70:73], v[46:47], off offset:2048 nt
	global_load_dwordx4 v[46:49], v[46:47], off offset:3072 nt
	global_load_dwordx4 v[78:81], v[50:51], off offset:2048 nt
	global_load_dwordx4 v[54:57], v[50:51], off offset:3072 nt
	global_load_dwordx4 v[74:77], v[52:53], off offset:2048 nt
	global_load_dwordx4 v[50:53], v[52:53], off offset:3072 nt
	s_waitcnt vmcnt(0)
	v_lshlrev_b32_e32 v149, 16, v82
	v_lshlrev_b32_e32 v151, 16, v83
	v_and_b32_e32 v150, 0xffff0000, v83
	v_lshlrev_b32_e32 v153, 16, v84
	v_lshlrev_b32_e32 v155, 16, v85
	v_and_b32_e32 v152, 0xffff0000, v85
	v_lshlrev_b32_e32 v83, 16, v86
	v_lshlrev_b32_e32 v85, 16, v87
	v_and_b32_e32 v154, 0xffff0000, v87
	v_lshlrev_b32_e32 v87, 16, v88
	v_and_b32_e32 v82, 0xffff0000, v82
	v_and_b32_e32 v86, 0xffff0000, v86
	v_lshlrev_b32_e32 v157, 16, v89
	v_add_f32_e32 v158, v83, v149
	v_and_b32_e32 v83, 0xffff0000, v90
	v_add_f32_e32 v160, v87, v153
	v_and_b32_e32 v87, 0xffff0000, v94
	v_lshlrev_b32_e32 v149, 16, v90
	v_add_f32_e32 v90, v85, v151
	v_lshlrev_b32_e32 v159, 16, v91
	v_and_b32_e32 v151, 0xffff0000, v91
	v_lshlrev_b32_e32 v91, 16, v92
	v_and_b32_e32 v85, 0xffff0000, v92
	v_add_f32_e32 v92, v157, v155
	v_lshlrev_b32_e32 v161, 16, v93
	v_and_b32_e32 v153, 0xffff0000, v93
	v_lshlrev_b32_e32 v93, 16, v94
	v_lshlrev_b32_e32 v162, 16, v95
	v_and_b32_e32 v155, 0xffff0000, v95
	v_lshlrev_b32_e32 v95, 16, v96
	v_pk_add_f32 v[82:83], v[82:83], v[86:87]
	v_and_b32_e32 v84, 0xffff0000, v84
	v_and_b32_e32 v88, 0xffff0000, v88
	v_and_b32_e32 v156, 0xffff0000, v89
	v_and_b32_e32 v89, 0xffff0000, v96
	v_lshlrev_b32_e32 v163, 16, v97
	v_and_b32_e32 v157, 0xffff0000, v97
	v_add_f32_e32 v94, v93, v149
	v_add_f32_e32 v86, v162, v159
	v_pk_add_f32 v[96:97], v[150:151], v[154:155]
	v_add_f32_e32 v150, v95, v91
	v_mov_b32_e32 v159, v82
	v_mov_b32_e32 v95, v83
	v_pk_add_f32 v[84:85], v[84:85], v[88:89]
	v_pk_add_f32 v[82:83], v[158:159], v[94:95]
	v_mov_b32_e32 v91, v96
	v_mov_b32_e32 v87, v97
	v_add_f32_e32 v88, v163, v161
	v_pk_add_f32 v[152:153], v[152:153], v[156:157]
	v_pk_fma_f32 v[30:31], v[98:99], v[82:83], v[30:31]
	v_pk_add_f32 v[82:83], v[90:91], v[86:87]
	v_mov_b32_e32 v161, v84
	v_mov_b32_e32 v151, v85
	v_pk_fma_f32 v[32:33], v[100:101], v[82:83], v[32:33]
	v_pk_add_f32 v[82:83], v[160:161], v[150:151]
	v_mov_b32_e32 v93, v152
	v_mov_b32_e32 v89, v153
	v_pk_fma_f32 v[26:27], v[102:103], v[82:83], v[26:27]
	v_pk_add_f32 v[82:83], v[92:93], v[88:89]
	v_lshlrev_b32_e32 v84, 16, v118
	v_pk_fma_f32 v[28:29], v[104:105], v[82:83], v[28:29]
	v_lshlrev_b32_e32 v82, 16, v106
	v_lshlrev_b32_e32 v83, 16, v110
	v_add_f32_e32 v82, v82, v83
	v_lshlrev_b32_e32 v83, 16, v114
	v_add_f32_e32 v84, v84, v83
	v_and_b32_e32 v87, 0xffff0000, v114
	v_and_b32_e32 v86, 0xffff0000, v110
	v_and_b32_e32 v89, 0xffff0000, v118
	v_and_b32_e32 v88, 0xffff0000, v106
	v_lshlrev_b32_e32 v83, 16, v107
	v_lshlrev_b32_e32 v85, 16, v111
	v_pk_add_f32 v[86:87], v[86:87], v[88:89]
	v_add_f32_e32 v88, v83, v85
	v_lshlrev_b32_e32 v83, 16, v115
	v_lshlrev_b32_e32 v85, 16, v119
	v_add_f32_e32 v90, v85, v83
	v_and_b32_e32 v93, 0xffff0000, v115
	v_and_b32_e32 v92, 0xffff0000, v111
	v_and_b32_e32 v95, 0xffff0000, v119
	v_and_b32_e32 v94, 0xffff0000, v107
	v_lshlrev_b32_e32 v83, 16, v108
	v_lshlrev_b32_e32 v85, 16, v112
	v_pk_add_f32 v[92:93], v[92:93], v[94:95]
	v_add_f32_e32 v94, v83, v85
	v_lshlrev_b32_e32 v83, 16, v116
	v_lshlrev_b32_e32 v85, 16, v120
	v_add_f32_e32 v96, v85, v83
	v_and_b32_e32 v99, 0xffff0000, v116
	v_and_b32_e32 v98, 0xffff0000, v112
	v_and_b32_e32 v101, 0xffff0000, v120
	v_and_b32_e32 v100, 0xffff0000, v108
	v_lshlrev_b32_e32 v83, 16, v109
	v_lshlrev_b32_e32 v85, 16, v113
	v_pk_add_f32 v[98:99], v[98:99], v[100:101]
	v_add_f32_e32 v100, v83, v85
	v_lshlrev_b32_e32 v83, 16, v117
	v_lshlrev_b32_e32 v85, 16, v121
	v_add_f32_e32 v102, v85, v83
	v_mov_b32_e32 v83, v86
	v_mov_b32_e32 v85, v87
	v_and_b32_e32 v105, 0xffff0000, v117
	v_and_b32_e32 v104, 0xffff0000, v113
	v_and_b32_e32 v107, 0xffff0000, v121
	v_and_b32_e32 v106, 0xffff0000, v109
	v_pk_add_f32 v[82:83], v[82:83], v[84:85]
	v_mov_b32_e32 v89, v92
	v_mov_b32_e32 v91, v93
	v_pk_add_f32 v[104:105], v[104:105], v[106:107]
	v_pk_fma_f32 v[22:23], v[126:127], v[82:83], v[22:23]
	v_pk_add_f32 v[82:83], v[88:89], v[90:91]
	v_mov_b32_e32 v95, v98
	v_mov_b32_e32 v97, v99
	v_pk_fma_f32 v[24:25], v[128:129], v[82:83], v[24:25]
	v_pk_add_f32 v[82:83], v[94:95], v[96:97]
	v_mov_b32_e32 v101, v104
	v_mov_b32_e32 v103, v105
	v_pk_fma_f32 v[18:19], v[122:123], v[82:83], v[18:19]
	v_pk_add_f32 v[82:83], v[100:101], v[102:103]
	v_and_b32_e32 v86, 0xffff0000, v66
	v_pk_fma_f32 v[20:21], v[124:125], v[82:83], v[20:21]
	v_lshlrev_b32_e32 v82, 16, v70
	v_lshlrev_b32_e32 v83, 16, v66
	v_and_b32_e32 v88, 0xffff0000, v70
	v_lshlrev_b32_e32 v66, 16, v71
	v_lshlrev_b32_e32 v70, 16, v67
	v_lshlrev_b32_e32 v84, 16, v74
	v_and_b32_e32 v89, 0xffff0000, v74
	v_add_f32_e32 v66, v66, v70
	v_lshlrev_b32_e32 v70, 16, v79
	v_lshlrev_b32_e32 v74, 16, v75
	v_add_f32_e32 v82, v82, v83
	v_lshlrev_b32_e32 v83, 16, v78
	v_and_b32_e32 v87, 0xffff0000, v78
	v_add_f32_e32 v70, v74, v70
	v_and_b32_e32 v79, 0xffff0000, v79
	v_and_b32_e32 v78, 0xffff0000, v67
	v_and_b32_e32 v75, 0xffff0000, v75
	v_and_b32_e32 v74, 0xffff0000, v71
	v_lshlrev_b32_e32 v67, 16, v72
	v_lshlrev_b32_e32 v71, 16, v68
	v_pk_add_f32 v[74:75], v[78:79], v[74:75]
	v_add_f32_e32 v78, v67, v71
	v_lshlrev_b32_e32 v67, 16, v80
	v_lshlrev_b32_e32 v71, 16, v76
	v_pk_add_f32 v[86:87], v[86:87], v[88:89]
	v_add_f32_e32 v88, v71, v67
	v_and_b32_e32 v90, 0xffff0000, v68
	v_lshlrev_b32_e32 v67, 16, v73
	v_lshlrev_b32_e32 v68, 16, v69
	v_add_f32_e32 v84, v84, v83
	v_and_b32_e32 v91, 0xffff0000, v80
	v_and_b32_e32 v93, 0xffff0000, v76
	v_and_b32_e32 v92, 0xffff0000, v72
	v_add_f32_e32 v68, v67, v68
	v_lshlrev_b32_e32 v67, 16, v81
	v_lshlrev_b32_e32 v71, 16, v77
	v_and_b32_e32 v81, 0xffff0000, v81
	v_and_b32_e32 v80, 0xffff0000, v69
	v_and_b32_e32 v77, 0xffff0000, v77
	v_and_b32_e32 v76, 0xffff0000, v73
	v_mov_b32_e32 v83, v86
	v_mov_b32_e32 v85, v87
	v_pk_add_f32 v[90:91], v[90:91], v[92:93]
	v_add_f32_e32 v72, v71, v67
	v_pk_add_f32 v[76:77], v[80:81], v[76:77]
	v_pk_add_f32 v[80:81], v[82:83], v[84:85]
	v_mov_b32_e32 v67, v74
	v_mov_b32_e32 v71, v75
	v_pk_fma_f32 v[14:15], v[62:63], v[80:81], v[14:15]
	v_pk_add_f32 v[62:63], v[66:67], v[70:71]
	v_mov_b32_e32 v79, v90
	v_mov_b32_e32 v89, v91
	v_pk_fma_f32 v[16:17], v[64:65], v[62:63], v[16:17]
	v_pk_add_f32 v[62:63], v[78:79], v[88:89]
	v_mov_b32_e32 v69, v76
	v_mov_b32_e32 v73, v77
	v_pk_fma_f32 v[10:11], v[58:59], v[62:63], v[10:11]
	v_pk_add_f32 v[58:59], v[68:69], v[72:73]
	v_and_b32_e32 v62, 0xffff0000, v42
	v_pk_fma_f32 v[12:13], v[60:61], v[58:59], v[12:13]
	v_lshlrev_b32_e32 v58, 16, v46
	v_lshlrev_b32_e32 v59, 16, v42
	v_and_b32_e32 v64, 0xffff0000, v46
	v_lshlrev_b32_e32 v42, 16, v47
	v_lshlrev_b32_e32 v46, 16, v43
	v_lshlrev_b32_e32 v60, 16, v50
	v_and_b32_e32 v65, 0xffff0000, v50
	v_add_f32_e32 v42, v42, v46
	v_lshlrev_b32_e32 v46, 16, v55
	v_lshlrev_b32_e32 v50, 16, v51
	v_add_f32_e32 v58, v58, v59
	v_lshlrev_b32_e32 v59, 16, v54
	v_and_b32_e32 v63, 0xffff0000, v54
	v_add_f32_e32 v46, v50, v46
	v_and_b32_e32 v55, 0xffff0000, v55
	v_and_b32_e32 v54, 0xffff0000, v43
	v_and_b32_e32 v51, 0xffff0000, v51
	v_and_b32_e32 v50, 0xffff0000, v47
	v_lshlrev_b32_e32 v43, 16, v48
	v_lshlrev_b32_e32 v47, 16, v44
	v_pk_add_f32 v[50:51], v[54:55], v[50:51]
	v_add_f32_e32 v54, v43, v47
	v_lshlrev_b32_e32 v43, 16, v56
	v_lshlrev_b32_e32 v47, 16, v52
	v_pk_add_f32 v[62:63], v[62:63], v[64:65]
	v_add_f32_e32 v64, v47, v43
	v_and_b32_e32 v66, 0xffff0000, v44
	v_lshlrev_b32_e32 v43, 16, v49
	v_lshlrev_b32_e32 v44, 16, v45
	v_add_f32_e32 v60, v60, v59
	v_and_b32_e32 v67, 0xffff0000, v56
	v_and_b32_e32 v69, 0xffff0000, v52
	v_and_b32_e32 v68, 0xffff0000, v48
	v_add_f32_e32 v44, v43, v44
	v_lshlrev_b32_e32 v43, 16, v57
	v_lshlrev_b32_e32 v47, 16, v53
	v_and_b32_e32 v57, 0xffff0000, v57
	v_and_b32_e32 v56, 0xffff0000, v45
	v_and_b32_e32 v53, 0xffff0000, v53
	v_and_b32_e32 v52, 0xffff0000, v49
	v_mov_b32_e32 v59, v62
	v_mov_b32_e32 v61, v63
	v_pk_add_f32 v[66:67], v[66:67], v[68:69]
	v_add_f32_e32 v48, v47, v43
	v_pk_add_f32 v[52:53], v[56:57], v[52:53]
	v_pk_add_f32 v[56:57], v[58:59], v[60:61]
	v_mov_b32_e32 v43, v50
	v_mov_b32_e32 v47, v51
	v_pk_fma_f32 v[6:7], v[38:39], v[56:57], v[6:7]
	v_pk_add_f32 v[38:39], v[42:43], v[46:47]
	v_mov_b32_e32 v55, v66
	v_mov_b32_e32 v65, v67
	v_pk_fma_f32 v[8:9], v[40:41], v[38:39], v[8:9]
	v_pk_add_f32 v[38:39], v[54:55], v[64:65]
	v_mov_b32_e32 v45, v52
	v_mov_b32_e32 v49, v53
	v_pk_fma_f32 v[2:3], v[34:35], v[38:39], v[2:3]
	v_pk_add_f32 v[34:35], v[44:45], v[48:49]
	s_nop 0
	v_pk_fma_f32 v[4:5], v[36:37], v[34:35], v[4:5]

.LBB0_1099:
	s_or_b64 exec, exec, s[56:57]
	s_waitcnt vmcnt(0) lgkmcnt(0)
	v_pk_fma_f32 v[138:139], v[150:151], v[138:139], v[162:163]
	v_pk_fma_f32 v[190:191], v[166:167], v[190:191], v[178:179]
	v_pk_fma_f32 v[138:139], v[146:147], v[154:155], v[138:139]
	v_pk_fma_f32 v[140:141], v[152:153], v[140:141], v[164:165]
	v_pk_fma_f32 v[138:139], v[134:135], v[158:159], v[138:139]
	v_pk_fma_f32 v[190:191], v[142:143], v[170:171], v[190:191]
	v_mul_f32_e32 v221, 0xbfb8aa3b, v138
	v_exp_f32_e32 v221, v221
	v_pk_fma_f32 v[140:141], v[148:149], v[156:157], v[140:141]
	v_pk_fma_f32 v[190:191], v[130:131], v[174:175], v[190:191]
	v_pk_fma_f32 v[140:141], v[136:137], v[160:161], v[140:141]
	v_add_f32_e32 v221, 1.0, v221
	v_rcp_f32_e32 v230, v221
	v_mul_f32_e32 v221, 0xbfb8aa3b, v139
	v_exp_f32_e32 v221, v221
	v_pk_fma_f32 v[192:193], v[168:169], v[192:193], v[180:181]
	v_pk_fma_f32 v[142:143], v[142:143], v[166:167], v[178:179]
	v_pk_fma_f32 v[192:193], v[144:145], v[172:173], v[192:193]
	v_add_f32_e32 v221, 1.0, v221
	v_rcp_f32_e32 v231, v221
	v_pk_fma_f32 v[192:193], v[132:133], v[176:177], v[192:193]
	v_pk_fma_f32 v[142:143], v[130:131], v[170:171], v[142:143]
	v_pk_fma_f32 v[144:145], v[144:145], v[168:169], v[180:181]
	v_pk_mul_f32 v[138:139], v[138:139], v[230:231]
	v_pk_fma_f32 v[142:143], v[122:123], v[174:175], v[142:143]
	v_pk_mul_f32 v[138:139], v[190:191], v[138:139]
	v_mul_f32_e32 v190, 0xbfb8aa3b, v140
	v_mul_f32_e32 v191, 0xbfb8aa3b, v141
	v_exp_f32_e32 v190, v190
	v_exp_f32_e32 v191, v191
	v_pk_fma_f32 v[144:145], v[132:133], v[172:173], v[144:145]
	v_pk_fma_f32 v[130:131], v[130:131], v[166:167], v[178:179]
	v_add_f32_e32 v190, 1.0, v190
	v_add_f32_e32 v191, 1.0, v191
	v_rcp_f32_e32 v190, v190
	v_rcp_f32_e32 v191, v191
	v_pk_fma_f32 v[144:145], v[124:125], v[176:177], v[144:145]
	v_pk_fma_f32 v[130:131], v[122:123], v[170:171], v[130:131]
	v_pk_fma_f32 v[132:133], v[132:133], v[168:169], v[180:181]
	v_pk_mul_f32 v[140:141], v[140:141], v[190:191]
	v_pk_fma_f32 v[130:131], v[114:115], v[174:175], v[130:131]
	v_pk_mul_f32 v[140:141], v[192:193], v[140:141]
	v_pk_fma_f32 v[132:133], v[124:125], v[172:173], v[132:133]
	v_cvt_pk_bf16_f32 v141, v140, v141
	v_cvt_pk_bf16_f32 v140, v138, v139
	v_pk_fma_f32 v[138:139], v[146:147], v[150:151], v[162:163]
	v_pk_fma_f32 v[132:133], v[116:117], v[176:177], v[132:133]
	v_pk_fma_f32 v[138:139], v[134:135], v[154:155], v[138:139]
	v_pk_fma_f32 v[134:135], v[134:135], v[150:151], v[162:163]
	v_pk_fma_f32 v[138:139], v[126:127], v[158:159], v[138:139]
	v_pk_fma_f32 v[134:135], v[126:127], v[154:155], v[134:135]
	v_mul_f32_e32 v146, 0xbfb8aa3b, v138
	v_mul_f32_e32 v147, 0xbfb8aa3b, v139
	v_exp_f32_e32 v146, v146
	v_exp_f32_e32 v147, v147
	v_pk_fma_f32 v[134:135], v[118:119], v[158:159], v[134:135]
	v_pk_fma_f32 v[126:127], v[126:127], v[150:151], v[162:163]
	v_add_f32_e32 v146, 1.0, v146
	v_add_f32_e32 v147, 1.0, v147
	v_rcp_f32_e32 v146, v146
	v_rcp_f32_e32 v147, v147
	v_pk_fma_f32 v[126:127], v[118:119], v[154:155], v[126:127]
	v_pk_fma_f32 v[122:123], v[122:123], v[166:167], v[178:179]
	v_pk_fma_f32 v[126:127], v[102:103], v[158:159], v[126:127]
	v_pk_mul_f32 v[138:139], v[138:139], v[146:147]
	v_pk_fma_f32 v[122:123], v[114:115], v[170:171], v[122:123]
	v_pk_mul_f32 v[142:143], v[142:143], v[138:139]
	v_pk_fma_f32 v[138:139], v[148:149], v[152:153], v[164:165]
	v_pk_fma_f32 v[122:123], v[98:99], v[174:175], v[122:123]
	v_pk_fma_f32 v[138:139], v[136:137], v[156:157], v[138:139]
	v_pk_fma_f32 v[124:125], v[124:125], v[168:169], v[180:181]
	v_pk_fma_f32 v[138:139], v[128:129], v[160:161], v[138:139]
	v_pk_fma_f32 v[118:119], v[118:119], v[150:151], v[162:163]
	v_mul_f32_e32 v146, 0xbfb8aa3b, v138
	v_mul_f32_e32 v147, 0xbfb8aa3b, v139
	v_exp_f32_e32 v146, v146
	v_exp_f32_e32 v147, v147
	v_pk_fma_f32 v[124:125], v[116:117], v[172:173], v[124:125]
	v_pk_fma_f32 v[118:119], v[102:103], v[154:155], v[118:119]
	v_add_f32_e32 v146, 1.0, v146
	v_add_f32_e32 v147, 1.0, v147
	v_rcp_f32_e32 v146, v146
	v_rcp_f32_e32 v147, v147
	v_pk_fma_f32 v[124:125], v[100:101], v[176:177], v[124:125]
	v_pk_fma_f32 v[118:119], v[94:95], v[158:159], v[118:119]
	v_pk_fma_f32 v[114:115], v[114:115], v[166:167], v[178:179]
	v_pk_mul_f32 v[138:139], v[138:139], v[146:147]
	v_pk_fma_f32 v[114:115], v[98:99], v[170:171], v[114:115]
	v_pk_mul_f32 v[138:139], v[144:145], v[138:139]
	v_pk_fma_f32 v[114:115], v[90:91], v[174:175], v[114:115]
	v_cvt_pk_bf16_f32 v139, v138, v139
	v_cvt_pk_bf16_f32 v138, v142, v143
	v_mul_f32_e32 v142, 0xbfb8aa3b, v134
	v_mul_f32_e32 v143, 0xbfb8aa3b, v135
	v_exp_f32_e32 v142, v142
	v_exp_f32_e32 v143, v143
	v_pk_fma_f32 v[116:117], v[116:117], v[168:169], v[180:181]
	v_pk_fma_f32 v[102:103], v[102:103], v[150:151], v[162:163]
	v_add_f32_e32 v142, 1.0, v142
	v_add_f32_e32 v143, 1.0, v143
	v_rcp_f32_e32 v142, v142
	v_rcp_f32_e32 v143, v143
	v_pk_fma_f32 v[116:117], v[100:101], v[172:173], v[116:117]
	v_pk_fma_f32 v[102:103], v[94:95], v[154:155], v[102:103]
	v_pk_fma_f32 v[116:117], v[92:93], v[176:177], v[116:117]
	v_pk_mul_f32 v[134:135], v[134:135], v[142:143]
	v_pk_fma_f32 v[102:103], v[86:87], v[158:159], v[102:103]
	v_pk_mul_f32 v[134:135], v[130:131], v[134:135]
	v_pk_fma_f32 v[130:131], v[136:137], v[152:153], v[164:165]
	v_pk_fma_f32 v[98:99], v[98:99], v[166:167], v[178:179]
	v_pk_fma_f32 v[130:131], v[128:129], v[156:157], v[130:131]
	v_pk_fma_f32 v[98:99], v[90:91], v[170:171], v[98:99]
	v_pk_fma_f32 v[130:131], v[120:121], v[160:161], v[130:131]
	v_pk_fma_f32 v[98:99], v[78:79], v[174:175], v[98:99]
	v_mul_f32_e32 v136, 0xbfb8aa3b, v130
	v_mul_f32_e32 v137, 0xbfb8aa3b, v131
	v_exp_f32_e32 v136, v136
	v_exp_f32_e32 v137, v137
	v_pk_fma_f32 v[94:95], v[94:95], v[150:151], v[162:163]
	v_pk_fma_f32 v[100:101], v[100:101], v[168:169], v[180:181]
	v_add_f32_e32 v136, 1.0, v136
	v_add_f32_e32 v137, 1.0, v137
	v_rcp_f32_e32 v136, v136
	v_rcp_f32_e32 v137, v137
	v_pk_fma_f32 v[94:95], v[86:87], v[154:155], v[94:95]
	v_pk_fma_f32 v[86:87], v[86:87], v[150:151], v[162:163]
	v_pk_fma_f32 v[100:101], v[92:93], v[172:173], v[100:101]
	v_pk_mul_f32 v[130:131], v[130:131], v[136:137]
	v_pk_fma_f32 v[94:95], v[82:83], v[158:159], v[94:95]
	v_pk_mul_f32 v[130:131], v[132:133], v[130:131]
	v_mul_f32_e32 v132, 0xbfb8aa3b, v126
	v_mul_f32_e32 v133, 0xbfb8aa3b, v127
	v_exp_f32_e32 v132, v132
	v_exp_f32_e32 v133, v133
	v_pk_fma_f32 v[90:91], v[90:91], v[166:167], v[178:179]
	v_pk_fma_f32 v[82:83], v[82:83], v[154:155], v[86:87]
	v_add_f32_e32 v132, 1.0, v132
	v_add_f32_e32 v133, 1.0, v133
	v_rcp_f32_e32 v132, v132
	v_rcp_f32_e32 v133, v133
	v_pk_fma_f32 v[100:101], v[80:81], v[176:177], v[100:101]
	v_pk_fma_f32 v[90:91], v[78:79], v[170:171], v[90:91]
	v_pk_fma_f32 v[82:83], v[158:159], v[182:183], v[82:83]
	v_pk_mul_f32 v[126:127], v[126:127], v[132:133]
	v_pk_fma_f32 v[78:79], v[78:79], v[166:167], v[178:179]
	v_pk_mul_f32 v[126:127], v[122:123], v[126:127]
	v_pk_fma_f32 v[122:123], v[128:129], v[152:153], v[164:165]
	v_pk_fma_f32 v[90:91], v[74:75], v[174:175], v[90:91]
	v_pk_fma_f32 v[122:123], v[120:121], v[156:157], v[122:123]
	v_mul_f32_e32 v86, 0xbfb8aa3b, v82
	v_pk_fma_f32 v[122:123], v[104:105], v[160:161], v[122:123]
	v_pk_fma_f32 v[74:75], v[74:75], v[170:171], v[78:79]
	v_mul_f32_e32 v128, 0xbfb8aa3b, v122
	v_mul_f32_e32 v129, 0xbfb8aa3b, v123
	v_exp_f32_e32 v128, v128
	v_exp_f32_e32 v129, v129
	v_mul_f32_e32 v78, 0xbfb8aa3b, v83
	v_exp_f32_e32 v86, v86
	v_add_f32_e32 v128, 1.0, v128
	v_add_f32_e32 v129, 1.0, v129
	v_rcp_f32_e32 v128, v128
	v_rcp_f32_e32 v129, v129
	v_exp_f32_e32 v78, v78
	v_add_f32_e32 v86, 1.0, v86
	v_rcp_f32_e32 v86, v86
	v_pk_mul_f32 v[122:123], v[122:123], v[128:129]
	v_add_f32_e32 v78, 1.0, v78
	v_pk_mul_f32 v[122:123], v[124:125], v[122:123]
	v_mul_f32_e32 v124, 0xbfb8aa3b, v118
	v_mul_f32_e32 v125, 0xbfb8aa3b, v119
	v_exp_f32_e32 v124, v124
	v_exp_f32_e32 v125, v125
	v_rcp_f32_e32 v87, v78
	v_pk_fma_f32 v[74:75], v[174:175], v[186:187], v[74:75]
	v_add_f32_e32 v124, 1.0, v124
	v_add_f32_e32 v125, 1.0, v125
	v_rcp_f32_e32 v124, v124
	v_rcp_f32_e32 v125, v125
	v_pk_mul_f32 v[78:79], v[82:83], v[86:87]
	v_pk_fma_f32 v[92:93], v[92:93], v[168:169], v[180:181]
	v_pk_mul_f32 v[78:79], v[74:75], v[78:79]
	v_pk_mul_f32 v[118:119], v[118:119], v[124:125]
	v_pk_fma_f32 v[74:75], v[88:89], v[152:153], v[164:165]
	v_pk_mul_f32 v[118:119], v[114:115], v[118:119]
	v_pk_fma_f32 v[114:115], v[120:121], v[152:153], v[164:165]
	v_pk_fma_f32 v[74:75], v[84:85], v[156:157], v[74:75]
	v_pk_fma_f32 v[114:115], v[104:105], v[156:157], v[114:115]
	v_pk_fma_f32 v[92:93], v[80:81], v[172:173], v[92:93]
	v_pk_fma_f32 v[114:115], v[96:97], v[160:161], v[114:115]
	v_pk_fma_f32 v[74:75], v[160:161], v[184:185], v[74:75]
	v_mul_f32_e32 v120, 0xbfb8aa3b, v114
	v_mul_f32_e32 v121, 0xbfb8aa3b, v115
	v_exp_f32_e32 v120, v120
	v_exp_f32_e32 v121, v121
	v_pk_fma_f32 v[80:81], v[80:81], v[168:169], v[180:181]
	v_pk_fma_f32 v[92:93], v[76:77], v[176:177], v[92:93]
	v_add_f32_e32 v120, 1.0, v120
	v_add_f32_e32 v121, 1.0, v121
	v_rcp_f32_e32 v120, v120
	v_rcp_f32_e32 v121, v121
	v_mul_f32_e32 v82, 0xbfb8aa3b, v74
	v_pk_fma_f32 v[76:77], v[76:77], v[172:173], v[80:81]
	v_mul_f32_e32 v80, 0xbfb8aa3b, v75
	v_pk_mul_f32 v[114:115], v[114:115], v[120:121]
	v_exp_f32_e32 v82, v82
	v_pk_mul_f32 v[114:115], v[116:117], v[114:115]
	v_mul_f32_e32 v116, 0xbfb8aa3b, v102
	v_mul_f32_e32 v117, 0xbfb8aa3b, v103
	v_exp_f32_e32 v116, v116
	v_exp_f32_e32 v117, v117
	v_exp_f32_e32 v80, v80
	v_add_f32_e32 v82, 1.0, v82
	v_add_f32_e32 v116, 1.0, v116
	v_add_f32_e32 v117, 1.0, v117
	v_rcp_f32_e32 v116, v116
	v_rcp_f32_e32 v117, v117
	v_add_f32_e32 v80, 1.0, v80
	v_rcp_f32_e32 v82, v82
	v_rcp_f32_e32 v83, v80
	v_pk_mul_f32 v[102:103], v[102:103], v[116:117]
	v_or_b32_e32 v220, 4, v214
	v_pk_mul_f32 v[102:103], v[98:99], v[102:103]
	v_pk_fma_f32 v[98:99], v[104:105], v[152:153], v[164:165]
	v_ashrrev_i32_e32 v221, 31, v220
	v_pk_fma_f32 v[98:99], v[96:97], v[156:157], v[98:99]
	v_pk_fma_f32 v[76:77], v[176:177], v[188:189], v[76:77]
	v_pk_fma_f32 v[98:99], v[88:89], v[160:161], v[98:99]
	v_pk_mul_f32 v[74:75], v[74:75], v[82:83]
	v_mul_f32_e32 v104, 0xbfb8aa3b, v98
	v_mul_f32_e32 v105, 0xbfb8aa3b, v99
	v_exp_f32_e32 v104, v104
	v_exp_f32_e32 v105, v105
	v_pk_mul_f32 v[74:75], v[76:77], v[74:75]
	v_cvt_pk_bf16_f32 v115, v114, v115
	v_add_f32_e32 v104, 1.0, v104
	v_add_f32_e32 v105, 1.0, v105
	v_rcp_f32_e32 v104, v104
	v_rcp_f32_e32 v105, v105
	v_cvt_pk_bf16_f32 v75, v74, v75
	v_cvt_pk_bf16_f32 v74, v78, v79
	global_load_dwordx4 v[76:79], v[218:219], off offset:16
	v_pk_mul_f32 v[98:99], v[98:99], v[104:105]
	v_cvt_pk_bf16_f32 v114, v118, v119
	v_pk_mul_f32 v[98:99], v[100:101], v[98:99]
	v_mul_f32_e32 v100, 0xbfb8aa3b, v94
	v_mul_f32_e32 v101, 0xbfb8aa3b, v95
	v_exp_f32_e32 v100, v100
	v_exp_f32_e32 v101, v101
	v_cvt_pk_bf16_f32 v99, v98, v99
	v_cvt_pk_bf16_f32 v98, v102, v103
	v_add_f32_e32 v100, 1.0, v100
	v_add_f32_e32 v101, 1.0, v101
	v_rcp_f32_e32 v100, v100
	v_rcp_f32_e32 v101, v101
	v_cvt_pk_bf16_f32 v131, v130, v131
	v_cvt_pk_bf16_f32 v130, v134, v135
	v_cvt_pk_bf16_f32 v123, v122, v123
	v_pk_mul_f32 v[94:95], v[94:95], v[100:101]
	v_cvt_pk_bf16_f32 v122, v126, v127
	v_pk_mul_f32 v[94:95], v[90:91], v[94:95]
	v_pk_fma_f32 v[90:91], v[96:97], v[152:153], v[164:165]
	v_lshl_add_u32 v229, s54, 8, v226
	v_pk_fma_f32 v[90:91], v[88:89], v[156:157], v[90:91]
	v_add_u32_e32 v88, 0x1604, v214
	v_pk_fma_f32 v[90:91], v[84:85], v[160:161], v[90:91]
	v_lshlrev_b64 v[84:85], 2, v[220:221]
	v_mul_f32_e32 v96, 0xbfb8aa3b, v90
	v_mul_f32_e32 v97, 0xbfb8aa3b, v91
	v_exp_f32_e32 v96, v96
	v_exp_f32_e32 v97, v97
	v_lshl_add_u64 v[80:81], s[30:31], 0, v[84:85]
	v_lshl_add_u64 v[84:85], s[36:37], 0, v[84:85]
	v_add_f32_e32 v96, 1.0, v96
	v_add_f32_e32 v97, 1.0, v97
	v_rcp_f32_e32 v96, v96
	v_rcp_f32_e32 v97, v97
	global_load_dwordx4 v[80:83], v[80:81], off
	v_ashrrev_i32_e32 v89, 31, v88
	v_lshlrev_b64 v[88:89], 2, v[88:89]
	v_pk_mul_f32 v[90:91], v[90:91], v[96:97]
	s_mov_b64 s[54:55], -1
	v_pk_mul_f32 v[90:91], v[92:93], v[90:91]
	v_lshl_add_u64 v[92:93], s[20:21], 0, v[88:89]
	v_cvt_pk_bf16_f32 v91, v90, v91
	v_cvt_pk_bf16_f32 v90, v94, v95
	global_load_dwordx4 v[84:87], v[84:85], off
	global_load_dwordx4 v[94:97], v[216:217], off offset:16
	global_load_dwordx4 v[102:105], v[92:93], off
	v_lshl_add_u64 v[92:93], s[30:31], 0, v[88:89]
	global_load_dwordx4 v[118:121], v[92:93], off
	v_lshl_add_u64 v[92:93], s[36:37], 0, v[88:89]
	v_lshl_add_u64 v[88:89], s[22:23], 0, v[88:89]
	global_load_dwordx4 v[134:137], v[88:89], off
	global_load_dwordx4 v[126:129], v[92:93], off
	s_andn2_b64 vcc, exec, s[8:9]
	s_waitcnt vmcnt(4)
	v_pk_fma_f32 v[88:89], v[106:107], v[76:77], v[94:95]
	s_nop 0
	v_pk_fma_f32 v[88:89], v[70:71], v[80:81], v[88:89]
	v_pk_fma_f32 v[70:71], v[70:71], v[76:77], v[94:95]
	v_pk_fma_f32 v[88:89], v[54:55], v[84:85], v[88:89]
	v_pk_fma_f32 v[70:71], v[54:55], v[80:81], v[70:71]
	v_mul_f32_e32 v92, 0xbfb8aa3b, v88
	v_mul_f32_e32 v93, 0xbfb8aa3b, v89
	v_exp_f32_e32 v92, v92
	v_exp_f32_e32 v93, v93
	s_waitcnt vmcnt(1)
	v_pk_fma_f32 v[100:101], v[110:111], v[102:103], v[134:135]
	v_pk_fma_f32 v[106:107], v[112:113], v[104:105], v[136:137]
	v_add_f32_e32 v92, 1.0, v92
	v_add_f32_e32 v93, 1.0, v93
	v_rcp_f32_e32 v92, v92
	v_rcp_f32_e32 v93, v93
	v_pk_fma_f32 v[100:101], v[58:59], v[118:119], v[100:101]
	v_pk_fma_f32 v[106:107], v[60:61], v[120:121], v[106:107]
	s_waitcnt vmcnt(0)
	v_pk_fma_f32 v[100:101], v[50:51], v[126:127], v[100:101]
	v_pk_mul_f32 v[88:89], v[88:89], v[92:93]
	v_pk_fma_f32 v[92:93], v[108:109], v[78:79], v[96:97]
	v_pk_mul_f32 v[88:89], v[100:101], v[88:89]
	v_pk_fma_f32 v[92:93], v[72:73], v[82:83], v[92:93]
	v_pk_fma_f32 v[106:107], v[52:53], v[128:129], v[106:107]
	v_pk_fma_f32 v[92:93], v[56:57], v[86:87], v[92:93]
	v_cvt_pk_bf16_f32 v142, v88, v89
	v_mul_f32_e32 v100, 0xbfb8aa3b, v92
	v_mul_f32_e32 v101, 0xbfb8aa3b, v93
	v_exp_f32_e32 v100, v100
	v_exp_f32_e32 v101, v101
	v_mov_b64_e32 v[88:89], s[16:17]
	v_pk_fma_f32 v[70:71], v[46:47], v[84:85], v[70:71]
	v_add_f32_e32 v100, 1.0, v100
	v_add_f32_e32 v101, 1.0, v101
	v_rcp_f32_e32 v100, v100
	v_rcp_f32_e32 v101, v101
	v_pk_fma_f32 v[58:59], v[58:59], v[102:103], v[134:135]
	v_pk_fma_f32 v[60:61], v[60:61], v[104:105], v[136:137]
	v_pk_fma_f32 v[58:59], v[50:51], v[118:119], v[58:59]
	v_pk_mul_f32 v[92:93], v[92:93], v[100:101]
	v_pk_fma_f32 v[58:59], v[42:43], v[126:127], v[58:59]
	v_pk_mul_f32 v[92:93], v[106:107], v[92:93]
	v_lshlrev_b64 v[106:107], 1, v[214:215]
	v_cvt_pk_bf16_f32 v143, v92, v93
	v_mad_i64_i32 v[92:93], s[40:41], v229, s77, v[88:89]
	v_lshl_add_u64 v[92:93], v[92:93], 0, v[106:107]
	global_store_dwordx4 v[92:93], v[140:143], off
	v_mul_f32_e32 v92, 0xbfb8aa3b, v70
	v_mul_f32_e32 v93, 0xbfb8aa3b, v71
	v_exp_f32_e32 v92, v92
	v_exp_f32_e32 v93, v93
	v_pk_fma_f32 v[60:61], v[52:53], v[120:121], v[60:61]
	v_pk_fma_f32 v[54:55], v[54:55], v[76:77], v[94:95]
	v_add_f32_e32 v92, 1.0, v92
	v_add_f32_e32 v93, 1.0, v93
	v_rcp_f32_e32 v92, v92
	v_rcp_f32_e32 v93, v93
	v_pk_fma_f32 v[60:61], v[44:45], v[128:129], v[60:61]
	v_pk_fma_f32 v[54:55], v[46:47], v[80:81], v[54:55]
	v_pk_fma_f32 v[50:51], v[50:51], v[102:103], v[134:135]
	v_pk_mul_f32 v[70:71], v[70:71], v[92:93]
	v_pk_fma_f32 v[54:55], v[38:39], v[84:85], v[54:55]
	v_pk_mul_f32 v[58:59], v[58:59], v[70:71]
	v_pk_fma_f32 v[70:71], v[72:73], v[78:79], v[96:97]
	v_cvt_pk_bf16_f32 v140, v58, v59
	v_pk_fma_f32 v[70:71], v[56:57], v[82:83], v[70:71]
	v_or_b32_e32 v58, 1, v229
	v_pk_fma_f32 v[70:71], v[48:49], v[86:87], v[70:71]
	v_mad_i64_i32 v[58:59], s[40:41], v58, s77, v[88:89]
	v_mul_f32_e32 v72, 0xbfb8aa3b, v70
	v_mul_f32_e32 v73, 0xbfb8aa3b, v71
	v_exp_f32_e32 v72, v72
	v_exp_f32_e32 v73, v73
	v_lshl_add_u64 v[58:59], v[58:59], 0, v[106:107]
	v_pk_fma_f32 v[50:51], v[42:43], v[118:119], v[50:51]
	v_add_f32_e32 v72, 1.0, v72
	v_add_f32_e32 v73, 1.0, v73
	v_rcp_f32_e32 v72, v72
	v_rcp_f32_e32 v73, v73
	v_pk_fma_f32 v[50:51], v[34:35], v[126:127], v[50:51]
	v_pk_fma_f32 v[52:53], v[52:53], v[104:105], v[136:137]
	v_pk_fma_f32 v[46:47], v[46:47], v[76:77], v[94:95]
	v_pk_mul_f32 v[70:71], v[70:71], v[72:73]
	v_pk_fma_f32 v[52:53], v[44:45], v[120:121], v[52:53]
	v_pk_mul_f32 v[60:61], v[60:61], v[70:71]
	v_pk_fma_f32 v[52:53], v[36:37], v[128:129], v[52:53]
	v_cvt_pk_bf16_f32 v141, v60, v61
	global_store_dwordx4 v[58:59], v[138:141], off
	v_mul_f32_e32 v58, 0xbfb8aa3b, v54
	v_mul_f32_e32 v59, 0xbfb8aa3b, v55
	v_exp_f32_e32 v58, v58
	v_exp_f32_e32 v59, v59
	v_pk_fma_f32 v[46:47], v[38:39], v[80:81], v[46:47]
	v_pk_fma_f32 v[42:43], v[42:43], v[102:103], v[134:135]
	v_add_f32_e32 v58, 1.0, v58
	v_add_f32_e32 v59, 1.0, v59
	v_rcp_f32_e32 v58, v58
	v_rcp_f32_e32 v59, v59
	v_pk_fma_f32 v[46:47], v[30:31], v[84:85], v[46:47]
	v_pk_fma_f32 v[42:43], v[34:35], v[118:119], v[42:43]
	v_pk_fma_f32 v[44:45], v[44:45], v[104:105], v[136:137]
	v_pk_mul_f32 v[54:55], v[54:55], v[58:59]
	v_pk_fma_f32 v[42:43], v[26:27], v[126:127], v[42:43]
	v_pk_mul_f32 v[50:51], v[50:51], v[54:55]
	v_pk_fma_f32 v[54:55], v[56:57], v[78:79], v[96:97]
	v_cvt_pk_bf16_f32 v132, v50, v51
	v_pk_fma_f32 v[54:55], v[48:49], v[82:83], v[54:55]
	v_or_b32_e32 v50, 2, v229
	v_pk_fma_f32 v[54:55], v[40:41], v[86:87], v[54:55]
	v_mad_i64_i32 v[50:51], s[40:41], v50, s77, v[88:89]
	v_mul_f32_e32 v56, 0xbfb8aa3b, v54
	v_mul_f32_e32 v57, 0xbfb8aa3b, v55
	v_exp_f32_e32 v56, v56
	v_exp_f32_e32 v57, v57
	v_lshl_add_u64 v[50:51], v[50:51], 0, v[106:107]
	v_pk_fma_f32 v[44:45], v[36:37], v[120:121], v[44:45]
	v_add_f32_e32 v56, 1.0, v56
	v_add_f32_e32 v57, 1.0, v57
	v_rcp_f32_e32 v56, v56
	v_rcp_f32_e32 v57, v57
	v_pk_fma_f32 v[44:45], v[28:29], v[128:129], v[44:45]
	v_pk_fma_f32 v[38:39], v[38:39], v[76:77], v[94:95]
	v_pk_fma_f32 v[34:35], v[34:35], v[102:103], v[134:135]
	v_pk_mul_f32 v[54:55], v[54:55], v[56:57]
	v_pk_fma_f32 v[38:39], v[30:31], v[80:81], v[38:39]
	v_pk_mul_f32 v[52:53], v[52:53], v[54:55]
	v_pk_fma_f32 v[38:39], v[22:23], v[84:85], v[38:39]
	v_cvt_pk_bf16_f32 v133, v52, v53
	global_store_dwordx4 v[50:51], v[130:133], off
	v_mul_f32_e32 v50, 0xbfb8aa3b, v46
	v_mul_f32_e32 v51, 0xbfb8aa3b, v47
	v_exp_f32_e32 v50, v50
	v_exp_f32_e32 v51, v51
	v_pk_fma_f32 v[34:35], v[26:27], v[118:119], v[34:35]
	v_pk_fma_f32 v[36:37], v[36:37], v[104:105], v[136:137]
	v_add_f32_e32 v50, 1.0, v50
	v_add_f32_e32 v51, 1.0, v51
	v_rcp_f32_e32 v50, v50
	v_rcp_f32_e32 v51, v51
	v_pk_fma_f32 v[34:35], v[18:19], v[126:127], v[34:35]
	v_pk_fma_f32 v[36:37], v[28:29], v[120:121], v[36:37]
	v_pk_fma_f32 v[30:31], v[30:31], v[76:77], v[94:95]
	v_pk_mul_f32 v[46:47], v[46:47], v[50:51]
	v_pk_fma_f32 v[36:37], v[20:21], v[128:129], v[36:37]
	v_pk_mul_f32 v[42:43], v[42:43], v[46:47]
	v_pk_fma_f32 v[46:47], v[48:49], v[78:79], v[96:97]
	v_cvt_pk_bf16_f32 v124, v42, v43
	v_pk_fma_f32 v[46:47], v[40:41], v[82:83], v[46:47]
	v_or_b32_e32 v42, 3, v229
	v_pk_fma_f32 v[46:47], v[32:33], v[86:87], v[46:47]
	v_mad_i64_i32 v[42:43], s[40:41], v42, s77, v[88:89]
	v_mul_f32_e32 v48, 0xbfb8aa3b, v46
	v_mul_f32_e32 v49, 0xbfb8aa3b, v47
	v_exp_f32_e32 v48, v48
	v_exp_f32_e32 v49, v49
	v_lshl_add_u64 v[42:43], v[42:43], 0, v[106:107]
	v_pk_fma_f32 v[30:31], v[22:23], v[80:81], v[30:31]
	v_add_f32_e32 v48, 1.0, v48
	v_add_f32_e32 v49, 1.0, v49
	v_rcp_f32_e32 v48, v48
	v_rcp_f32_e32 v49, v49
	v_pk_fma_f32 v[30:31], v[14:15], v[84:85], v[30:31]
	v_pk_fma_f32 v[26:27], v[26:27], v[102:103], v[134:135]
	v_pk_fma_f32 v[28:29], v[28:29], v[104:105], v[136:137]
	v_pk_mul_f32 v[46:47], v[46:47], v[48:49]
	v_pk_fma_f32 v[26:27], v[18:19], v[118:119], v[26:27]
	v_pk_mul_f32 v[44:45], v[44:45], v[46:47]
	v_pk_fma_f32 v[26:27], v[6:7], v[126:127], v[26:27]
	v_cvt_pk_bf16_f32 v125, v44, v45
	global_store_dwordx4 v[42:43], v[122:125], off
	v_mul_f32_e32 v42, 0xbfb8aa3b, v38
	v_mul_f32_e32 v43, 0xbfb8aa3b, v39
	v_exp_f32_e32 v42, v42
	v_exp_f32_e32 v43, v43
	v_pk_fma_f32 v[28:29], v[20:21], v[120:121], v[28:29]
	v_pk_fma_f32 v[22:23], v[22:23], v[76:77], v[94:95]
	v_add_f32_e32 v42, 1.0, v42
	v_add_f32_e32 v43, 1.0, v43
	v_rcp_f32_e32 v42, v42
	v_rcp_f32_e32 v43, v43
	v_pk_fma_f32 v[28:29], v[8:9], v[128:129], v[28:29]
	v_pk_fma_f32 v[22:23], v[14:15], v[80:81], v[22:23]
	v_pk_fma_f32 v[14:15], v[14:15], v[76:77], v[94:95]
	v_pk_mul_f32 v[38:39], v[38:39], v[42:43]
	v_pk_fma_f32 v[22:23], v[10:11], v[84:85], v[22:23]
	v_pk_mul_f32 v[34:35], v[34:35], v[38:39]
	v_pk_fma_f32 v[38:39], v[40:41], v[78:79], v[96:97]
	v_cvt_pk_bf16_f32 v116, v34, v35
	v_pk_fma_f32 v[38:39], v[32:33], v[82:83], v[38:39]
	v_or_b32_e32 v34, 4, v229
	v_pk_fma_f32 v[38:39], v[24:25], v[86:87], v[38:39]
	v_mad_i64_i32 v[34:35], s[40:41], v34, s77, v[88:89]
	v_mul_f32_e32 v40, 0xbfb8aa3b, v38
	v_mul_f32_e32 v41, 0xbfb8aa3b, v39
	v_exp_f32_e32 v40, v40
	v_exp_f32_e32 v41, v41
	v_lshl_add_u64 v[34:35], v[34:35], 0, v[106:107]
	v_pk_fma_f32 v[18:19], v[18:19], v[102:103], v[134:135]
	v_add_f32_e32 v40, 1.0, v40
	v_add_f32_e32 v41, 1.0, v41
	v_rcp_f32_e32 v40, v40
	v_rcp_f32_e32 v41, v41
	v_pk_fma_f32 v[10:11], v[10:11], v[80:81], v[14:15]
	v_pk_fma_f32 v[18:19], v[6:7], v[118:119], v[18:19]
	v_pk_fma_f32 v[10:11], v[66:67], v[84:85], v[10:11]
	v_pk_mul_f32 v[38:39], v[38:39], v[40:41]
	v_pk_fma_f32 v[6:7], v[6:7], v[102:103], v[134:135]
	v_pk_mul_f32 v[36:37], v[36:37], v[38:39]
	v_pk_fma_f32 v[18:19], v[2:3], v[126:127], v[18:19]
	v_cvt_pk_bf16_f32 v117, v36, v37
	global_store_dwordx4 v[34:35], v[114:117], off
	v_mul_f32_e32 v34, 0xbfb8aa3b, v30
	v_mul_f32_e32 v35, 0xbfb8aa3b, v31
	v_exp_f32_e32 v34, v34
	v_exp_f32_e32 v35, v35
	v_mul_f32_e32 v14, 0xbfb8aa3b, v10
	v_pk_fma_f32 v[2:3], v[2:3], v[118:119], v[6:7]
	v_add_f32_e32 v34, 1.0, v34
	v_add_f32_e32 v35, 1.0, v35
	v_rcp_f32_e32 v34, v34
	v_rcp_f32_e32 v35, v35
	v_mul_f32_e32 v6, 0xbfb8aa3b, v11
	v_exp_f32_e32 v14, v14
	v_exp_f32_e32 v6, v6
	v_pk_mul_f32 v[30:31], v[30:31], v[34:35]
	v_pk_fma_f32 v[2:3], v[62:63], v[126:127], v[2:3]
	v_pk_mul_f32 v[26:27], v[26:27], v[30:31]
	v_pk_fma_f32 v[30:31], v[32:33], v[78:79], v[96:97]
	v_cvt_pk_bf16_f32 v100, v26, v27
	v_pk_fma_f32 v[30:31], v[24:25], v[82:83], v[30:31]
	v_or_b32_e32 v26, 5, v229
	v_pk_fma_f32 v[30:31], v[16:17], v[86:87], v[30:31]
	v_mad_i64_i32 v[26:27], s[40:41], v26, s77, v[88:89]
	v_mul_f32_e32 v32, 0xbfb8aa3b, v30
	v_mul_f32_e32 v33, 0xbfb8aa3b, v31
	v_exp_f32_e32 v32, v32
	v_exp_f32_e32 v33, v33
	v_lshl_add_u64 v[26:27], v[26:27], 0, v[106:107]
	v_add_f32_e32 v14, 1.0, v14
	v_add_f32_e32 v32, 1.0, v32
	v_add_f32_e32 v33, 1.0, v33
	v_rcp_f32_e32 v32, v32
	v_rcp_f32_e32 v33, v33
	v_add_f32_e32 v6, 1.0, v6
	v_rcp_f32_e32 v14, v14
	v_rcp_f32_e32 v15, v6
	v_pk_mul_f32 v[30:31], v[30:31], v[32:33]
	v_pk_fma_f32 v[20:21], v[20:21], v[104:105], v[136:137]
	v_pk_mul_f32 v[28:29], v[28:29], v[30:31]
	v_pk_mul_f32 v[6:7], v[10:11], v[14:15]
	v_cvt_pk_bf16_f32 v101, v28, v29
	global_store_dwordx4 v[26:27], v[98:101], off
	v_mul_f32_e32 v26, 0xbfb8aa3b, v22
	v_mul_f32_e32 v27, 0xbfb8aa3b, v23
	v_exp_f32_e32 v26, v26
	v_exp_f32_e32 v27, v27
	v_pk_mul_f32 v[2:3], v[2:3], v[6:7]
	v_pk_fma_f32 v[6:7], v[16:17], v[78:79], v[96:97]
	v_add_f32_e32 v26, 1.0, v26
	v_add_f32_e32 v27, 1.0, v27
	v_rcp_f32_e32 v26, v26
	v_rcp_f32_e32 v27, v27
	v_pk_fma_f32 v[6:7], v[12:13], v[82:83], v[6:7]
	v_pk_fma_f32 v[20:21], v[8:9], v[120:121], v[20:21]
	v_pk_fma_f32 v[6:7], v[68:69], v[86:87], v[6:7]
	v_pk_mul_f32 v[22:23], v[22:23], v[26:27]
	v_pk_fma_f32 v[8:9], v[8:9], v[104:105], v[136:137]
	v_pk_mul_f32 v[18:19], v[18:19], v[22:23]
	v_pk_fma_f32 v[22:23], v[24:25], v[78:79], v[96:97]
	v_pk_fma_f32 v[20:21], v[4:5], v[128:129], v[20:21]
	v_pk_fma_f32 v[22:23], v[16:17], v[82:83], v[22:23]
	v_mul_f32_e32 v10, 0xbfb8aa3b, v6
	v_pk_fma_f32 v[22:23], v[12:13], v[86:87], v[22:23]
	v_pk_fma_f32 v[4:5], v[4:5], v[120:121], v[8:9]
	v_mul_f32_e32 v24, 0xbfb8aa3b, v22
	v_mul_f32_e32 v25, 0xbfb8aa3b, v23
	v_mul_f32_e32 v8, 0xbfb8aa3b, v7
	v_exp_f32_e32 v24, v24
	v_exp_f32_e32 v25, v25
	v_exp_f32_e32 v10, v10
	v_exp_f32_e32 v8, v8
	v_add_f32_e32 v24, 1.0, v24
	v_add_f32_e32 v25, 1.0, v25
	v_add_f32_e32 v10, 1.0, v10
	v_add_f32_e32 v8, 1.0, v8
	v_rcp_f32_e32 v24, v24
	v_rcp_f32_e32 v25, v25
	v_rcp_f32_e32 v10, v10
	v_rcp_f32_e32 v11, v8
	v_cvt_pk_bf16_f32 v92, v18, v19
	v_pk_mul_f32 v[22:23], v[22:23], v[24:25]
	v_or_b32_e32 v18, 6, v229
	v_pk_fma_f32 v[4:5], v[64:65], v[128:129], v[4:5]
	v_pk_mul_f32 v[6:7], v[6:7], v[10:11]
	v_cvt_pk_bf16_f32 v76, v2, v3
	v_or_b32_e32 v2, 7, v229
	v_pk_mul_f32 v[20:21], v[20:21], v[22:23]
	v_mad_i64_i32 v[18:19], s[40:41], v18, s77, v[88:89]
	v_pk_mul_f32 v[4:5], v[4:5], v[6:7]
	v_mad_i64_i32 v[2:3], s[40:41], v2, s77, v[88:89]
	v_cvt_pk_bf16_f32 v93, v20, v21
	v_lshl_add_u64 v[18:19], v[18:19], 0, v[106:107]
	v_cvt_pk_bf16_f32 v77, v4, v5
	v_lshl_add_u64 v[2:3], v[2:3], 0, v[106:107]
	global_store_dwordx4 v[18:19], v[90:93], off
	global_store_dwordx4 v[2:3], v[74:77], off
	s_cbranch_vccnz .LBB0_1076
	s_and_b64 vcc, exec, s[10:11]
	s_cbranch_vccnz .LBB0_1075
	s_barrier
	s_branch .LBB0_1075

.LBB0_1145:
	s_movk_i32 s6, 0x57f
	v_cmp_lt_i32_e32 vcc, s6, v0
	s_movk_i32 s6, 0x580
	v_cmp_gt_i32_e64 s[6:7], s6, v0
	s_mov_b64 s[36:37], 0
	s_and_saveexec_b64 s[42:43], s[6:7]
	s_xor_b64 s[6:7], exec, s[42:43]
	s_and_b64 s[36:37], s[24:25], exec
	s_or_saveexec_b64 s[6:7], s[6:7]
	v_mov_b32_e32 v2, 0
	v_mov_b32_e32 v4, s34
	v_mov_b32_e32 v3, s29
	v_mov_b32_e32 v5, s39
	s_xor_b64 exec, exec, s[6:7]
	s_andn2_b64 s[36:37], s[36:37], exec
	s_and_b64 s[42:43], s[26:27], exec
	v_mov_b32_e32 v2, 0xff
	v_mov_b32_e32 v4, s33
	v_mov_b32_e32 v3, s35
	v_mov_b32_e32 v5, s38
	s_or_b64 s[36:37], s[36:37], s[42:43]
	s_or_b64 exec, exec, s[6:7]
	s_and_saveexec_b64 s[6:7], s[36:37]
	s_cbranch_execz .LBB0_1144
	v_cndmask_b32_e32 v6, 0, v246, vcc
	v_add3_u32 v6, s28, v6, v0
	v_mov_b64_e32 v[8:9], s[14:15]
	v_ashrrev_i32_e32 v7, 31, v6
	v_mad_i64_i32 v[10:11], s[36:37], v4, s50, v[8:9]
	v_lshlrev_b64 v[12:13], 2, v[6:7]
	v_mad_u64_u32 v[14:15], s[36:37], v3, s50, v[8:9]
	v_mad_u64_u32 v[4:5], s[36:37], v5, s50, v[8:9]
	v_lshl_add_u64 v[10:11], v[10:11], 0, v[12:13]
	v_lshl_add_u64 v[14:15], v[14:15], 0, v[12:13]
	v_lshl_add_u64 v[4:5], v[4:5], 0, v[12:13]
	v_lshl_add_u64 v[8:9], s[22:23], 0, v[12:13]
	v_lshl_add_u64 v[12:13], s[20:21], 0, v[12:13]
	v_add_co_u32_e32 v18, vcc, s50, v12
	global_load_dword v16, v[8:9], off
	s_nop 0
	v_addc_co_u32_e32 v19, vcc, 0, v13, vcc
	v_add_co_u32_e32 v20, vcc, s41, v12
	s_mov_b32 s36, 0x10000
	s_nop 0
	v_addc_co_u32_e32 v21, vcc, 0, v13, vcc
	v_add_co_u32_e32 v8, vcc, s51, v8
	global_load_dword v22, v[12:13], off
	global_load_dword v18, v[18:19], off
	global_load_dword v20, v[20:21], off
	global_load_dword v24, v[10:11], off
	global_load_dword v26, v[14:15], off
	global_load_dword v28, v[4:5], off
	v_addc_co_u32_e32 v9, vcc, 0, v9, vcc
	global_load_dword v17, v[8:9], off offset:2048
	v_add_co_u32_e32 v8, vcc, s51, v12
	s_nop 1
	v_addc_co_u32_e32 v9, vcc, 0, v13, vcc
	global_load_dword v23, v[8:9], off offset:2048
	v_add_co_u32_e32 v8, vcc, s51, v10
	s_nop 1
	v_addc_co_u32_e32 v9, vcc, 0, v11, vcc
	global_load_dword v25, v[8:9], off offset:2048
	v_add_co_u32_e32 v8, vcc, s36, v12
	s_mov_b32 s36, 0x1b000
	s_nop 0
	v_addc_co_u32_e32 v9, vcc, 0, v13, vcc
	global_load_dword v19, v[8:9], off offset:2048
	v_add_co_u32_e32 v8, vcc, s51, v14
	s_nop 1
	v_addc_co_u32_e32 v9, vcc, 0, v15, vcc
	global_load_dword v27, v[8:9], off offset:2048
	v_add_co_u32_e32 v8, vcc, s36, v12
	s_nop 1
	v_addc_co_u32_e32 v9, vcc, 0, v13, vcc
	v_add_co_u32_e32 v4, vcc, s51, v4
	global_load_dword v21, v[8:9], off offset:2048
	s_nop 0
	v_addc_co_u32_e32 v5, vcc, 0, v5, vcc
	global_load_dword v29, v[4:5], off offset:2048
	v_or_b32_e32 v8, s40, v2
	s_waitcnt vmcnt(0)
	v_pk_fma_f32 v[4:5], v[22:23], v[24:25], v[16:17]
	s_nop 0
	v_pk_fma_f32 v[4:5], v[18:19], v[26:27], v[4:5]
	s_nop 0
	v_pk_fma_f32 v[4:5], v[20:21], v[28:29], v[4:5]
	s_nop 0
	v_mul_f32_e32 v3, 0xbfb8aa3b, v4
	v_exp_f32_e32 v3, v3
	s_nop 0
	v_add_f32_e32 v2, 1.0, v3
	v_rcp_f32_e32 v9, v2
	v_mov_b64_e32 v[2:3], s[8:9]
	v_mad_u64_u32 v[2:3], s[36:37], v8, s77, v[2:3]
	v_mul_f32_e32 v4, v4, v9
	v_mul_f32_e32 v4, v4, v5
	v_cvt_pk_bf16_f32 v4, v4, s0
	v_lshl_add_u64 v[2:3], v[6:7], 1, v[2:3]
	global_store_short v[2:3], v4, off
	s_branch .LBB0_1144

.LBB0_1191:
	s_andn2_b64 vcc, exec, s[22:23]
	s_cbranch_vccnz .LBB0_1193
	v_lshlrev_b64 v[176:177], 1, v[154:155]
	v_lshl_add_u64 v[178:179], s[2:3], 0, v[176:177]
	v_lshlrev_b64 v[180:181], 12, v[152:153]
	v_lshl_add_u64 v[106:107], v[154:155], 2, s[6:7]
	v_lshl_add_u64 v[152:153], v[178:179], 0, v[180:181]
	global_load_dwordx4 v[110:113], v[106:107], off offset:16
	global_load_dwordx4 v[118:121], v[106:107], off
	global_load_dwordx4 v[102:105], v[106:107], off offset:528
	global_load_dwordx4 v[106:109], v[106:107], off offset:512
	global_load_dwordx4 v[204:207], v[152:153], off
	global_load_dwordx4 v[208:211], v[152:153], off offset:256
	v_ashrrev_i32_e32 v151, 31, v150
	v_lshlrev_b64 v[186:187], 12, v[150:151]
	v_lshl_add_u64 v[150:151], v[178:179], 0, v[186:187]
	global_load_dwordx4 v[212:215], v[150:151], off
	global_load_dwordx4 v[162:165], v[150:151], off offset:256
	v_ashrrev_i32_e32 v149, 31, v148
	v_lshlrev_b64 v[184:185], 12, v[148:149]
	v_lshl_add_u64 v[148:149], v[178:179], 0, v[184:185]
	global_load_dwordx4 v[158:161], v[148:149], off
	global_load_dwordx4 v[154:157], v[148:149], off offset:256
	v_ashrrev_i32_e32 v147, 31, v146
	v_lshlrev_b64 v[182:183], 12, v[146:147]
	v_lshl_add_u64 v[146:147], v[178:179], 0, v[182:183]
	global_load_dwordx4 v[150:153], v[146:147], off
	global_load_dwordx4 v[146:149], v[146:147], off offset:256
	s_mov_b64 s[20:21], 0x80000
	s_waitcnt vmcnt(0)
	v_lshlrev_b32_e32 v216, 16, v204
	v_and_b32_e32 v217, 0xffff0000, v204
	v_lshlrev_b32_e32 v204, 16, v205
	v_and_b32_e32 v205, 0xffff0000, v205
	v_pk_fma_f32 v[144:145], v[144:145], v[120:121], v[204:205]
	v_lshlrev_b32_e32 v204, 16, v206
	v_and_b32_e32 v205, 0xffff0000, v206
	v_pk_fma_f32 v[142:143], v[142:143], v[118:119], v[216:217]
	v_pk_fma_f32 v[204:205], v[138:139], v[110:111], v[204:205]
	v_lshlrev_b32_e32 v138, 16, v207
	v_and_b32_e32 v139, 0xffff0000, v207
	v_pk_fma_f32 v[206:207], v[140:141], v[112:113], v[138:139]
	v_cvt_pk_bf16_f32 v138, v142, v143
	v_lshl_add_u64 v[142:143], s[2:3], 0, v[180:181]
	v_cvt_pk_bf16_f32 v139, v144, v145
	v_cvt_pk_bf16_f32 v140, v204, v205
	v_cvt_pk_bf16_f32 v141, v206, v207
	v_lshl_add_u64 v[142:143], v[142:143], 0, v[176:177]
	global_store_dwordx4 v[142:143], v[138:141], off
	s_nop 1
	v_lshlrev_b32_e32 v138, 16, v208
	v_and_b32_e32 v139, 0xffff0000, v208
	v_pk_fma_f32 v[130:131], v[130:131], v[106:107], v[138:139]
	v_lshlrev_b32_e32 v138, 16, v209
	v_and_b32_e32 v139, 0xffff0000, v209
	v_pk_fma_f32 v[132:133], v[132:133], v[108:109], v[138:139]
	v_lshlrev_b32_e32 v138, 16, v210
	v_and_b32_e32 v139, 0xffff0000, v210
	v_pk_fma_f32 v[138:139], v[122:123], v[102:103], v[138:139]
	v_lshlrev_b32_e32 v122, 16, v211
	v_and_b32_e32 v123, 0xffff0000, v211
	v_pk_fma_f32 v[140:141], v[124:125], v[104:105], v[122:123]
	v_cvt_pk_bf16_f32 v122, v130, v131
	v_cvt_pk_bf16_f32 v123, v132, v133
	v_cvt_pk_bf16_f32 v124, v138, v139
	v_cvt_pk_bf16_f32 v125, v140, v141
	global_store_dwordx4 v[142:143], v[122:125], off offset:256
	v_lshlrev_b32_e32 v130, 16, v214
	v_and_b32_e32 v131, 0xffff0000, v214
	v_lshlrev_b32_e32 v122, 16, v212
	v_and_b32_e32 v123, 0xffff0000, v212
	v_lshlrev_b32_e32 v124, 16, v213
	v_and_b32_e32 v125, 0xffff0000, v213
	v_pk_fma_f32 v[122:123], v[134:135], v[118:119], v[122:123]
	v_pk_fma_f32 v[124:125], v[136:137], v[120:121], v[124:125]
	v_pk_fma_f32 v[126:127], v[126:127], v[110:111], v[130:131]
	v_lshlrev_b32_e32 v130, 16, v215
	v_and_b32_e32 v131, 0xffff0000, v215
	v_pk_fma_f32 v[128:129], v[128:129], v[112:113], v[130:131]
	v_cvt_pk_bf16_f32 v122, v122, v123
	v_cvt_pk_bf16_f32 v123, v124, v125
	v_cvt_pk_bf16_f32 v124, v126, v127
	v_lshl_add_u64 v[126:127], s[2:3], 0, v[186:187]
	v_cvt_pk_bf16_f32 v125, v128, v129
	v_lshl_add_u64 v[126:127], v[126:127], 0, v[176:177]
	global_store_dwordx4 v[126:127], v[122:125], off
	s_nop 1
	v_lshlrev_b32_e32 v122, 16, v162
	v_and_b32_e32 v123, 0xffff0000, v162
	v_pk_fma_f32 v[114:115], v[114:115], v[106:107], v[122:123]
	v_lshlrev_b32_e32 v122, 16, v163
	v_and_b32_e32 v123, 0xffff0000, v163
	v_pk_fma_f32 v[116:117], v[116:117], v[108:109], v[122:123]
	v_lshlrev_b32_e32 v122, 16, v164
	v_and_b32_e32 v123, 0xffff0000, v164
	v_pk_fma_f32 v[122:123], v[94:95], v[102:103], v[122:123]
	v_lshlrev_b32_e32 v94, 16, v165
	v_and_b32_e32 v95, 0xffff0000, v165
	v_pk_fma_f32 v[124:125], v[96:97], v[104:105], v[94:95]
	v_cvt_pk_bf16_f32 v94, v114, v115
	v_cvt_pk_bf16_f32 v95, v116, v117
	v_cvt_pk_bf16_f32 v96, v122, v123
	v_cvt_pk_bf16_f32 v97, v124, v125
	global_store_dwordx4 v[126:127], v[94:97], off offset:256
	s_nop 1
	v_lshlrev_b32_e32 v94, 16, v158
	v_and_b32_e32 v95, 0xffff0000, v158
	v_pk_fma_f32 v[94:95], v[98:99], v[118:119], v[94:95]
	v_lshlrev_b32_e32 v98, 16, v160
	v_and_b32_e32 v99, 0xffff0000, v160
	v_lshlrev_b32_e32 v96, 16, v159
	v_and_b32_e32 v97, 0xffff0000, v159
	v_pk_fma_f32 v[98:99], v[90:91], v[110:111], v[98:99]
	v_lshlrev_b32_e32 v90, 16, v161
	v_and_b32_e32 v91, 0xffff0000, v161
	v_pk_fma_f32 v[96:97], v[100:101], v[120:121], v[96:97]
	v_pk_fma_f32 v[100:101], v[92:93], v[112:113], v[90:91]
	v_cvt_pk_bf16_f32 v90, v94, v95
	v_lshl_add_u64 v[94:95], s[2:3], 0, v[184:185]
	v_cvt_pk_bf16_f32 v91, v96, v97
	v_cvt_pk_bf16_f32 v92, v98, v99
	v_cvt_pk_bf16_f32 v93, v100, v101
	v_lshl_add_u64 v[94:95], v[94:95], 0, v[176:177]
	global_store_dwordx4 v[94:95], v[90:93], off
	s_nop 1
	v_lshlrev_b32_e32 v90, 16, v154
	v_and_b32_e32 v91, 0xffff0000, v154
	v_pk_fma_f32 v[82:83], v[82:83], v[106:107], v[90:91]
	v_lshlrev_b32_e32 v90, 16, v155
	v_and_b32_e32 v91, 0xffff0000, v155
	v_pk_fma_f32 v[84:85], v[84:85], v[108:109], v[90:91]
	v_lshlrev_b32_e32 v90, 16, v156
	v_and_b32_e32 v91, 0xffff0000, v156
	v_pk_fma_f32 v[90:91], v[74:75], v[102:103], v[90:91]
	v_lshlrev_b32_e32 v74, 16, v157
	v_and_b32_e32 v75, 0xffff0000, v157
	v_pk_fma_f32 v[92:93], v[76:77], v[104:105], v[74:75]
	v_cvt_pk_bf16_f32 v74, v82, v83
	v_cvt_pk_bf16_f32 v75, v84, v85
	v_cvt_pk_bf16_f32 v76, v90, v91
	v_cvt_pk_bf16_f32 v77, v92, v93
	global_store_dwordx4 v[94:95], v[74:77], off offset:256
	v_lshlrev_b32_e32 v82, 16, v152
	v_and_b32_e32 v83, 0xffff0000, v152
	v_lshlrev_b32_e32 v74, 16, v150
	v_and_b32_e32 v75, 0xffff0000, v150
	v_lshlrev_b32_e32 v76, 16, v151
	v_and_b32_e32 v77, 0xffff0000, v151
	v_pk_fma_f32 v[74:75], v[86:87], v[118:119], v[74:75]
	v_pk_fma_f32 v[76:77], v[88:89], v[120:121], v[76:77]
	v_pk_fma_f32 v[78:79], v[78:79], v[110:111], v[82:83]
	v_lshlrev_b32_e32 v82, 16, v153
	v_and_b32_e32 v83, 0xffff0000, v153
	v_pk_fma_f32 v[80:81], v[80:81], v[112:113], v[82:83]
	v_cvt_pk_bf16_f32 v74, v74, v75
	v_cvt_pk_bf16_f32 v75, v76, v77
	v_cvt_pk_bf16_f32 v76, v78, v79
	v_lshl_add_u64 v[78:79], s[2:3], 0, v[182:183]
	v_cvt_pk_bf16_f32 v77, v80, v81
	v_lshl_add_u64 v[78:79], v[78:79], 0, v[176:177]
	global_store_dwordx4 v[78:79], v[74:77], off
	s_nop 1
	v_lshlrev_b32_e32 v74, 16, v146
	v_and_b32_e32 v75, 0xffff0000, v146
	v_pk_fma_f32 v[70:71], v[70:71], v[106:107], v[74:75]
	v_lshlrev_b32_e32 v74, 16, v147
	v_and_b32_e32 v75, 0xffff0000, v147
	v_pk_fma_f32 v[72:73], v[72:73], v[108:109], v[74:75]
	v_lshlrev_b32_e32 v74, 16, v148
	v_and_b32_e32 v75, 0xffff0000, v148
	v_pk_fma_f32 v[74:75], v[66:67], v[102:103], v[74:75]
	v_lshlrev_b32_e32 v66, 16, v149
	v_and_b32_e32 v67, 0xffff0000, v149
	v_pk_fma_f32 v[76:77], v[68:69], v[104:105], v[66:67]
	v_cvt_pk_bf16_f32 v66, v70, v71
	v_cvt_pk_bf16_f32 v67, v72, v73
	v_cvt_pk_bf16_f32 v68, v74, v75
	v_cvt_pk_bf16_f32 v69, v76, v77
	global_store_dwordx4 v[78:79], v[66:69], off offset:256
	v_lshl_add_u64 v[78:79], v[180:181], 0, s[20:21]
	v_lshl_add_u64 v[70:71], v[178:179], 0, v[78:79]
	global_load_dwordx4 v[66:69], v[70:71], off
	global_load_dwordx4 v[70:73], v[70:71], off offset:256
	s_mov_b64 s[20:21], 0x90000
	v_lshl_add_u64 v[100:101], v[180:181], 0, s[20:21]
	v_lshl_add_u64 v[74:75], v[178:179], 0, v[100:101]
	global_load_dwordx4 v[80:83], v[74:75], off
	global_load_dwordx4 v[84:87], v[74:75], off offset:256
	s_mov_b64 s[20:21], 0xa0000
	v_lshl_add_u64 v[114:115], v[180:181], 0, s[20:21]
	v_lshl_add_u64 v[74:75], v[178:179], 0, v[114:115]
	global_load_dwordx4 v[88:91], v[74:75], off
	global_load_dwordx4 v[92:95], v[74:75], off offset:256
	s_mov_b64 s[20:21], 0xb0000
	v_lshl_add_u64 v[116:117], v[180:181], 0, s[20:21]
	v_lshl_add_u64 v[74:75], v[178:179], 0, v[116:117]
	global_load_dwordx4 v[96:99], v[74:75], off
	global_load_dwordx4 v[74:77], v[74:75], off offset:256
	s_waitcnt vmcnt(7)
	v_lshlrev_b32_e32 v122, 16, v66
	v_and_b32_e32 v123, 0xffff0000, v66
	v_lshlrev_b32_e32 v66, 16, v67
	v_and_b32_e32 v67, 0xffff0000, v67
	v_pk_fma_f32 v[64:65], v[64:65], v[120:121], v[66:67]
	v_lshlrev_b32_e32 v66, 16, v68
	v_and_b32_e32 v67, 0xffff0000, v68
	v_pk_fma_f32 v[62:63], v[62:63], v[118:119], v[122:123]
	v_pk_fma_f32 v[66:67], v[58:59], v[110:111], v[66:67]
	v_lshlrev_b32_e32 v58, 16, v69
	v_and_b32_e32 v59, 0xffff0000, v69
	v_pk_fma_f32 v[68:69], v[60:61], v[112:113], v[58:59]
	v_cvt_pk_bf16_f32 v58, v62, v63
	v_lshl_add_u64 v[62:63], s[2:3], 0, v[78:79]
	v_cvt_pk_bf16_f32 v59, v64, v65
	v_cvt_pk_bf16_f32 v60, v66, v67
	v_cvt_pk_bf16_f32 v61, v68, v69
	v_lshl_add_u64 v[62:63], v[62:63], 0, v[176:177]
	global_store_dwordx4 v[62:63], v[58:61], off
	s_waitcnt vmcnt(7)
	s_nop 0
	v_lshlrev_b32_e32 v58, 16, v70
	v_and_b32_e32 v59, 0xffff0000, v70
	v_pk_fma_f32 v[54:55], v[54:55], v[106:107], v[58:59]
	v_lshlrev_b32_e32 v58, 16, v71
	v_and_b32_e32 v59, 0xffff0000, v71
	v_pk_fma_f32 v[56:57], v[56:57], v[108:109], v[58:59]
	v_lshlrev_b32_e32 v58, 16, v72
	v_and_b32_e32 v59, 0xffff0000, v72
	v_pk_fma_f32 v[58:59], v[46:47], v[102:103], v[58:59]
	v_lshlrev_b32_e32 v46, 16, v73
	v_and_b32_e32 v47, 0xffff0000, v73
	v_pk_fma_f32 v[60:61], v[48:49], v[104:105], v[46:47]
	v_cvt_pk_bf16_f32 v46, v54, v55
	v_cvt_pk_bf16_f32 v47, v56, v57
	v_cvt_pk_bf16_f32 v48, v58, v59
	v_cvt_pk_bf16_f32 v49, v60, v61
	global_store_dwordx4 v[62:63], v[46:49], off offset:256
	s_waitcnt vmcnt(7)
	s_nop 0
	v_lshlrev_b32_e32 v46, 16, v80
	v_and_b32_e32 v47, 0xffff0000, v80
	v_pk_fma_f32 v[46:47], v[50:51], v[118:119], v[46:47]
	v_lshlrev_b32_e32 v50, 16, v82
	v_and_b32_e32 v51, 0xffff0000, v82
	v_lshlrev_b32_e32 v48, 16, v81
	v_and_b32_e32 v49, 0xffff0000, v81
	v_pk_fma_f32 v[50:51], v[42:43], v[110:111], v[50:51]
	v_lshlrev_b32_e32 v42, 16, v83
	v_and_b32_e32 v43, 0xffff0000, v83
	v_pk_fma_f32 v[48:49], v[52:53], v[120:121], v[48:49]
	v_pk_fma_f32 v[52:53], v[44:45], v[112:113], v[42:43]
	v_cvt_pk_bf16_f32 v42, v46, v47
	v_lshl_add_u64 v[46:47], s[2:3], 0, v[100:101]
	v_cvt_pk_bf16_f32 v43, v48, v49
	v_cvt_pk_bf16_f32 v44, v50, v51
	v_cvt_pk_bf16_f32 v45, v52, v53
	v_lshl_add_u64 v[46:47], v[46:47], 0, v[176:177]
	global_store_dwordx4 v[46:47], v[42:45], off
	s_waitcnt vmcnt(7)
	s_nop 0
	v_lshlrev_b32_e32 v42, 16, v84
	v_and_b32_e32 v43, 0xffff0000, v84
	v_pk_fma_f32 v[38:39], v[38:39], v[106:107], v[42:43]
	v_lshlrev_b32_e32 v42, 16, v85
	v_and_b32_e32 v43, 0xffff0000, v85
	v_pk_fma_f32 v[40:41], v[40:41], v[108:109], v[42:43]
	v_lshlrev_b32_e32 v42, 16, v86
	v_and_b32_e32 v43, 0xffff0000, v86
	v_pk_fma_f32 v[42:43], v[30:31], v[102:103], v[42:43]
	v_lshlrev_b32_e32 v30, 16, v87
	v_and_b32_e32 v31, 0xffff0000, v87
	v_pk_fma_f32 v[44:45], v[32:33], v[104:105], v[30:31]
	v_cvt_pk_bf16_f32 v30, v38, v39
	v_cvt_pk_bf16_f32 v31, v40, v41
	v_cvt_pk_bf16_f32 v32, v42, v43
	v_cvt_pk_bf16_f32 v33, v44, v45
	global_store_dwordx4 v[46:47], v[30:33], off offset:256
	s_waitcnt vmcnt(7)
	s_nop 0
	v_lshlrev_b32_e32 v30, 16, v88
	v_and_b32_e32 v31, 0xffff0000, v88
	v_pk_fma_f32 v[30:31], v[34:35], v[118:119], v[30:31]
	v_lshlrev_b32_e32 v34, 16, v90
	v_and_b32_e32 v35, 0xffff0000, v90
	v_lshlrev_b32_e32 v32, 16, v89
	v_and_b32_e32 v33, 0xffff0000, v89
	v_pk_fma_f32 v[34:35], v[26:27], v[110:111], v[34:35]
	v_lshlrev_b32_e32 v26, 16, v91
	v_and_b32_e32 v27, 0xffff0000, v91
	v_pk_fma_f32 v[32:33], v[36:37], v[120:121], v[32:33]
	v_pk_fma_f32 v[36:37], v[28:29], v[112:113], v[26:27]
	v_cvt_pk_bf16_f32 v26, v30, v31
	v_lshl_add_u64 v[30:31], s[2:3], 0, v[114:115]
	v_cvt_pk_bf16_f32 v27, v32, v33
	v_cvt_pk_bf16_f32 v28, v34, v35
	v_cvt_pk_bf16_f32 v29, v36, v37
	v_lshl_add_u64 v[30:31], v[30:31], 0, v[176:177]
	global_store_dwordx4 v[30:31], v[26:29], off
	s_waitcnt vmcnt(7)
	s_nop 0
	v_lshlrev_b32_e32 v26, 16, v92
	v_and_b32_e32 v27, 0xffff0000, v92
	v_pk_fma_f32 v[22:23], v[22:23], v[106:107], v[26:27]
	v_lshlrev_b32_e32 v26, 16, v93
	v_and_b32_e32 v27, 0xffff0000, v93
	v_pk_fma_f32 v[24:25], v[24:25], v[108:109], v[26:27]
	v_lshlrev_b32_e32 v26, 16, v94
	v_and_b32_e32 v27, 0xffff0000, v94
	v_pk_fma_f32 v[26:27], v[14:15], v[102:103], v[26:27]
	v_lshlrev_b32_e32 v14, 16, v95
	v_and_b32_e32 v15, 0xffff0000, v95
	v_pk_fma_f32 v[28:29], v[16:17], v[104:105], v[14:15]
	v_cvt_pk_bf16_f32 v14, v22, v23
	v_cvt_pk_bf16_f32 v15, v24, v25
	v_cvt_pk_bf16_f32 v16, v26, v27
	v_cvt_pk_bf16_f32 v17, v28, v29
	global_store_dwordx4 v[30:31], v[14:17], off offset:256
	s_waitcnt vmcnt(7)
	s_nop 0
	v_lshlrev_b32_e32 v14, 16, v96
	v_and_b32_e32 v15, 0xffff0000, v96
	v_pk_fma_f32 v[14:15], v[18:19], v[118:119], v[14:15]
	v_lshlrev_b32_e32 v18, 16, v98
	v_and_b32_e32 v19, 0xffff0000, v98
	v_lshlrev_b32_e32 v16, 16, v97
	v_and_b32_e32 v17, 0xffff0000, v97
	v_pk_fma_f32 v[18:19], v[10:11], v[110:111], v[18:19]
	v_lshlrev_b32_e32 v10, 16, v99
	v_and_b32_e32 v11, 0xffff0000, v99
	v_pk_fma_f32 v[16:17], v[20:21], v[120:121], v[16:17]
	v_pk_fma_f32 v[20:21], v[12:13], v[112:113], v[10:11]
	v_cvt_pk_bf16_f32 v10, v14, v15
	v_lshl_add_u64 v[14:15], s[2:3], 0, v[116:117]
	v_cvt_pk_bf16_f32 v11, v16, v17
	v_cvt_pk_bf16_f32 v12, v18, v19
	v_cvt_pk_bf16_f32 v13, v20, v21
	v_lshl_add_u64 v[110:111], v[14:15], 0, v[176:177]
	global_store_dwordx4 v[110:111], v[10:13], off
	s_waitcnt vmcnt(7)
	s_nop 0
	v_lshlrev_b32_e32 v10, 16, v74
	v_and_b32_e32 v11, 0xffff0000, v74
	v_pk_fma_f32 v[6:7], v[6:7], v[106:107], v[10:11]
	v_lshlrev_b32_e32 v10, 16, v75
	v_and_b32_e32 v11, 0xffff0000, v75
	v_pk_fma_f32 v[8:9], v[8:9], v[108:109], v[10:11]
	v_lshlrev_b32_e32 v10, 16, v76
	v_and_b32_e32 v11, 0xffff0000, v76
	v_pk_fma_f32 v[2:3], v[2:3], v[102:103], v[10:11]
	v_lshlrev_b32_e32 v10, 16, v77
	v_and_b32_e32 v11, 0xffff0000, v77
	v_pk_fma_f32 v[4:5], v[4:5], v[104:105], v[10:11]
	v_cvt_pk_bf16_f32 v102, v6, v7
	v_cvt_pk_bf16_f32 v103, v8, v9
	v_cvt_pk_bf16_f32 v104, v2, v3

.LBB0_1229:
	global_load_dwordx4 v[0:3], v[44:45], off
	global_load_dwordx4 v[4:7], v[44:45], off offset:16
	v_pk_mul_f32 v[8:9], v[84:85], v[84:85]
	v_pk_mul_f32 v[10:11], v[86:87], v[86:87]
	v_add_f32_e32 v8, v9, v8
	v_add_f32_e32 v8, v10, v8
	v_pk_mul_f32 v[12:13], v[80:81], v[80:81]
	v_add_f32_e32 v8, v11, v8
	v_add_f32_e32 v8, v12, v8
	v_pk_mul_f32 v[14:15], v[82:83], v[82:83]
	v_add_f32_e32 v8, v13, v8
	v_add_f32_e32 v8, v14, v8
	v_pk_mul_f32 v[16:17], v[76:77], v[76:77]
	v_add_f32_e32 v8, v15, v8
	v_add_f32_e32 v8, v16, v8
	v_pk_mul_f32 v[18:19], v[78:79], v[78:79]
	v_add_f32_e32 v8, v17, v8
	v_add_f32_e32 v8, v18, v8
	v_pk_mul_f32 v[20:21], v[72:73], v[72:73]
	v_add_f32_e32 v8, v19, v8
	v_add_f32_e32 v8, v20, v8
	v_pk_mul_f32 v[22:23], v[74:75], v[74:75]
	v_add_f32_e32 v8, v21, v8
	v_add_f32_e32 v8, v22, v8
	v_pk_mul_f32 v[24:25], v[68:69], v[68:69]
	v_add_f32_e32 v8, v23, v8
	v_add_f32_e32 v8, v24, v8
	v_pk_mul_f32 v[26:27], v[70:71], v[70:71]
	v_add_f32_e32 v8, v25, v8
	v_add_f32_e32 v8, v26, v8
	v_pk_mul_f32 v[28:29], v[64:65], v[64:65]
	v_add_f32_e32 v8, v27, v8
	v_add_f32_e32 v8, v28, v8
	v_pk_mul_f32 v[30:31], v[66:67], v[66:67]
	v_add_f32_e32 v8, v29, v8
	v_add_f32_e32 v8, v30, v8
	v_pk_mul_f32 v[32:33], v[56:57], v[56:57]
	v_add_f32_e32 v8, v31, v8
	v_add_f32_e32 v8, v32, v8
	v_pk_mul_f32 v[34:35], v[60:61], v[60:61]
	v_add_f32_e32 v8, v33, v8
	v_add_f32_e32 v8, v34, v8
	v_pk_mul_f32 v[36:37], v[58:59], v[58:59]
	v_add_f32_e32 v8, v35, v8
	v_add_f32_e32 v8, v36, v8
	v_pk_mul_f32 v[38:39], v[62:63], v[62:63]
	v_add_f32_e32 v8, v37, v8
	v_add_f32_e32 v8, v38, v8
	v_add_f32_e32 v8, v39, v8
	s_add_i32 s2, s2, s82
	v_lshl_add_u64 v[52:53], v[52:53], 0, s[56:57]
	v_add_f32_dpp v8, v8, v8 quad_perm:[1,0,3,2] row_mask:0xf bank_mask:0xf bound_ctrl:1
	s_cmpk_lt_i32 s2, 0x2800
	s_nop 0
	v_add_f32_dpp v8, v8, v8 quad_perm:[2,3,0,1] row_mask:0xf bank_mask:0xf bound_ctrl:1
	s_nop 1
	v_add_f32_dpp v8, v8, v8 row_half_mirror row_mask:0xf bank_mask:0xf bound_ctrl:1
	s_nop 1
	v_add_f32_dpp v8, v8, v8 row_mirror row_mask:0xf bank_mask:0xf bound_ctrl:1
	ds_swizzle_b32 v9, v8 offset:swizzle(SWAP,16)
	s_waitcnt lgkmcnt(0)
	v_add_f32_e32 v8, v8, v9
	v_mov_b32_e32 v9, v8
	s_nop 1
	v_permlane32_swap_b32_e32 v8, v9
	v_add_f32_e32 v8, v8, v9
	v_fmamk_f32 v8, v8, 0x3a000000, v99
	v_rsq_f32_e32 v8, v8
	s_nop 0
	v_pk_mul_f32 v[10:11], v[84:85], v[8:9] op_sel_hi:[1,0]
	v_pk_mul_f32 v[12:13], v[86:87], v[8:9] op_sel_hi:[1,0]
	v_pk_mul_f32 v[14:15], v[80:81], v[8:9] op_sel_hi:[1,0]
	v_pk_mul_f32 v[16:17], v[82:83], v[8:9] op_sel_hi:[1,0]
	s_waitcnt vmcnt(1)
	v_pk_mul_f32 v[2:3], v[2:3], v[12:13]
	v_pk_mul_f32 v[0:1], v[0:1], v[10:11]
	s_waitcnt vmcnt(0)
	v_pk_mul_f32 v[6:7], v[6:7], v[16:17]
	v_pk_mul_f32 v[4:5], v[4:5], v[14:15]
	global_store_dwordx4 v[54:55], v[0:3], off offset:-4096
	global_store_dwordx4 v[54:55], v[4:7], off offset:-4080
	global_load_dwordx4 v[0:3], v[44:45], off offset:2048
	global_load_dwordx4 v[4:7], v[44:45], off offset:2064
	v_pk_mul_f32 v[10:11], v[78:79], v[8:9] op_sel_hi:[1,0]
	v_pk_mul_f32 v[12:13], v[76:77], v[8:9] op_sel_hi:[1,0]
	v_pk_mul_f32 v[14:15], v[74:75], v[8:9] op_sel_hi:[1,0]
	v_pk_mul_f32 v[16:17], v[72:73], v[8:9] op_sel_hi:[1,0]
	s_waitcnt vmcnt(1)
	v_pk_mul_f32 v[0:1], v[0:1], v[12:13]
	v_pk_mul_f32 v[2:3], v[2:3], v[10:11]
	s_waitcnt vmcnt(0)
	v_pk_mul_f32 v[4:5], v[4:5], v[16:17]
	v_pk_mul_f32 v[6:7], v[6:7], v[14:15]
	global_store_dwordx4 v[54:55], v[0:3], off offset:-2048
	global_store_dwordx4 v[54:55], v[4:7], off offset:-2032
	global_load_dwordx4 v[0:3], v[46:47], off
	global_load_dwordx4 v[4:7], v[46:47], off offset:16
	v_pk_mul_f32 v[10:11], v[70:71], v[8:9] op_sel_hi:[1,0]
	v_pk_mul_f32 v[12:13], v[68:69], v[8:9] op_sel_hi:[1,0]
	v_pk_mul_f32 v[14:15], v[66:67], v[8:9] op_sel_hi:[1,0]
	v_pk_mul_f32 v[16:17], v[64:65], v[8:9] op_sel_hi:[1,0]
	s_waitcnt vmcnt(1)
	v_pk_mul_f32 v[0:1], v[12:13], v[0:1]
	v_pk_mul_f32 v[2:3], v[10:11], v[2:3]
	s_waitcnt vmcnt(0)
	v_pk_mul_f32 v[4:5], v[16:17], v[4:5]
	v_pk_mul_f32 v[6:7], v[14:15], v[6:7]
	global_store_dwordx4 v[54:55], v[0:3], off
	global_store_dwordx4 v[54:55], v[4:7], off offset:16
	global_load_dwordx4 v[0:3], v[48:49], off
	global_load_dwordx4 v[4:7], v[48:49], off offset:16
	v_pk_mul_f32 v[10:11], v[60:61], v[8:9] op_sel_hi:[1,0]
	v_pk_mul_f32 v[12:13], v[56:57], v[8:9] op_sel_hi:[1,0]
	v_pk_mul_f32 v[14:15], v[62:63], v[8:9] op_sel_hi:[1,0]
	v_pk_mul_f32 v[8:9], v[58:59], v[8:9] op_sel_hi:[1,0]
	s_waitcnt vmcnt(1)
	v_pk_mul_f32 v[0:1], v[12:13], v[0:1]
	v_pk_mul_f32 v[2:3], v[10:11], v[2:3]
	s_waitcnt vmcnt(0)
	v_pk_mul_f32 v[4:5], v[8:9], v[4:5]
	v_pk_mul_f32 v[6:7], v[14:15], v[6:7]
	global_store_dwordx4 v[54:55], v[0:3], off offset:2048
	global_store_dwordx4 v[54:55], v[4:7], off offset:2064
	v_lshl_add_u64 v[54:55], v[54:55], 0, s[4:5]
	s_cbranch_scc0 .LBB0_1232
